# dnscan: XCD-paired units, pipelined compute step, 3-set loader; dncomb row prefetch; no barrier after last postnorm
# speedup vs baseline: 1.0067x; 1.0067x over previous
.LBB0_496:
	v_readlane_b32 s4, v254, 33
	v_readlane_b32 s5, v254, 34
	s_mov_b64 s[0:1], -1
	s_and_b64 vcc, exec, s[4:5]
	s_mul_i32 s23, s28, 0x88
	s_cbranch_vccz .LBB0_517
	s_mov_b32 s0, s92
	v_mbcnt_lo_u32_b32 v74, -1, 0
	v_mbcnt_hi_u32_b32 v74, -1, v74
	s_lshl_b32 s48, s28, 1
	v_and_b32_e32 v132, 31, v74
	v_or_b32_e32 v75, s0, v132
	v_bfe_u32 v131, v74, 5, 1
	v_mad_u64_u32 v[0:1], s[0:1], v75, s28, 0
	v_lshl_add_u64 v[0:1], v[0:1], 1, s[56:57]
	v_lshlrev_b32_e32 v160, 4, v131
	v_lshl_add_u64 v[4:5], v[0:1], 0, v[160:161]
	global_load_dwordx4 v[24:27], v[4:5], off
	global_load_dwordx4 v[16:19], v[4:5], off offset:32
	global_load_dwordx4 v[28:31], v[4:5], off offset:64
	global_load_dwordx4 v[20:23], v[4:5], off offset:96
	global_load_dwordx4 v[8:11], v[4:5], off offset:128
	global_load_dwordx4 v[0:3], v[4:5], off offset:160
	global_load_dwordx4 v[12:15], v[4:5], off offset:192
	s_nop 0
	global_load_dwordx4 v[4:7], v[4:5], off offset:224
	v_bfe_u32 v69, v74, 4, 2
	v_readlane_b32 s0, v253, 3
	v_and_b32_e32 v73, 15, v74
	v_readlane_b32 s1, v253, 4
	v_or_b32_e32 v32, s0, v69
	v_lshlrev_b32_e32 v35, 4, v74
	v_bitop3_b32 v33, v69, v73, s1 bitop3:0x36
	v_lshlrev_b32_e32 v33, 4, v33
	v_bfe_u32 v72, v74, 2, 3
	v_and_b32_e32 v35, 48, v35
	v_mul_lo_u32 v32, v32, s48
	v_or_b32_e32 v34, s0, v72
	v_lshl_or_b32 v133, v131, 6, v35
	s_and_b32 s37, s91, 0xffff
	s_mov_b32 s36, s90
	v_or_b32_e32 v35, v33, v32
	v_readlane_b32 s1, v253, 6
	s_mov_b32 s0, m0
	s_mov_b32 m0, s1
	s_nop 0
	buffer_load_dwordx4 v35, s[36:39], s49 offen lds
	s_mov_b32 m0, s0
	s_lshl_b32 s0, s28, 3
	v_bitop3_b32 v32, v33, 64, v32 bitop3:0x36
	v_readlane_b32 s4, v253, 8
	s_mov_b32 s1, m0
	s_mov_b32 m0, s4
	s_nop 0
	buffer_load_dwordx4 v32, s[36:39], s0 offen lds
	s_mov_b32 m0, s1
	s_and_b32 s0, s41, 0xffff
	s_mov_b64 s[12:13], s[36:37]
	v_mul_lo_u32 v33, v34, s48
	s_mov_b64 s[14:15], s[38:39]
	s_mov_b32 s12, s40
	s_mov_b32 s13, s0
	v_or_b32_e32 v33, v33, v133
	v_readlane_b32 s1, v253, 7
	s_mov_b32 s0, m0
	s_mov_b32 m0, s1
	s_nop 0
	buffer_load_dwordx4 v33, s[12:15], s49 offen lds
	s_mov_b32 m0, s0
	v_or_b32_e32 v34, 0x80, v33
	v_readlane_b32 s1, v253, 9
	s_mov_b32 s0, m0
	s_mov_b32 m0, s1
	s_nop 0
	buffer_load_dwordx4 v34, s[12:15], s49 offen lds
	s_mov_b32 m0, s0
	s_mov_b32 s17, s93
	s_mov_b32 s93, s60
	s_mov_b32 s60, s72
	s_lshl_b32 s72, s28, 7
	v_readlane_b32 s1, v253, 10
	s_mov_b32 s0, m0
	s_mov_b32 m0, s1
	s_nop 0
	buffer_load_dwordx4 v35, s[36:39], s72 offen lds
	s_mov_b32 m0, s0
	v_readlane_b32 s1, v253, 11
	s_mov_b32 s0, m0
	s_mov_b32 m0, s1
	s_nop 0
	buffer_load_dwordx4 v32, s[36:39], s23 offen lds
	s_mov_b32 m0, s0
	v_lshlrev_b32_e32 v68, 3, v131
	s_mov_b32 s16, s33
	s_mov_b32 s33, s65
	s_mov_b32 s65, s97
	s_cmp_eq_u64 s[10:11], 0
	v_lshlrev_b32_e32 v160, 2, v68
	s_mov_b32 s0, 0x800000
	s_waitcnt vmcnt(7)
	v_lshlrev_b32_e32 v34, 16, v24
	v_and_b32_e32 v35, 0xffff0000, v24
	s_waitcnt vmcnt(5)
	v_lshlrev_b32_e32 v32, 16, v28
	v_and_b32_e32 v33, 0xffff0000, v28
	v_lshlrev_b32_e32 v36, 16, v25
	v_and_b32_e32 v37, 0xffff0000, v25
	v_lshlrev_b32_e32 v24, 16, v29
	v_and_b32_e32 v25, 0xffff0000, v29
	v_lshlrev_b32_e32 v38, 16, v26
	v_and_b32_e32 v39, 0xffff0000, v26
	v_lshlrev_b32_e32 v28, 16, v30
	v_and_b32_e32 v29, 0xffff0000, v30
	v_lshlrev_b32_e32 v40, 16, v27
	v_and_b32_e32 v41, 0xffff0000, v27
	v_lshlrev_b32_e32 v26, 16, v31
	v_and_b32_e32 v27, 0xffff0000, v31
	v_lshlrev_b32_e32 v42, 16, v16
	v_and_b32_e32 v43, 0xffff0000, v16
	s_waitcnt vmcnt(4)
	v_lshlrev_b32_e32 v30, 16, v20
	v_and_b32_e32 v31, 0xffff0000, v20
	v_lshlrev_b32_e32 v44, 16, v17
	v_and_b32_e32 v45, 0xffff0000, v17
	v_lshlrev_b32_e32 v16, 16, v21
	v_and_b32_e32 v17, 0xffff0000, v21
	v_lshlrev_b32_e32 v46, 16, v18
	v_and_b32_e32 v47, 0xffff0000, v18
	v_lshlrev_b32_e32 v20, 16, v22
	v_and_b32_e32 v21, 0xffff0000, v22
	v_lshlrev_b32_e32 v48, 16, v19
	v_and_b32_e32 v49, 0xffff0000, v19
	v_lshlrev_b32_e32 v18, 16, v23
	v_and_b32_e32 v19, 0xffff0000, v23
	s_waitcnt vmcnt(3)
	v_lshlrev_b32_e32 v50, 16, v8
	v_and_b32_e32 v51, 0xffff0000, v8
	s_waitcnt vmcnt(1)
	v_lshlrev_b32_e32 v22, 16, v12
	v_and_b32_e32 v23, 0xffff0000, v12
	v_lshlrev_b32_e32 v52, 16, v9
	v_and_b32_e32 v53, 0xffff0000, v9
	v_lshlrev_b32_e32 v8, 16, v13
	v_and_b32_e32 v9, 0xffff0000, v13
	v_lshlrev_b32_e32 v54, 16, v10
	v_and_b32_e32 v55, 0xffff0000, v10
	v_lshlrev_b32_e32 v12, 16, v14
	v_and_b32_e32 v13, 0xffff0000, v14
	v_lshlrev_b32_e32 v56, 16, v11
	v_and_b32_e32 v57, 0xffff0000, v11
	v_lshlrev_b32_e32 v10, 16, v15
	v_and_b32_e32 v11, 0xffff0000, v15
	v_lshlrev_b32_e32 v58, 16, v0
	v_and_b32_e32 v59, 0xffff0000, v0
	s_waitcnt vmcnt(0)
	v_lshlrev_b32_e32 v14, 16, v4
	v_and_b32_e32 v15, 0xffff0000, v4
	v_lshlrev_b32_e32 v60, 16, v1
	v_and_b32_e32 v61, 0xffff0000, v1
	v_lshlrev_b32_e32 v4, 16, v5
	v_and_b32_e32 v5, 0xffff0000, v5
	v_lshlrev_b32_e32 v64, 16, v2
	v_and_b32_e32 v65, 0xffff0000, v2
	v_lshlrev_b32_e32 v62, 16, v6
	v_and_b32_e32 v63, 0xffff0000, v6
	v_lshlrev_b32_e32 v66, 16, v3
	v_and_b32_e32 v67, 0xffff0000, v3
	v_lshlrev_b32_e32 v6, 16, v7
	v_and_b32_e32 v7, 0xffff0000, v7
	s_cbranch_scc1 .LBB0_499
	v_mul_f32_e32 v0, v35, v35
	v_pk_fma_f32 v[0:1], v[34:35], v[34:35], v[0:1] op_sel_hi:[1,1,0]
	v_mul_f32_e32 v2, v37, v37
	v_pk_fma_f32 v[0:1], v[36:37], v[36:37], v[0:1]
	v_lshl_add_u64 v[70:71], s[10:11], 0, v[160:161]
	v_pk_add_f32 v[0:1], v[2:3], v[0:1] op_sel_hi:[0,1]
	v_pk_fma_f32 v[0:1], v[38:39], v[38:39], v[0:1]
	v_mul_f32_e32 v2, v39, v39
	v_pk_add_f32 v[0:1], v[2:3], v[0:1] op_sel_hi:[0,1]
	v_pk_fma_f32 v[0:1], v[40:41], v[40:41], v[0:1]
	v_mul_f32_e32 v2, v41, v41
	v_pk_add_f32 v[0:1], v[2:3], v[0:1] op_sel_hi:[0,1]
	v_pk_fma_f32 v[0:1], v[42:43], v[42:43], v[0:1]
	v_mul_f32_e32 v2, v43, v43
	v_pk_add_f32 v[0:1], v[2:3], v[0:1] op_sel_hi:[0,1]
	v_pk_fma_f32 v[0:1], v[44:45], v[44:45], v[0:1]
	v_mul_f32_e32 v2, v45, v45
	v_pk_add_f32 v[0:1], v[2:3], v[0:1] op_sel_hi:[0,1]
	v_pk_fma_f32 v[0:1], v[46:47], v[46:47], v[0:1]
	v_mul_f32_e32 v2, v47, v47
	v_pk_add_f32 v[0:1], v[2:3], v[0:1] op_sel_hi:[0,1]
	v_pk_fma_f32 v[0:1], v[48:49], v[48:49], v[0:1]
	v_mul_f32_e32 v2, v49, v49
	v_pk_add_f32 v[0:1], v[2:3], v[0:1] op_sel_hi:[0,1]
	v_pk_fma_f32 v[0:1], v[32:33], v[32:33], v[0:1]
	v_mul_f32_e32 v2, v33, v33
	v_pk_add_f32 v[0:1], v[2:3], v[0:1] op_sel_hi:[0,1]
	v_pk_fma_f32 v[0:1], v[24:25], v[24:25], v[0:1]
	v_mul_f32_e32 v2, v25, v25
	v_pk_add_f32 v[0:1], v[2:3], v[0:1] op_sel_hi:[0,1]
	v_pk_fma_f32 v[0:1], v[28:29], v[28:29], v[0:1]
	v_mul_f32_e32 v2, v29, v29
	v_pk_add_f32 v[0:1], v[2:3], v[0:1] op_sel_hi:[0,1]
	v_pk_fma_f32 v[0:1], v[26:27], v[26:27], v[0:1]
	v_mul_f32_e32 v2, v27, v27
	v_pk_add_f32 v[0:1], v[2:3], v[0:1] op_sel_hi:[0,1]
	v_pk_fma_f32 v[0:1], v[30:31], v[30:31], v[0:1]
	v_mul_f32_e32 v2, v31, v31
	v_pk_add_f32 v[0:1], v[2:3], v[0:1] op_sel_hi:[0,1]
	v_pk_fma_f32 v[0:1], v[16:17], v[16:17], v[0:1]
	v_mul_f32_e32 v2, v17, v17
	v_pk_add_f32 v[0:1], v[2:3], v[0:1] op_sel_hi:[0,1]
	v_pk_fma_f32 v[0:1], v[20:21], v[20:21], v[0:1]
	v_mul_f32_e32 v2, v21, v21
	v_pk_add_f32 v[0:1], v[2:3], v[0:1] op_sel_hi:[0,1]
	v_pk_fma_f32 v[0:1], v[18:19], v[18:19], v[0:1]
	v_mul_f32_e32 v2, v19, v19
	v_pk_add_f32 v[0:1], v[2:3], v[0:1] op_sel_hi:[0,1]
	v_pk_fma_f32 v[0:1], v[50:51], v[50:51], v[0:1]
	v_mul_f32_e32 v2, v51, v51
	v_pk_add_f32 v[0:1], v[2:3], v[0:1] op_sel_hi:[0,1]
	v_pk_fma_f32 v[0:1], v[52:53], v[52:53], v[0:1]
	v_mul_f32_e32 v2, v53, v53
	v_pk_add_f32 v[0:1], v[2:3], v[0:1] op_sel_hi:[0,1]
	v_pk_fma_f32 v[0:1], v[54:55], v[54:55], v[0:1]
	v_mul_f32_e32 v2, v55, v55
	v_pk_add_f32 v[0:1], v[2:3], v[0:1] op_sel_hi:[0,1]
	v_pk_fma_f32 v[0:1], v[56:57], v[56:57], v[0:1]
	v_mul_f32_e32 v2, v57, v57
	v_pk_add_f32 v[0:1], v[2:3], v[0:1] op_sel_hi:[0,1]
	v_pk_fma_f32 v[0:1], v[58:59], v[58:59], v[0:1]
	v_mul_f32_e32 v2, v59, v59
	v_pk_add_f32 v[0:1], v[2:3], v[0:1] op_sel_hi:[0,1]
	v_pk_fma_f32 v[0:1], v[60:61], v[60:61], v[0:1]
	v_mul_f32_e32 v2, v61, v61
	v_pk_add_f32 v[0:1], v[2:3], v[0:1] op_sel_hi:[0,1]
	v_pk_fma_f32 v[0:1], v[64:65], v[64:65], v[0:1]
	v_mul_f32_e32 v2, v65, v65
	v_pk_add_f32 v[0:1], v[2:3], v[0:1] op_sel_hi:[0,1]
	v_pk_fma_f32 v[0:1], v[66:67], v[66:67], v[0:1]
	v_mul_f32_e32 v2, v67, v67
	v_pk_add_f32 v[0:1], v[2:3], v[0:1] op_sel_hi:[0,1]
	v_pk_fma_f32 v[0:1], v[22:23], v[22:23], v[0:1]
	v_mul_f32_e32 v2, v23, v23
	v_pk_add_f32 v[0:1], v[2:3], v[0:1] op_sel_hi:[0,1]
	v_pk_fma_f32 v[0:1], v[8:9], v[8:9], v[0:1]
	v_mul_f32_e32 v2, v9, v9
	v_pk_add_f32 v[0:1], v[2:3], v[0:1] op_sel_hi:[0,1]
	v_pk_fma_f32 v[0:1], v[12:13], v[12:13], v[0:1]
	v_mul_f32_e32 v2, v13, v13
	v_pk_add_f32 v[0:1], v[2:3], v[0:1] op_sel_hi:[0,1]
	v_pk_fma_f32 v[0:1], v[10:11], v[10:11], v[0:1]
	v_mul_f32_e32 v2, v11, v11
	v_pk_add_f32 v[0:1], v[2:3], v[0:1] op_sel_hi:[0,1]
	v_pk_fma_f32 v[0:1], v[14:15], v[14:15], v[0:1]
	v_mul_f32_e32 v2, v15, v15
	v_pk_add_f32 v[0:1], v[2:3], v[0:1] op_sel_hi:[0,1]
	v_pk_fma_f32 v[0:1], v[4:5], v[4:5], v[0:1]
	v_mul_f32_e32 v2, v5, v5
	v_pk_add_f32 v[0:1], v[2:3], v[0:1] op_sel_hi:[0,1]
	v_pk_fma_f32 v[0:1], v[62:63], v[62:63], v[0:1]
	v_mul_f32_e32 v2, v63, v63
	v_pk_add_f32 v[0:1], v[2:3], v[0:1] op_sel_hi:[0,1]
	v_pk_fma_f32 v[0:1], v[6:7], v[6:7], v[0:1]
	v_mul_f32_e32 v2, v7, v7
	v_pk_add_f32 v[0:1], v[2:3], v[0:1] op_sel_hi:[0,1]
	v_mov_b32_e32 v1, v0
	s_nop 1
	v_permlane32_swap_b32_e32 v0, v1
	v_add_f32_e32 v0, v0, v1
	v_fmamk_f32 v0, v0, 0x3c000000, v206
	v_cmp_gt_f32_e32 vcc, s0, v0
	v_mul_f32_e32 v1, 0x4b800000, v0
	s_nop 0
	v_cndmask_b32_e32 v0, v0, v1, vcc
	v_rsq_f32_e32 v0, v0
	s_nop 0
	v_mul_f32_e32 v1, 0x45800000, v0
	v_cndmask_b32_e32 v68, v0, v1, vcc
	flat_load_dwordx4 v[0:3], v[70:71] offset:80
	s_waitcnt vmcnt(0) lgkmcnt(0)
	v_pk_mul_f32 v[2:3], v[68:69], v[2:3] op_sel_hi:[0,1]
	v_pk_mul_f32 v[0:1], v[68:69], v[0:1] op_sel_hi:[0,1]
	v_pk_mul_f32 v[48:49], v[2:3], v[48:49]
	v_pk_mul_f32 v[46:47], v[0:1], v[46:47]
	flat_load_dwordx4 v[0:3], v[70:71] offset:64
	s_waitcnt vmcnt(0) lgkmcnt(0)
	v_pk_mul_f32 v[2:3], v[68:69], v[2:3] op_sel_hi:[0,1]
	v_pk_mul_f32 v[0:1], v[68:69], v[0:1] op_sel_hi:[0,1]
	v_pk_mul_f32 v[44:45], v[2:3], v[44:45]
	v_pk_mul_f32 v[42:43], v[0:1], v[42:43]
	flat_load_dwordx4 v[0:3], v[70:71] offset:16
	s_waitcnt vmcnt(0) lgkmcnt(0)
	v_pk_mul_f32 v[2:3], v[2:3], v[68:69] op_sel_hi:[1,0]
	v_pk_mul_f32 v[0:1], v[0:1], v[68:69] op_sel_hi:[1,0]
	v_pk_mul_f32 v[40:41], v[2:3], v[40:41]
	v_pk_mul_f32 v[38:39], v[0:1], v[38:39]
	flat_load_dwordx4 v[0:3], v[70:71]
	s_waitcnt vmcnt(0) lgkmcnt(0)
	v_pk_mul_f32 v[2:3], v[2:3], v[68:69] op_sel_hi:[1,0]
	v_pk_mul_f32 v[0:1], v[0:1], v[68:69] op_sel_hi:[1,0]
	v_pk_mul_f32 v[36:37], v[2:3], v[36:37]
	v_pk_mul_f32 v[34:35], v[0:1], v[34:35]
	flat_load_dwordx4 v[0:3], v[70:71] offset:144
	flat_load_dwordx4 v[76:79], v[70:71] offset:128
	s_waitcnt vmcnt(0) lgkmcnt(0)
	v_pk_mul_f32 v[0:1], v[68:69], v[0:1] op_sel_hi:[0,1]
	v_pk_mul_f32 v[76:77], v[68:69], v[76:77] op_sel_hi:[0,1]
	v_pk_mul_f32 v[32:33], v[76:77], v[32:33]
	v_pk_mul_f32 v[76:77], v[68:69], v[78:79] op_sel_hi:[0,1]
	v_pk_mul_f32 v[28:29], v[0:1], v[28:29]
	v_pk_mul_f32 v[0:1], v[68:69], v[2:3] op_sel_hi:[0,1]
	v_pk_mul_f32 v[24:25], v[76:77], v[24:25]
	v_pk_mul_f32 v[26:27], v[0:1], v[26:27]
	flat_load_dwordx4 v[0:3], v[70:71] offset:208
	flat_load_dwordx4 v[76:79], v[70:71] offset:192
	s_waitcnt vmcnt(0) lgkmcnt(0)
	v_pk_mul_f32 v[0:1], v[68:69], v[0:1] op_sel_hi:[0,1]
	v_pk_mul_f32 v[76:77], v[68:69], v[76:77] op_sel_hi:[0,1]
	v_pk_mul_f32 v[30:31], v[76:77], v[30:31]
	v_pk_mul_f32 v[76:77], v[68:69], v[78:79] op_sel_hi:[0,1]
	v_pk_mul_f32 v[20:21], v[0:1], v[20:21]
	v_pk_mul_f32 v[0:1], v[68:69], v[2:3] op_sel_hi:[0,1]
	v_pk_mul_f32 v[16:17], v[76:77], v[16:17]
	v_pk_mul_f32 v[18:19], v[0:1], v[18:19]
	flat_load_dwordx4 v[0:3], v[70:71] offset:336
	s_waitcnt vmcnt(0) lgkmcnt(0)
	v_pk_mul_f32 v[2:3], v[68:69], v[2:3] op_sel_hi:[0,1]
	v_pk_mul_f32 v[0:1], v[68:69], v[0:1] op_sel_hi:[0,1]
	v_pk_mul_f32 v[66:67], v[2:3], v[66:67]
	v_pk_mul_f32 v[64:65], v[0:1], v[64:65]
	flat_load_dwordx4 v[0:3], v[70:71] offset:320
	s_waitcnt vmcnt(0) lgkmcnt(0)
	v_pk_mul_f32 v[2:3], v[68:69], v[2:3] op_sel_hi:[0,1]
	v_pk_mul_f32 v[0:1], v[68:69], v[0:1] op_sel_hi:[0,1]
	v_pk_mul_f32 v[60:61], v[2:3], v[60:61]
	v_pk_mul_f32 v[58:59], v[0:1], v[58:59]
	flat_load_dwordx4 v[0:3], v[70:71] offset:272
	s_waitcnt vmcnt(0) lgkmcnt(0)
	v_pk_mul_f32 v[2:3], v[68:69], v[2:3] op_sel_hi:[0,1]
	v_pk_mul_f32 v[0:1], v[68:69], v[0:1] op_sel_hi:[0,1]
	v_pk_mul_f32 v[56:57], v[2:3], v[56:57]
	v_pk_mul_f32 v[54:55], v[0:1], v[54:55]
	flat_load_dwordx4 v[0:3], v[70:71] offset:256
	s_waitcnt vmcnt(0) lgkmcnt(0)
	v_pk_mul_f32 v[2:3], v[68:69], v[2:3] op_sel_hi:[0,1]
	v_pk_mul_f32 v[0:1], v[68:69], v[0:1] op_sel_hi:[0,1]
	v_pk_mul_f32 v[52:53], v[2:3], v[52:53]
	v_pk_mul_f32 v[50:51], v[0:1], v[50:51]
	flat_load_dwordx4 v[0:3], v[70:71] offset:400
	flat_load_dwordx4 v[76:79], v[70:71] offset:384
	s_waitcnt vmcnt(0) lgkmcnt(0)
	v_pk_mul_f32 v[0:1], v[68:69], v[0:1] op_sel_hi:[0,1]
	v_pk_mul_f32 v[76:77], v[68:69], v[76:77] op_sel_hi:[0,1]
	v_pk_mul_f32 v[22:23], v[76:77], v[22:23]
	v_pk_mul_f32 v[76:77], v[68:69], v[78:79] op_sel_hi:[0,1]
	v_pk_mul_f32 v[12:13], v[0:1], v[12:13]
	v_pk_mul_f32 v[0:1], v[68:69], v[2:3] op_sel_hi:[0,1]
	v_pk_mul_f32 v[8:9], v[76:77], v[8:9]
	v_pk_mul_f32 v[10:11], v[0:1], v[10:11]
	flat_load_dwordx4 v[0:3], v[70:71] offset:464
	flat_load_dwordx4 v[76:79], v[70:71] offset:448
	s_waitcnt vmcnt(0) lgkmcnt(0)
	v_pk_mul_f32 v[0:1], v[68:69], v[0:1] op_sel_hi:[0,1]
	v_pk_mul_f32 v[70:71], v[68:69], v[76:77] op_sel_hi:[0,1]
	v_pk_mul_f32 v[14:15], v[70:71], v[14:15]
	v_pk_mul_f32 v[70:71], v[68:69], v[78:79] op_sel_hi:[0,1]
	v_pk_mul_f32 v[62:63], v[0:1], v[62:63]
	v_pk_mul_f32 v[0:1], v[68:69], v[2:3] op_sel_hi:[0,1]
	v_pk_mul_f32 v[4:5], v[70:71], v[4:5]
	v_pk_mul_f32 v[6:7], v[0:1], v[6:7]

.LBB0_513:
	v_pk_mul_f32 v[0:1], v[34:35], s[70:71] op_sel_hi:[1,0]
	v_pk_mul_f32 v[8:9], v[8:9], s[70:71] op_sel_hi:[1,0]
	v_cvt_pk_bf16_f32 v112, v0, v1
	v_bitop3_b32 v1, v131, v73, 2 bitop3:0x36
	v_cvt_pk_bf16_f32 v121, v8, v9
	v_lshlrev_b32_e32 v8, 4, v1
	v_bitop3_b32 v1, v131, v73, 4 bitop3:0x36
	v_pk_mul_f32 v[10:11], v[10:11], s[70:71] op_sel_hi:[1,0]
	s_cmp_lg_u32 0, -1
	v_lshlrev_b32_e32 v9, 4, v1
	v_bitop3_b32 v1, v131, v73, 6 bitop3:0x36
	v_pk_mul_f32 v[2:3], v[36:37], s[70:71] op_sel_hi:[1,0]
	v_pk_mul_f32 v[36:37], v[40:41], s[70:71] op_sel_hi:[1,0]
	v_pk_mul_f32 v[40:41], v[44:45], s[70:71] op_sel_hi:[1,0]
	v_pk_mul_f32 v[44:45], v[48:49], s[70:71] op_sel_hi:[1,0]
	v_pk_mul_f32 v[48:49], v[52:53], s[70:71] op_sel_hi:[1,0]
	v_pk_mul_f32 v[52:53], v[56:57], s[70:71] op_sel_hi:[1,0]
	v_pk_mul_f32 v[56:57], v[60:61], s[70:71] op_sel_hi:[1,0]
	v_cvt_pk_bf16_f32 v123, v10, v11
	s_cselect_b32 s4, 0, 0
	v_lshlrev_b32_e32 v10, 4, v1
	v_bitop3_b32 v1, v131, v73, 8 bitop3:0x36
	v_pk_mul_f32 v[34:35], v[38:39], s[70:71] op_sel_hi:[1,0]
	v_pk_mul_f32 v[38:39], v[42:43], s[70:71] op_sel_hi:[1,0]
	v_pk_mul_f32 v[42:43], v[46:47], s[70:71] op_sel_hi:[1,0]
	v_pk_mul_f32 v[46:47], v[50:51], s[70:71] op_sel_hi:[1,0]
	v_pk_mul_f32 v[50:51], v[54:55], s[70:71] op_sel_hi:[1,0]
	v_pk_mul_f32 v[54:55], v[58:59], s[70:71] op_sel_hi:[1,0]
	v_pk_mul_f32 v[58:59], v[64:65], s[70:71] op_sel_hi:[1,0]
	v_cvt_pk_bf16_f32 v117, v56, v57
	s_add_i32 s4, s4, 0x10000
	v_xor_b32_e32 v0, v131, v73
	v_lshlrev_b32_e32 v57, 4, v1
	v_bitop3_b32 v1, v131, v73, 10 bitop3:0x36
	v_cvt_pk_bf16_f32 v118, v58, v59
	v_lshl_add_u32 v56, v132, 8, s4
	v_lshlrev_b32_e32 v0, 4, v0
	v_lshlrev_b32_e32 v58, 4, v1
	v_bitop3_b32 v1, v131, v73, 12 bitop3:0x36
	v_pk_mul_f32 v[32:33], v[32:33], s[70:71] op_sel_hi:[1,0]
	v_pk_mul_f32 v[60:61], v[66:67], s[70:71] op_sel_hi:[1,0]
	v_pk_mul_f32 v[4:5], v[4:5], s[70:71] op_sel_hi:[1,0]
	v_pk_mul_f32 v[6:7], v[6:7], s[70:71] op_sel_hi:[1,0]
	v_lshlrev_b32_e32 v59, 4, v1
	v_bitop3_b32 v1, v131, v73, 14 bitop3:0x36
	v_add_u32_e32 v141, v0, v56
	v_add_u32_e32 v140, v8, v56
	v_cvt_pk_bf16_f32 v113, v2, v3
	v_cvt_pk_bf16_f32 v114, v34, v35
	v_cvt_pk_bf16_f32 v115, v36, v37
	v_cvt_pk_bf16_f32 v108, v38, v39
	v_cvt_pk_bf16_f32 v104, v32, v33
	v_cvt_pk_bf16_f32 v119, v60, v61
	v_cvt_pk_bf16_f32 v125, v4, v5
	v_cvt_pk_bf16_f32 v127, v6, v7
	v_lshlrev_b32_e32 v60, 4, v1
	ds_read_b128 v[0:3], v141
	ds_read_b128 v[4:7], v141 offset:8192
	ds_read_b128 v[32:35], v140
	ds_read_b128 v[36:39], v140 offset:8192
	v_add_u32_e32 v134, v9, v56
	v_cvt_pk_bf16_f32 v109, v40, v41
	v_cvt_pk_bf16_f32 v110, v42, v43
	ds_read_b128 v[40:43], v134
	v_pk_mul_f32 v[24:25], v[24:25], s[70:71] op_sel_hi:[1,0]
	v_pk_mul_f32 v[28:29], v[28:29], s[70:71] op_sel_hi:[1,0]
	v_pk_mul_f32 v[26:27], v[26:27], s[70:71] op_sel_hi:[1,0]
	v_pk_mul_f32 v[30:31], v[30:31], s[70:71] op_sel_hi:[1,0]
	v_pk_mul_f32 v[16:17], v[16:17], s[70:71] op_sel_hi:[1,0]
	v_pk_mul_f32 v[20:21], v[20:21], s[70:71] op_sel_hi:[1,0]
	v_pk_mul_f32 v[18:19], v[18:19], s[70:71] op_sel_hi:[1,0]
	v_pk_mul_f32 v[22:23], v[22:23], s[70:71] op_sel_hi:[1,0]
	v_pk_mul_f32 v[12:13], v[12:13], s[70:71] op_sel_hi:[1,0]
	v_pk_mul_f32 v[14:15], v[14:15], s[70:71] op_sel_hi:[1,0]
	v_pk_mul_f32 v[62:63], v[62:63], s[70:71] op_sel_hi:[1,0]
	v_xor_b32_e32 v8, v69, v73
	v_readlane_b32 s4, v253, 5
	v_cvt_pk_bf16_f32 v111, v44, v45
	v_cvt_pk_bf16_f32 v105, v24, v25
	v_cvt_pk_bf16_f32 v106, v28, v29
	v_cvt_pk_bf16_f32 v107, v26, v27
	v_cvt_pk_bf16_f32 v100, v30, v31
	v_cvt_pk_bf16_f32 v101, v16, v17
	v_cvt_pk_bf16_f32 v102, v20, v21
	v_cvt_pk_bf16_f32 v103, v18, v19
	v_cvt_pk_bf16_f32 v96, v46, v47
	v_cvt_pk_bf16_f32 v97, v48, v49
	v_cvt_pk_bf16_f32 v98, v50, v51
	v_cvt_pk_bf16_f32 v99, v52, v53
	v_cvt_pk_bf16_f32 v116, v54, v55
	v_cvt_pk_bf16_f32 v120, v22, v23
	v_cvt_pk_bf16_f32 v122, v12, v13
	v_cvt_pk_bf16_f32 v124, v14, v15
	v_cvt_pk_bf16_f32 v126, v62, v63
	v_lshlrev_b32_e32 v143, 4, v8
	v_or_b32_e32 v144, s4, v69
	v_or_b32_e32 v145, s4, v72
	s_waitcnt lgkmcnt(4)
	v_mfma_f32_32x32x16_bf16 v[16:31], v[0:3], v[112:115], 0
	ds_read_b128 v[44:47], v134 offset:8192
	v_add_u32_e32 v135, v10, v56
	s_waitcnt lgkmcnt(4)
	v_mfma_f32_32x32x16_bf16 v[0:15], v[4:7], v[112:115], 0
	ds_read_b128 v[48:51], v135
	s_waitcnt lgkmcnt(4)
	v_mfma_f32_32x32x16_bf16 v[16:31], v[32:35], v[108:111], v[16:31]
	ds_read_b128 v[52:55], v135 offset:8192
	s_waitcnt lgkmcnt(4)
	v_mfma_f32_32x32x16_bf16 v[0:15], v[36:39], v[108:111], v[0:15]
	v_add_u32_e32 v136, v57, v56
	ds_read_b128 v[32:35], v136
	s_waitcnt lgkmcnt(4)
	v_mfma_f32_32x32x16_bf16 v[16:31], v[40:43], v[104:107], v[16:31]
	ds_read_b128 v[36:39], v136 offset:8192
	s_waitcnt lgkmcnt(4)
	v_mfma_f32_32x32x16_bf16 v[0:15], v[44:47], v[104:107], v[0:15]
	v_add_u32_e32 v137, v58, v56
	ds_read_b128 v[40:43], v137
	s_waitcnt lgkmcnt(4)
	v_mfma_f32_32x32x16_bf16 v[16:31], v[48:51], v[100:103], v[16:31]
	ds_read_b128 v[44:47], v137 offset:8192
	s_waitcnt lgkmcnt(4)
	v_mfma_f32_32x32x16_bf16 v[0:15], v[52:55], v[100:103], v[0:15]
	v_add_u32_e32 v138, v59, v56
	ds_read_b128 v[48:51], v138
	s_waitcnt lgkmcnt(4)
	v_mfma_f32_32x32x16_bf16 v[16:31], v[32:35], v[96:99], v[16:31]
	ds_read_b128 v[52:55], v138 offset:8192
	s_waitcnt lgkmcnt(4)
	v_mfma_f32_32x32x16_bf16 v[0:15], v[36:39], v[96:99], v[0:15]
	v_add_u32_e32 v139, v60, v56
	ds_read_b128 v[32:35], v139
	s_waitcnt lgkmcnt(4)
	v_mfma_f32_32x32x16_bf16 v[16:31], v[40:43], v[116:119], v[16:31]
	ds_read_b128 v[36:39], v139 offset:8192
	s_waitcnt lgkmcnt(4)
	v_mfma_f32_32x32x16_bf16 v[0:15], v[44:47], v[116:119], v[0:15]
	s_waitcnt lgkmcnt(3)
	v_mfma_f32_32x32x16_bf16 v[16:31], v[48:51], v[120:123], v[16:31]
	s_waitcnt lgkmcnt(2)
	v_mfma_f32_32x32x16_bf16 v[0:15], v[52:55], v[120:123], v[0:15]
	s_waitcnt lgkmcnt(1)
	v_mfma_f32_32x32x16_bf16 v[16:31], v[32:35], v[124:127], v[16:31]
	s_waitcnt lgkmcnt(0)
	v_mfma_f32_32x32x16_bf16 v[0:15], v[36:39], v[124:127], v[0:15]
	s_waitcnt vmcnt(0)
	s_barrier
	v_readlane_b32 s4, v253, 15
	v_readlane_b32 s5, v253, 16
	s_andn2_b64 vcc, exec, s[4:5]
	s_nop 0
	v_cndmask_b32_e64 v32, 0, 1, s[4:5]
	v_cmp_ne_u32_e64 s[6:7], 1, v32
	s_cbranch_vccnz .LBB0_515
	v_mul_u32_u24_e32 v32, s48, v144
	v_or_b32_e32 v33, v32, v143
	s_lshl_b32 s4, s28, 8
	s_mov_b32 s5, m0
	s_mov_b32 m0, s58
	s_nop 0
	buffer_load_dwordx4 v33, s[36:39], s4 offen lds
	s_mov_b32 m0, s5
	v_bitop3_b32 v33, v32, 64, v143 bitop3:0x36
	s_mul_i32 s4, s28, 0x108
	s_mov_b32 s5, m0
	s_mov_b32 m0, s84
	s_nop 0
	buffer_load_dwordx4 v33, s[36:39], s4 offen lds
	s_mov_b32 m0, s5
	v_bitop3_b32 v33, v32, s87, v143 bitop3:0x36
	s_mul_i32 s4, s28, 0x110
	s_mov_b32 s5, m0
	s_mov_b32 m0, s79
	s_nop 0
	buffer_load_dwordx4 v33, s[36:39], s4 offen lds
	s_mov_b32 m0, s5
	v_bitop3_b32 v32, v32, s53, v143 bitop3:0x36
	s_mul_i32 s4, s28, 0x118
	s_mov_b32 s5, m0
	s_mov_b32 m0, s80
	s_nop 0
	buffer_load_dwordx4 v32, s[36:39], s4 offen lds
	s_mov_b32 m0, s5
	v_mul_u32_u24_e32 v32, s48, v145
	v_or_b32_e32 v32, v32, v133
	s_mov_b32 s4, m0
	s_mov_b32 m0, s59
	s_nop 0
	buffer_load_dwordx4 v32, s[12:15], s72 offen lds
	s_mov_b32 m0, s4
	v_or_b32_e32 v33, 0x80, v32
	s_mov_b32 s4, m0
	s_mov_b32 m0, s88
	s_nop 0
	buffer_load_dwordx4 v33, s[12:15], s72 offen lds
	s_mov_b32 m0, s4
	s_mul_i32 s4, s28, 0x90
	s_mov_b32 s5, m0
	s_mov_b32 m0, s89
	s_nop 0
	buffer_load_dwordx4 v32, s[12:15], s4 offen lds
	s_mov_b32 m0, s5
	s_nop 0
	s_mov_b32 s5, m0
	s_mov_b32 m0, s44
	s_nop 0
	buffer_load_dwordx4 v33, s[12:15], s4 offen lds
	s_mov_b32 m0, s5

.LBB0_517:
	s_and_b64 vcc, exec, s[0:1]
	s_cbranch_vccz .LBB0_626
	v_mbcnt_lo_u32_b32 v67, -1, 0
	v_mbcnt_hi_u32_b32 v67, -1, v67
	s_lshl_b32 s48, s28, 1
	v_and_b32_e32 v197, 31, v67
	v_or_b32_e32 v71, s92, v197
	v_bfe_u32 v196, v67, 5, 1
	v_mad_u64_u32 v[0:1], s[0:1], v71, s28, 0
	v_lshl_add_u64 v[0:1], v[0:1], 1, s[56:57]
	v_lshlrev_b32_e32 v160, 4, v196
	v_lshl_add_u64 v[4:5], v[0:1], 0, v[160:161]
	global_load_dwordx4 v[24:27], v[4:5], off
	global_load_dwordx4 v[16:19], v[4:5], off offset:32
	global_load_dwordx4 v[28:31], v[4:5], off offset:64
	global_load_dwordx4 v[20:23], v[4:5], off offset:96
	global_load_dwordx4 v[8:11], v[4:5], off offset:128
	global_load_dwordx4 v[0:3], v[4:5], off offset:160
	global_load_dwordx4 v[12:15], v[4:5], off offset:192
	s_nop 0
	global_load_dwordx4 v[4:7], v[4:5], off offset:224
	v_bfe_u32 v68, v67, 4, 2
	v_readlane_b32 s0, v253, 3
	v_and_b32_e32 v69, 15, v67
	v_readlane_b32 s1, v253, 4
	v_or_b32_e32 v32, s0, v68
	v_lshlrev_b32_e32 v35, 4, v67
	v_bitop3_b32 v33, v68, v69, s1 bitop3:0x36
	v_lshlrev_b32_e32 v33, 4, v33
	v_bfe_u32 v70, v67, 2, 3
	v_and_b32_e32 v35, 48, v35
	v_mul_lo_u32 v32, v32, s48
	v_or_b32_e32 v34, s0, v70
	v_lshl_or_b32 v198, v196, 6, v35
	s_and_b32 s37, s91, 0xffff
	s_mov_b32 s36, s90
	v_or_b32_e32 v35, v33, v32
	v_readlane_b32 s1, v253, 6
	s_mov_b32 s0, m0
	s_mov_b32 m0, s1
	s_nop 0
	buffer_load_dwordx4 v35, s[36:39], s49 offen lds
	s_mov_b32 m0, s0
	s_lshl_b32 s0, s28, 3
	v_bitop3_b32 v32, v33, 64, v32 bitop3:0x36
	v_readlane_b32 s4, v253, 8
	s_mov_b32 s1, m0
	s_mov_b32 m0, s4
	s_nop 0
	buffer_load_dwordx4 v32, s[36:39], s0 offen lds
	s_mov_b32 m0, s1
	s_and_b32 s0, s41, 0xffff
	s_mov_b64 s[12:13], s[36:37]
	v_mul_lo_u32 v33, v34, s48
	s_mov_b64 s[14:15], s[38:39]
	s_mov_b32 s12, s40
	s_mov_b32 s13, s0
	v_or_b32_e32 v33, v33, v198
	v_readlane_b32 s1, v253, 7
	s_mov_b32 s0, m0
	s_mov_b32 m0, s1
	s_nop 0
	buffer_load_dwordx4 v33, s[12:15], s49 offen lds
	s_mov_b32 m0, s0
	v_or_b32_e32 v34, 0x80, v33
	v_readlane_b32 s1, v253, 9
	s_mov_b32 s0, m0
	s_mov_b32 m0, s1
	s_nop 0
	buffer_load_dwordx4 v34, s[12:15], s49 offen lds
	s_mov_b32 m0, s0
	v_or_b32_e32 v34, 0x100, v33
	v_readlane_b32 s1, v253, 17
	s_mov_b32 s0, m0
	s_mov_b32 m0, s1
	s_nop 0
	buffer_load_dwordx4 v34, s[12:15], s49 offen lds
	s_mov_b32 m0, s0
	v_or_b32_e32 v33, 0x180, v33
	v_readlane_b32 s1, v253, 18
	s_mov_b32 s0, m0
	s_mov_b32 m0, s1
	s_nop 0
	buffer_load_dwordx4 v33, s[12:15], s49 offen lds
	s_mov_b32 m0, s0
	s_lshl_b32 s68, s28, 7
	v_readlane_b32 s1, v253, 10
	s_mov_b32 s0, m0
	s_mov_b32 m0, s1
	s_nop 0
	buffer_load_dwordx4 v35, s[36:39], s68 offen lds
	s_mov_b32 m0, s0
	v_readlane_b32 s1, v253, 11
	s_mov_b32 s0, m0
	s_mov_b32 m0, s1
	s_nop 0
	buffer_load_dwordx4 v32, s[36:39], s23 offen lds
	s_mov_b32 m0, s0
	v_lshlrev_b32_e32 v66, 3, v196
	s_cmp_eq_u64 s[10:11], 0
	v_lshlrev_b32_e32 v160, 2, v66
	s_waitcnt vmcnt(7)
	v_lshlrev_b32_e32 v34, 16, v24
	v_and_b32_e32 v35, 0xffff0000, v24
	s_waitcnt vmcnt(5)
	v_lshlrev_b32_e32 v32, 16, v28
	v_and_b32_e32 v33, 0xffff0000, v28
	v_lshlrev_b32_e32 v36, 16, v25
	v_and_b32_e32 v37, 0xffff0000, v25
	v_lshlrev_b32_e32 v24, 16, v29
	v_and_b32_e32 v25, 0xffff0000, v29
	v_lshlrev_b32_e32 v38, 16, v26
	v_and_b32_e32 v39, 0xffff0000, v26
	v_lshlrev_b32_e32 v28, 16, v30
	v_and_b32_e32 v29, 0xffff0000, v30
	v_lshlrev_b32_e32 v40, 16, v27
	v_and_b32_e32 v41, 0xffff0000, v27
	v_lshlrev_b32_e32 v26, 16, v31
	v_and_b32_e32 v27, 0xffff0000, v31
	v_lshlrev_b32_e32 v42, 16, v16
	v_and_b32_e32 v43, 0xffff0000, v16
	s_waitcnt vmcnt(4)
	v_lshlrev_b32_e32 v30, 16, v20
	v_and_b32_e32 v31, 0xffff0000, v20
	v_lshlrev_b32_e32 v44, 16, v17
	v_and_b32_e32 v45, 0xffff0000, v17
	v_lshlrev_b32_e32 v16, 16, v21
	v_and_b32_e32 v17, 0xffff0000, v21
	v_lshlrev_b32_e32 v46, 16, v18
	v_and_b32_e32 v47, 0xffff0000, v18
	v_lshlrev_b32_e32 v20, 16, v22
	v_and_b32_e32 v21, 0xffff0000, v22
	v_lshlrev_b32_e32 v48, 16, v19
	v_and_b32_e32 v49, 0xffff0000, v19
	v_lshlrev_b32_e32 v18, 16, v23
	v_and_b32_e32 v19, 0xffff0000, v23
	s_waitcnt vmcnt(3)
	v_lshlrev_b32_e32 v50, 16, v8
	v_and_b32_e32 v51, 0xffff0000, v8
	s_waitcnt vmcnt(1)
	v_lshlrev_b32_e32 v22, 16, v12
	v_and_b32_e32 v23, 0xffff0000, v12
	v_lshlrev_b32_e32 v52, 16, v9
	v_and_b32_e32 v53, 0xffff0000, v9
	v_lshlrev_b32_e32 v8, 16, v13
	v_and_b32_e32 v9, 0xffff0000, v13
	v_lshlrev_b32_e32 v54, 16, v10
	v_and_b32_e32 v55, 0xffff0000, v10
	v_lshlrev_b32_e32 v12, 16, v14
	v_and_b32_e32 v13, 0xffff0000, v14
	v_lshlrev_b32_e32 v56, 16, v11
	v_and_b32_e32 v57, 0xffff0000, v11
	v_lshlrev_b32_e32 v10, 16, v15
	v_and_b32_e32 v11, 0xffff0000, v15
	v_lshlrev_b32_e32 v58, 16, v0
	v_and_b32_e32 v59, 0xffff0000, v0
	s_waitcnt vmcnt(0)
	v_lshlrev_b32_e32 v14, 16, v4
	v_and_b32_e32 v15, 0xffff0000, v4
	v_lshlrev_b32_e32 v60, 16, v1
	v_and_b32_e32 v61, 0xffff0000, v1
	v_lshlrev_b32_e32 v0, 16, v5
	v_and_b32_e32 v1, 0xffff0000, v5
	v_lshlrev_b32_e32 v62, 16, v2
	v_and_b32_e32 v63, 0xffff0000, v2
	v_lshlrev_b32_e32 v4, 16, v6
	v_and_b32_e32 v5, 0xffff0000, v6
	v_lshlrev_b32_e32 v64, 16, v3
	v_and_b32_e32 v65, 0xffff0000, v3
	v_lshlrev_b32_e32 v2, 16, v7
	v_and_b32_e32 v3, 0xffff0000, v7
	s_cbranch_scc1 .LBB0_520
	v_mul_f32_e32 v6, v35, v35
	v_pk_fma_f32 v[6:7], v[34:35], v[34:35], v[6:7] op_sel_hi:[1,1,0]
	v_mul_f32_e32 v66, v37, v37
	v_pk_fma_f32 v[6:7], v[36:37], v[36:37], v[6:7]
	s_nop 0
	v_pk_add_f32 v[6:7], v[66:67], v[6:7] op_sel_hi:[0,1]
	v_pk_fma_f32 v[6:7], v[38:39], v[38:39], v[6:7]
	v_mul_f32_e32 v66, v39, v39
	v_pk_add_f32 v[6:7], v[66:67], v[6:7] op_sel_hi:[0,1]
	v_pk_fma_f32 v[6:7], v[40:41], v[40:41], v[6:7]
	v_mul_f32_e32 v66, v41, v41
	v_pk_add_f32 v[6:7], v[66:67], v[6:7] op_sel_hi:[0,1]
	v_pk_fma_f32 v[6:7], v[42:43], v[42:43], v[6:7]
	v_mul_f32_e32 v66, v43, v43
	v_pk_add_f32 v[6:7], v[66:67], v[6:7] op_sel_hi:[0,1]
	v_pk_fma_f32 v[6:7], v[44:45], v[44:45], v[6:7]
	v_mul_f32_e32 v66, v45, v45
	v_pk_add_f32 v[6:7], v[66:67], v[6:7] op_sel_hi:[0,1]
	v_pk_fma_f32 v[6:7], v[46:47], v[46:47], v[6:7]
	v_mul_f32_e32 v66, v47, v47
	v_pk_add_f32 v[6:7], v[66:67], v[6:7] op_sel_hi:[0,1]
	v_pk_fma_f32 v[6:7], v[48:49], v[48:49], v[6:7]
	v_mul_f32_e32 v66, v49, v49
	v_pk_add_f32 v[6:7], v[66:67], v[6:7] op_sel_hi:[0,1]
	v_pk_fma_f32 v[6:7], v[32:33], v[32:33], v[6:7]
	v_mul_f32_e32 v66, v33, v33
	v_pk_add_f32 v[6:7], v[66:67], v[6:7] op_sel_hi:[0,1]
	v_pk_fma_f32 v[6:7], v[24:25], v[24:25], v[6:7]
	v_mul_f32_e32 v66, v25, v25
	v_pk_add_f32 v[6:7], v[66:67], v[6:7] op_sel_hi:[0,1]
	v_pk_fma_f32 v[6:7], v[28:29], v[28:29], v[6:7]
	v_mul_f32_e32 v66, v29, v29
	v_pk_add_f32 v[6:7], v[66:67], v[6:7] op_sel_hi:[0,1]
	v_pk_fma_f32 v[76:77], v[26:27], v[26:27], v[6:7]
	v_lshl_add_u64 v[6:7], s[10:11], 0, v[160:161]
	v_mul_f32_e32 v66, v27, v27
	flat_load_dwordx4 v[72:75], v[6:7] offset:80
	v_pk_add_f32 v[76:77], v[66:67], v[76:77] op_sel_hi:[0,1]
	v_pk_fma_f32 v[80:81], v[30:31], v[30:31], v[76:77]
	flat_load_dwordx4 v[76:79], v[6:7] offset:64
	v_mul_f32_e32 v66, v31, v31
	v_pk_add_f32 v[80:81], v[66:67], v[80:81] op_sel_hi:[0,1]
	v_pk_fma_f32 v[84:85], v[16:17], v[16:17], v[80:81]
	flat_load_dwordx4 v[80:83], v[6:7] offset:16
	v_mul_f32_e32 v66, v17, v17
	v_pk_add_f32 v[84:85], v[66:67], v[84:85] op_sel_hi:[0,1]
	v_pk_fma_f32 v[88:89], v[20:21], v[20:21], v[84:85]
	flat_load_dwordx4 v[84:87], v[6:7]
	v_mul_f32_e32 v66, v21, v21
	v_pk_add_f32 v[88:89], v[66:67], v[88:89] op_sel_hi:[0,1]
	v_pk_fma_f32 v[88:89], v[18:19], v[18:19], v[88:89]
	v_mul_f32_e32 v66, v19, v19
	v_pk_add_f32 v[88:89], v[66:67], v[88:89] op_sel_hi:[0,1]
	v_pk_fma_f32 v[88:89], v[50:51], v[50:51], v[88:89]
	v_mul_f32_e32 v66, v51, v51
	v_pk_add_f32 v[88:89], v[66:67], v[88:89] op_sel_hi:[0,1]
	v_pk_fma_f32 v[88:89], v[52:53], v[52:53], v[88:89]
	v_mul_f32_e32 v66, v53, v53
	v_pk_add_f32 v[88:89], v[66:67], v[88:89] op_sel_hi:[0,1]
	v_pk_fma_f32 v[88:89], v[54:55], v[54:55], v[88:89]
	v_mul_f32_e32 v66, v55, v55
	v_pk_add_f32 v[88:89], v[66:67], v[88:89] op_sel_hi:[0,1]
	v_pk_fma_f32 v[88:89], v[56:57], v[56:57], v[88:89]
	v_mul_f32_e32 v66, v57, v57
	v_pk_add_f32 v[88:89], v[66:67], v[88:89] op_sel_hi:[0,1]
	v_pk_fma_f32 v[88:89], v[58:59], v[58:59], v[88:89]
	v_mul_f32_e32 v66, v59, v59
	v_pk_add_f32 v[88:89], v[66:67], v[88:89] op_sel_hi:[0,1]
	v_pk_fma_f32 v[88:89], v[60:61], v[60:61], v[88:89]
	v_mul_f32_e32 v66, v61, v61
	v_pk_add_f32 v[88:89], v[66:67], v[88:89] op_sel_hi:[0,1]
	v_pk_fma_f32 v[88:89], v[62:63], v[62:63], v[88:89]
	v_mul_f32_e32 v66, v63, v63
	v_pk_add_f32 v[88:89], v[66:67], v[88:89] op_sel_hi:[0,1]
	v_pk_fma_f32 v[88:89], v[64:65], v[64:65], v[88:89]
	v_mul_f32_e32 v66, v65, v65
	v_pk_add_f32 v[88:89], v[66:67], v[88:89] op_sel_hi:[0,1]
	v_pk_fma_f32 v[88:89], v[22:23], v[22:23], v[88:89]
	v_mul_f32_e32 v66, v23, v23
	v_pk_add_f32 v[88:89], v[66:67], v[88:89] op_sel_hi:[0,1]
	v_pk_fma_f32 v[88:89], v[8:9], v[8:9], v[88:89]
	v_mul_f32_e32 v66, v9, v9
	v_pk_add_f32 v[88:89], v[66:67], v[88:89] op_sel_hi:[0,1]
	v_pk_fma_f32 v[88:89], v[12:13], v[12:13], v[88:89]
	v_mul_f32_e32 v66, v13, v13
	v_pk_add_f32 v[88:89], v[66:67], v[88:89] op_sel_hi:[0,1]
	v_pk_fma_f32 v[88:89], v[10:11], v[10:11], v[88:89]
	v_mul_f32_e32 v66, v11, v11
	v_pk_add_f32 v[88:89], v[66:67], v[88:89] op_sel_hi:[0,1]
	v_pk_fma_f32 v[88:89], v[14:15], v[14:15], v[88:89]
	v_mul_f32_e32 v66, v15, v15
	v_pk_add_f32 v[88:89], v[66:67], v[88:89] op_sel_hi:[0,1]
	v_pk_fma_f32 v[88:89], v[0:1], v[0:1], v[88:89]
	v_mul_f32_e32 v66, v1, v1
	v_pk_add_f32 v[88:89], v[66:67], v[88:89] op_sel_hi:[0,1]
	v_pk_fma_f32 v[88:89], v[4:5], v[4:5], v[88:89]
	v_mul_f32_e32 v66, v5, v5
	v_pk_add_f32 v[88:89], v[66:67], v[88:89] op_sel_hi:[0,1]
	v_pk_fma_f32 v[88:89], v[2:3], v[2:3], v[88:89]
	v_mul_f32_e32 v66, v3, v3
	v_pk_add_f32 v[88:89], v[66:67], v[88:89] op_sel_hi:[0,1]
	v_mov_b32_e32 v66, v88
	s_nop 1
	v_permlane32_swap_b32_e32 v88, v66
	v_add_f32_e32 v66, v88, v66
	v_fmamk_f32 v66, v66, 0x3c000000, v206
	v_mul_f32_e32 v88, 0x4b800000, v66
	v_cmp_gt_f32_e32 vcc, s96, v66
	s_nop 1
	v_cndmask_b32_e32 v66, v66, v88, vcc
	v_rsq_f32_e32 v66, v66
	s_nop 0
	v_mul_f32_e32 v88, 0x45800000, v66
	v_cndmask_b32_e32 v66, v66, v88, vcc
	s_waitcnt vmcnt(0) lgkmcnt(0)
	v_pk_mul_f32 v[72:73], v[66:67], v[72:73] op_sel_hi:[0,1]
	v_pk_mul_f32 v[46:47], v[72:73], v[46:47]
	v_pk_mul_f32 v[72:73], v[66:67], v[78:79] op_sel_hi:[0,1]
	v_pk_mul_f32 v[44:45], v[72:73], v[44:45]
	v_pk_mul_f32 v[72:73], v[66:67], v[76:77] op_sel_hi:[0,1]
	v_pk_mul_f32 v[42:43], v[72:73], v[42:43]
	v_pk_mul_f32 v[72:73], v[82:83], v[66:67] op_sel_hi:[1,0]
	v_pk_mul_f32 v[74:75], v[66:67], v[74:75] op_sel_hi:[0,1]
	v_pk_mul_f32 v[40:41], v[72:73], v[40:41]
	v_pk_mul_f32 v[72:73], v[80:81], v[66:67] op_sel_hi:[1,0]
	v_pk_mul_f32 v[48:49], v[74:75], v[48:49]
	v_pk_mul_f32 v[38:39], v[72:73], v[38:39]
	v_pk_mul_f32 v[72:73], v[86:87], v[66:67] op_sel_hi:[1,0]
	s_nop 0
	v_pk_mul_f32 v[36:37], v[72:73], v[36:37]
	v_pk_mul_f32 v[72:73], v[84:85], v[66:67] op_sel_hi:[1,0]
	s_nop 0
	v_pk_mul_f32 v[34:35], v[72:73], v[34:35]
	flat_load_dwordx4 v[72:75], v[6:7] offset:144
	flat_load_dwordx4 v[76:79], v[6:7] offset:128
	s_waitcnt vmcnt(0) lgkmcnt(0)
	v_pk_mul_f32 v[72:73], v[66:67], v[72:73] op_sel_hi:[0,1]
	v_pk_mul_f32 v[76:77], v[66:67], v[76:77] op_sel_hi:[0,1]
	v_pk_mul_f32 v[32:33], v[76:77], v[32:33]
	v_pk_mul_f32 v[76:77], v[66:67], v[78:79] op_sel_hi:[0,1]
	v_pk_mul_f32 v[28:29], v[72:73], v[28:29]
	v_pk_mul_f32 v[72:73], v[66:67], v[74:75] op_sel_hi:[0,1]
	v_pk_mul_f32 v[24:25], v[76:77], v[24:25]
	v_pk_mul_f32 v[26:27], v[72:73], v[26:27]
	flat_load_dwordx4 v[72:75], v[6:7] offset:208
	flat_load_dwordx4 v[76:79], v[6:7] offset:192
	s_waitcnt vmcnt(0) lgkmcnt(0)
	v_pk_mul_f32 v[72:73], v[66:67], v[72:73] op_sel_hi:[0,1]
	v_pk_mul_f32 v[76:77], v[66:67], v[76:77] op_sel_hi:[0,1]
	v_pk_mul_f32 v[30:31], v[76:77], v[30:31]
	v_pk_mul_f32 v[76:77], v[66:67], v[78:79] op_sel_hi:[0,1]
	v_pk_mul_f32 v[20:21], v[72:73], v[20:21]
	v_pk_mul_f32 v[72:73], v[66:67], v[74:75] op_sel_hi:[0,1]
	v_pk_mul_f32 v[16:17], v[76:77], v[16:17]
	v_pk_mul_f32 v[18:19], v[72:73], v[18:19]
	flat_load_dwordx4 v[72:75], v[6:7] offset:336
	s_waitcnt vmcnt(0) lgkmcnt(0)
	v_pk_mul_f32 v[74:75], v[66:67], v[74:75] op_sel_hi:[0,1]
	v_pk_mul_f32 v[72:73], v[66:67], v[72:73] op_sel_hi:[0,1]
	v_pk_mul_f32 v[64:65], v[74:75], v[64:65]
	v_pk_mul_f32 v[62:63], v[72:73], v[62:63]
	flat_load_dwordx4 v[72:75], v[6:7] offset:320
	s_waitcnt vmcnt(0) lgkmcnt(0)
	v_pk_mul_f32 v[74:75], v[66:67], v[74:75] op_sel_hi:[0,1]
	v_pk_mul_f32 v[72:73], v[66:67], v[72:73] op_sel_hi:[0,1]
	v_pk_mul_f32 v[60:61], v[74:75], v[60:61]
	v_pk_mul_f32 v[58:59], v[72:73], v[58:59]
	flat_load_dwordx4 v[72:75], v[6:7] offset:272
	s_waitcnt vmcnt(0) lgkmcnt(0)
	v_pk_mul_f32 v[74:75], v[66:67], v[74:75] op_sel_hi:[0,1]
	v_pk_mul_f32 v[72:73], v[66:67], v[72:73] op_sel_hi:[0,1]
	v_pk_mul_f32 v[56:57], v[74:75], v[56:57]
	v_pk_mul_f32 v[54:55], v[72:73], v[54:55]
	flat_load_dwordx4 v[72:75], v[6:7] offset:256
	s_waitcnt vmcnt(0) lgkmcnt(0)
	v_pk_mul_f32 v[74:75], v[66:67], v[74:75] op_sel_hi:[0,1]
	v_pk_mul_f32 v[72:73], v[66:67], v[72:73] op_sel_hi:[0,1]
	v_pk_mul_f32 v[52:53], v[74:75], v[52:53]
	v_pk_mul_f32 v[50:51], v[72:73], v[50:51]
	flat_load_dwordx4 v[72:75], v[6:7] offset:400
	flat_load_dwordx4 v[76:79], v[6:7] offset:384
	s_waitcnt vmcnt(0) lgkmcnt(0)
	v_pk_mul_f32 v[72:73], v[66:67], v[72:73] op_sel_hi:[0,1]
	v_pk_mul_f32 v[76:77], v[66:67], v[76:77] op_sel_hi:[0,1]
	v_pk_mul_f32 v[22:23], v[76:77], v[22:23]
	v_pk_mul_f32 v[76:77], v[66:67], v[78:79] op_sel_hi:[0,1]
	v_pk_mul_f32 v[12:13], v[72:73], v[12:13]
	v_pk_mul_f32 v[72:73], v[66:67], v[74:75] op_sel_hi:[0,1]
	v_pk_mul_f32 v[8:9], v[76:77], v[8:9]
	v_pk_mul_f32 v[10:11], v[72:73], v[10:11]
	flat_load_dwordx4 v[72:75], v[6:7] offset:464
	flat_load_dwordx4 v[76:79], v[6:7] offset:448
	s_waitcnt vmcnt(0) lgkmcnt(0)
	v_pk_mul_f32 v[6:7], v[66:67], v[76:77] op_sel_hi:[0,1]
	v_pk_mul_f32 v[14:15], v[6:7], v[14:15]
	v_pk_mul_f32 v[6:7], v[66:67], v[78:79] op_sel_hi:[0,1]
	v_pk_mul_f32 v[0:1], v[6:7], v[0:1]
	v_pk_mul_f32 v[6:7], v[66:67], v[72:73] op_sel_hi:[0,1]
	v_pk_mul_f32 v[4:5], v[6:7], v[4:5]
	v_pk_mul_f32 v[6:7], v[66:67], v[74:75] op_sel_hi:[0,1]
	v_pk_mul_f32 v[2:3], v[6:7], v[2:3]

.LBB0_534:
	v_pk_mul_f32 v[0:1], v[0:1], s[70:71] op_sel_hi:[1,0]
	v_pk_mul_f32 v[8:9], v[8:9], s[70:71] op_sel_hi:[1,0]
	v_cvt_pk_bf16_f32 v191, v0, v1
	v_bitop3_b32 v1, v196, v69, 2 bitop3:0x36
	v_cvt_pk_bf16_f32 v187, v8, v9
	v_lshlrev_b32_e32 v8, 4, v1
	v_bitop3_b32 v1, v196, v69, 4 bitop3:0x36
	v_pk_mul_f32 v[10:11], v[10:11], s[70:71] op_sel_hi:[1,0]
	s_cmp_lg_u32 0, -1
	v_lshlrev_b32_e32 v9, 4, v1
	v_bitop3_b32 v1, v196, v69, 6 bitop3:0x36
	v_pk_mul_f32 v[6:7], v[34:35], s[70:71] op_sel_hi:[1,0]
	v_pk_mul_f32 v[34:35], v[36:37], s[70:71] op_sel_hi:[1,0]
	v_pk_mul_f32 v[36:37], v[38:39], s[70:71] op_sel_hi:[1,0]
	v_pk_mul_f32 v[38:39], v[40:41], s[70:71] op_sel_hi:[1,0]
	v_pk_mul_f32 v[40:41], v[42:43], s[70:71] op_sel_hi:[1,0]
	v_pk_mul_f32 v[42:43], v[44:45], s[70:71] op_sel_hi:[1,0]
	v_pk_mul_f32 v[44:45], v[46:47], s[70:71] op_sel_hi:[1,0]
	v_pk_mul_f32 v[46:47], v[48:49], s[70:71] op_sel_hi:[1,0]
	v_pk_mul_f32 v[48:49], v[50:51], s[70:71] op_sel_hi:[1,0]
	v_pk_mul_f32 v[50:51], v[52:53], s[70:71] op_sel_hi:[1,0]
	v_pk_mul_f32 v[52:53], v[54:55], s[70:71] op_sel_hi:[1,0]
	v_pk_mul_f32 v[54:55], v[56:57], s[70:71] op_sel_hi:[1,0]
	v_pk_mul_f32 v[56:57], v[58:59], s[70:71] op_sel_hi:[1,0]
	v_cvt_pk_bf16_f32 v189, v10, v11
	s_cselect_b32 s4, 0, 0
	v_lshlrev_b32_e32 v10, 4, v1
	v_bitop3_b32 v1, v196, v69, 8 bitop3:0x36
	v_pk_mul_f32 v[58:59], v[60:61], s[70:71] op_sel_hi:[1,0]
	v_cvt_pk_bf16_f32 v182, v56, v57
	s_add_i32 s4, s4, 0x10000
	v_xor_b32_e32 v0, v196, v69
	v_lshlrev_b32_e32 v57, 4, v1
	v_bitop3_b32 v1, v196, v69, 10 bitop3:0x36
	v_cvt_pk_bf16_f32 v183, v58, v59
	v_lshl_add_u32 v56, v197, 8, s4
	v_lshlrev_b32_e32 v0, 4, v0
	v_lshlrev_b32_e32 v58, 4, v1
	v_bitop3_b32 v1, v196, v69, 12 bitop3:0x36
	v_pk_mul_f32 v[32:33], v[32:33], s[70:71] op_sel_hi:[1,0]
	v_pk_mul_f32 v[60:61], v[62:63], s[70:71] op_sel_hi:[1,0]
	v_pk_mul_f32 v[4:5], v[4:5], s[70:71] op_sel_hi:[1,0]
	v_pk_mul_f32 v[2:3], v[2:3], s[70:71] op_sel_hi:[1,0]
	v_lshlrev_b32_e32 v59, 4, v1
	v_bitop3_b32 v1, v196, v69, 14 bitop3:0x36
	v_add_u32_e32 v205, v0, v56
	v_add_u32_e32 v204, v8, v56
	v_cvt_pk_bf16_f32 v178, v6, v7
	v_cvt_pk_bf16_f32 v179, v34, v35
	v_cvt_pk_bf16_f32 v180, v36, v37
	v_cvt_pk_bf16_f32 v181, v38, v39
	v_cvt_pk_bf16_f32 v170, v32, v33
	v_cvt_pk_bf16_f32 v184, v60, v61
	v_cvt_pk_bf16_f32 v192, v4, v5
	v_cvt_pk_bf16_f32 v193, v2, v3
	v_lshlrev_b32_e32 v60, 4, v1
	ds_read_b128 v[0:3], v205
	ds_read_b128 v[4:7], v205 offset:8192
	ds_read_b128 v[32:35], v204
	ds_read_b128 v[36:39], v204 offset:8192
	v_add_u32_e32 v195, v9, v56
	v_cvt_pk_bf16_f32 v174, v40, v41
	v_cvt_pk_bf16_f32 v175, v42, v43
	ds_read_b128 v[40:43], v195
	v_pk_mul_f32 v[24:25], v[24:25], s[70:71] op_sel_hi:[1,0]
	v_pk_mul_f32 v[28:29], v[28:29], s[70:71] op_sel_hi:[1,0]
	v_pk_mul_f32 v[26:27], v[26:27], s[70:71] op_sel_hi:[1,0]
	v_pk_mul_f32 v[30:31], v[30:31], s[70:71] op_sel_hi:[1,0]
	v_pk_mul_f32 v[16:17], v[16:17], s[70:71] op_sel_hi:[1,0]
	v_pk_mul_f32 v[20:21], v[20:21], s[70:71] op_sel_hi:[1,0]
	v_pk_mul_f32 v[18:19], v[18:19], s[70:71] op_sel_hi:[1,0]
	v_pk_mul_f32 v[62:63], v[64:65], s[70:71] op_sel_hi:[1,0]
	v_pk_mul_f32 v[22:23], v[22:23], s[70:71] op_sel_hi:[1,0]
	v_pk_mul_f32 v[12:13], v[12:13], s[70:71] op_sel_hi:[1,0]
	v_pk_mul_f32 v[14:15], v[14:15], s[70:71] op_sel_hi:[1,0]
	v_xor_b32_e32 v8, v68, v69
	v_readlane_b32 s4, v253, 5
	v_cvt_pk_bf16_f32 v176, v44, v45
	v_cvt_pk_bf16_f32 v177, v46, v47
	v_cvt_pk_bf16_f32 v171, v24, v25
	v_cvt_pk_bf16_f32 v172, v28, v29
	v_cvt_pk_bf16_f32 v173, v26, v27
	v_cvt_pk_bf16_f32 v166, v30, v31
	v_cvt_pk_bf16_f32 v167, v16, v17
	v_cvt_pk_bf16_f32 v168, v20, v21
	v_cvt_pk_bf16_f32 v169, v18, v19
	v_cvt_pk_bf16_f32 v162, v48, v49
	v_cvt_pk_bf16_f32 v163, v50, v51
	v_cvt_pk_bf16_f32 v164, v52, v53
	v_cvt_pk_bf16_f32 v165, v54, v55
	v_cvt_pk_bf16_f32 v185, v62, v63
	v_cvt_pk_bf16_f32 v186, v22, v23
	v_cvt_pk_bf16_f32 v188, v12, v13
	v_cvt_pk_bf16_f32 v190, v14, v15
	v_lshlrev_b32_e32 v213, 4, v8
	v_or_b32_e32 v218, s4, v70
	v_or_b32_e32 v219, s4, v68
	s_waitcnt lgkmcnt(4)
	v_mfma_f32_32x32x16_bf16 v[16:31], v[0:3], v[178:181], 0
	ds_read_b128 v[44:47], v195 offset:8192
	v_add_u32_e32 v199, v10, v56
	s_waitcnt lgkmcnt(4)
	v_mfma_f32_32x32x16_bf16 v[0:15], v[4:7], v[178:181], 0
	ds_read_b128 v[48:51], v199
	s_waitcnt lgkmcnt(4)
	v_mfma_f32_32x32x16_bf16 v[16:31], v[32:35], v[174:177], v[16:31]
	ds_read_b128 v[52:55], v199 offset:8192
	s_waitcnt lgkmcnt(4)
	v_mfma_f32_32x32x16_bf16 v[0:15], v[36:39], v[174:177], v[0:15]
	v_add_u32_e32 v200, v57, v56
	ds_read_b128 v[32:35], v200
	s_waitcnt lgkmcnt(4)
	v_mfma_f32_32x32x16_bf16 v[16:31], v[40:43], v[170:173], v[16:31]
	ds_read_b128 v[36:39], v200 offset:8192
	s_waitcnt lgkmcnt(4)
	v_mfma_f32_32x32x16_bf16 v[0:15], v[44:47], v[170:173], v[0:15]
	v_add_u32_e32 v201, v58, v56
	ds_read_b128 v[40:43], v201
	s_waitcnt lgkmcnt(4)
	v_mfma_f32_32x32x16_bf16 v[16:31], v[48:51], v[166:169], v[16:31]
	ds_read_b128 v[44:47], v201 offset:8192
	s_waitcnt lgkmcnt(4)
	v_mfma_f32_32x32x16_bf16 v[0:15], v[52:55], v[166:169], v[0:15]
	v_add_u32_e32 v202, v59, v56
	ds_read_b128 v[48:51], v202
	s_waitcnt lgkmcnt(4)
	v_mfma_f32_32x32x16_bf16 v[16:31], v[32:35], v[162:165], v[16:31]
	ds_read_b128 v[52:55], v202 offset:8192
	s_waitcnt lgkmcnt(4)
	v_mfma_f32_32x32x16_bf16 v[0:15], v[36:39], v[162:165], v[0:15]
	v_add_u32_e32 v203, v60, v56
	ds_read_b128 v[32:35], v203
	s_waitcnt lgkmcnt(4)
	v_mfma_f32_32x32x16_bf16 v[16:31], v[40:43], v[182:185], v[16:31]
	ds_read_b128 v[36:39], v203 offset:8192
	s_waitcnt lgkmcnt(4)
	v_mfma_f32_32x32x16_bf16 v[0:15], v[44:47], v[182:185], v[0:15]
	s_waitcnt lgkmcnt(3)
	v_mfma_f32_32x32x16_bf16 v[16:31], v[48:51], v[186:189], v[16:31]
	s_waitcnt lgkmcnt(2)
	v_mfma_f32_32x32x16_bf16 v[0:15], v[52:55], v[186:189], v[0:15]
	s_waitcnt lgkmcnt(1)
	v_mfma_f32_32x32x16_bf16 v[16:31], v[32:35], v[190:193], v[16:31]
	s_waitcnt lgkmcnt(0)
	v_mfma_f32_32x32x16_bf16 v[0:15], v[36:39], v[190:193], v[0:15]
	s_waitcnt vmcnt(0)
	s_barrier
	v_readlane_b32 s4, v253, 15
	v_readlane_b32 s5, v253, 16
	s_andn2_b64 vcc, exec, s[4:5]
	s_nop 0
	v_cndmask_b32_e64 v32, 0, 1, s[4:5]
	v_cmp_ne_u32_e64 s[6:7], 1, v32
	s_cbranch_vccnz .LBB0_536
	v_mul_u32_u24_e32 v32, s48, v219
	v_or_b32_e32 v33, v32, v213
	s_lshl_b32 s4, s28, 8
	s_mov_b32 s5, m0
	s_mov_b32 m0, s58
	s_nop 0
	buffer_load_dwordx4 v33, s[36:39], s4 offen lds
	s_mov_b32 m0, s5
	v_bitop3_b32 v33, v32, 64, v213 bitop3:0x36
	s_mul_i32 s4, s28, 0x108
	s_mov_b32 s5, m0
	s_mov_b32 m0, s84
	s_nop 0
	buffer_load_dwordx4 v33, s[36:39], s4 offen lds
	s_mov_b32 m0, s5
	v_bitop3_b32 v33, v32, s87, v213 bitop3:0x36
	s_mul_i32 s4, s28, 0x110
	s_mov_b32 s5, m0
	s_mov_b32 m0, s79
	s_nop 0
	buffer_load_dwordx4 v33, s[36:39], s4 offen lds
	s_mov_b32 m0, s5
	v_bitop3_b32 v32, v32, s53, v213 bitop3:0x36
	s_mul_i32 s4, s28, 0x118
	s_mov_b32 s5, m0
	s_mov_b32 m0, s80
	s_nop 0
	buffer_load_dwordx4 v32, s[36:39], s4 offen lds
	s_mov_b32 m0, s5
	v_mul_u32_u24_e32 v32, s48, v218
	v_or_b32_e32 v32, v32, v198
	s_mov_b32 s4, m0
	s_mov_b32 m0, s59
	s_nop 0
	buffer_load_dwordx4 v32, s[12:15], s68 offen lds
	s_mov_b32 m0, s4
	v_or_b32_e32 v33, 0x80, v32
	s_mov_b32 s4, m0
	s_mov_b32 m0, s88
	s_nop 0
	buffer_load_dwordx4 v33, s[12:15], s68 offen lds
	s_mov_b32 m0, s4
	s_mul_i32 s4, s28, 0x90
	s_mov_b32 s5, m0
	s_mov_b32 m0, s89
	s_nop 0
	buffer_load_dwordx4 v32, s[12:15], s4 offen lds
	s_mov_b32 m0, s5
	s_nop 0
	s_mov_b32 s5, m0
	s_mov_b32 m0, s44
	s_nop 0
	buffer_load_dwordx4 v33, s[12:15], s4 offen lds
	s_mov_b32 m0, s5
	v_or_b32_e32 v33, 0x100, v32
	s_mov_b32 s5, m0
	s_mov_b32 m0, s65
	s_nop 0
	buffer_load_dwordx4 v33, s[12:15], s68 offen lds
	s_mov_b32 m0, s5
	v_or_b32_e32 v32, 0x180, v32
	s_mov_b32 s5, m0
	s_mov_b32 m0, s33
	s_nop 0
	buffer_load_dwordx4 v32, s[12:15], s68 offen lds
	s_mov_b32 m0, s5
	s_nop 0
	s_mov_b32 s5, m0
	s_mov_b32 m0, s93
	s_nop 0
	buffer_load_dwordx4 v33, s[12:15], s4 offen lds
	s_mov_b32 m0, s5
	s_nop 0
	s_mov_b32 s5, m0
	s_mov_b32 m0, s16
	s_nop 0
	buffer_load_dwordx4 v32, s[12:15], s4 offen lds
	s_mov_b32 m0, s5

.LBB0_543:
	ds_read_b64_tr_b16 v[144:145], v160
	ds_read_b64_tr_b16 v[148:149], v160 offset:512
	ds_read_b64_tr_b16 v[152:153], v160 offset:1024
	ds_read_b64_tr_b16 v[156:157], v160 offset:1536
	ds_read_b64_tr_b16 v[146:147], v160 offset:2048
	ds_read_b64_tr_b16 v[150:151], v160 offset:2560
	ds_read_b64_tr_b16 v[154:155], v160 offset:3072
	ds_read_b64_tr_b16 v[158:159], v160 offset:3584
	ds_read_b64_tr_b16 v[222:223], v160 offset:4096
	ds_read_b64_tr_b16 v[224:225], v160 offset:6144
	s_waitcnt lgkmcnt(5)
	v_mfma_f32_32x32x16_bf16 v[96:111], v[140:143], v[144:147], v[96:111]
	ds_read_b64_tr_b16 v[226:227], v160 offset:4608
	ds_read_b64_tr_b16 v[228:229], v160 offset:6656
	s_waitcnt lgkmcnt(6)
	v_mfma_f32_32x32x16_bf16 v[112:127], v[140:143], v[148:151], v[112:127]
	ds_read_b64_tr_b16 v[144:145], v160 offset:5120
	ds_read_b64_tr_b16 v[146:147], v160 offset:7168
	s_waitcnt lgkmcnt(7)
	v_mfma_f32_32x32x16_bf16 v[64:79], v[140:143], v[152:155], v[64:79]
	ds_read_b64_tr_b16 v[148:149], v160 offset:5632
	ds_read_b64_tr_b16 v[150:151], v160 offset:7680
	s_waitcnt lgkmcnt(8)
	v_mfma_f32_32x32x16_bf16 v[80:95], v[140:143], v[156:159], v[80:95]
	ds_read_b64_tr_b16 v[152:153], v160 offset:8192
	ds_read_b64_tr_b16 v[154:155], v160 offset:10240
	s_waitcnt lgkmcnt(8)
	v_mfma_f32_32x32x16_bf16 v[96:111], v[136:139], v[222:225], v[96:111]
	ds_read_b64_tr_b16 v[156:157], v160 offset:8704
	ds_read_b64_tr_b16 v[158:159], v160 offset:10752
	s_waitcnt lgkmcnt(8)
	v_mfma_f32_32x32x16_bf16 v[112:127], v[136:139], v[226:229], v[112:127]
	ds_read_b64_tr_b16 v[222:223], v160 offset:9216
	ds_read_b64_tr_b16 v[224:225], v160 offset:11264
	s_waitcnt lgkmcnt(8)
	v_mfma_f32_32x32x16_bf16 v[64:79], v[136:139], v[144:147], v[64:79]
	ds_read_b64_tr_b16 v[226:227], v160 offset:9728
	ds_read_b64_tr_b16 v[228:229], v160 offset:11776
	s_waitcnt lgkmcnt(8)
	v_mfma_f32_32x32x16_bf16 v[80:95], v[136:139], v[148:151], v[80:95]
	ds_read_b64_tr_b16 v[144:145], v160 offset:12288
	ds_read_b64_tr_b16 v[146:147], v160 offset:14336
	s_waitcnt lgkmcnt(8)
	v_mfma_f32_32x32x16_bf16 v[96:111], v[132:135], v[152:155], v[96:111]
	ds_read_b64_tr_b16 v[148:149], v160 offset:12800
	ds_read_b64_tr_b16 v[150:151], v160 offset:14848
	s_waitcnt lgkmcnt(8)
	v_mfma_f32_32x32x16_bf16 v[112:127], v[132:135], v[156:159], v[112:127]
	ds_read_b64_tr_b16 v[152:153], v160 offset:13312
	ds_read_b64_tr_b16 v[154:155], v160 offset:15360
	s_waitcnt lgkmcnt(8)
	v_mfma_f32_32x32x16_bf16 v[64:79], v[132:135], v[222:225], v[64:79]
	ds_read_b64_tr_b16 v[156:157], v160 offset:13824
	ds_read_b64_tr_b16 v[158:159], v160 offset:15872
	s_waitcnt lgkmcnt(8)
	v_mfma_f32_32x32x16_bf16 v[80:95], v[132:135], v[226:229], v[80:95]
	ds_read_b64_tr_b16 v[222:223], v160 offset:16384
	ds_read_b64_tr_b16 v[224:225], v160 offset:18432
	s_waitcnt lgkmcnt(8)
	v_mfma_f32_32x32x16_bf16 v[96:111], v[128:131], v[144:147], v[96:111]
	ds_read_b64_tr_b16 v[226:227], v160 offset:16896
	ds_read_b64_tr_b16 v[228:229], v160 offset:18944
	s_waitcnt lgkmcnt(8)
	v_mfma_f32_32x32x16_bf16 v[112:127], v[128:131], v[148:151], v[112:127]
	ds_read_b64_tr_b16 v[144:145], v160 offset:17408
	ds_read_b64_tr_b16 v[146:147], v160 offset:19456
	s_waitcnt lgkmcnt(8)
	v_mfma_f32_32x32x16_bf16 v[64:79], v[128:131], v[152:155], v[64:79]
	ds_read_b64_tr_b16 v[148:149], v160 offset:17920
	ds_read_b64_tr_b16 v[150:151], v160 offset:19968
	s_waitcnt lgkmcnt(8)
	v_mfma_f32_32x32x16_bf16 v[80:95], v[128:131], v[156:159], v[80:95]
	ds_read_b64_tr_b16 v[152:153], v160 offset:20480
	ds_read_b64_tr_b16 v[154:155], v160 offset:22528
	s_waitcnt lgkmcnt(8)
	v_mfma_f32_32x32x16_bf16 v[32:47], v[140:143], v[222:225], v[32:47]
	ds_read_b64_tr_b16 v[156:157], v160 offset:20992
	ds_read_b64_tr_b16 v[158:159], v160 offset:23040
	s_waitcnt lgkmcnt(8)
	v_mfma_f32_32x32x16_bf16 v[48:63], v[140:143], v[226:229], v[48:63]
	ds_read_b64_tr_b16 v[222:223], v160 offset:21504
	ds_read_b64_tr_b16 v[224:225], v160 offset:23552
	s_waitcnt lgkmcnt(8)
	v_mfma_f32_32x32x16_bf16 v[0:15], v[140:143], v[144:147], v[0:15]
	ds_read_b64_tr_b16 v[226:227], v160 offset:22016
	ds_read_b64_tr_b16 v[228:229], v160 offset:24064
	s_waitcnt lgkmcnt(8)
	v_mfma_f32_32x32x16_bf16 v[16:31], v[140:143], v[148:151], v[16:31]
	ds_read_b64_tr_b16 v[144:145], v160 offset:24576
	ds_read_b64_tr_b16 v[146:147], v160 offset:26624
	s_waitcnt lgkmcnt(8)
	v_mfma_f32_32x32x16_bf16 v[32:47], v[136:139], v[152:155], v[32:47]
	ds_read_b64_tr_b16 v[140:141], v160 offset:25088
	ds_read_b64_tr_b16 v[142:143], v160 offset:27136
	s_waitcnt lgkmcnt(8)
	v_mfma_f32_32x32x16_bf16 v[48:63], v[136:139], v[156:159], v[48:63]
	ds_read_b64_tr_b16 v[148:149], v160 offset:25600
	ds_read_b64_tr_b16 v[150:151], v160 offset:27648
	s_waitcnt lgkmcnt(8)
	v_mfma_f32_32x32x16_bf16 v[0:15], v[136:139], v[222:225], v[0:15]
	ds_read_b64_tr_b16 v[152:153], v160 offset:26112
	ds_read_b64_tr_b16 v[154:155], v160 offset:28160
	s_waitcnt lgkmcnt(8)
	v_mfma_f32_32x32x16_bf16 v[16:31], v[136:139], v[226:229], v[16:31]
	ds_read_b64_tr_b16 v[156:157], v160 offset:28672
	ds_read_b64_tr_b16 v[158:159], v160 offset:30720
	s_waitcnt lgkmcnt(8)
	v_mfma_f32_32x32x16_bf16 v[32:47], v[132:135], v[144:147], v[32:47]
	ds_read_b64_tr_b16 v[136:137], v160 offset:29184
	ds_read_b64_tr_b16 v[138:139], v160 offset:31232
	s_waitcnt lgkmcnt(8)
	v_mfma_f32_32x32x16_bf16 v[48:63], v[132:135], v[140:143], v[48:63]
	ds_read_b64_tr_b16 v[144:145], v160 offset:29696
	ds_read_b64_tr_b16 v[146:147], v160 offset:31744
	s_waitcnt lgkmcnt(8)
	v_mfma_f32_32x32x16_bf16 v[0:15], v[132:135], v[148:151], v[0:15]
	ds_read_b64_tr_b16 v[140:141], v160 offset:30208
	ds_read_b64_tr_b16 v[142:143], v160 offset:32256
	s_waitcnt lgkmcnt(8)
	v_mfma_f32_32x32x16_bf16 v[16:31], v[132:135], v[152:155], v[16:31]
	ds_read_b128 v[148:151], v205 offset:16384
	s_waitcnt lgkmcnt(7)
	v_mfma_f32_32x32x16_bf16 v[32:47], v[128:131], v[156:159], v[32:47]
	ds_read_b128 v[132:135], v205 offset:24576
	s_waitcnt lgkmcnt(6)
	v_mfma_f32_32x32x16_bf16 v[48:63], v[128:131], v[136:139], v[48:63]
	ds_read_b128 v[222:225], v204 offset:16384
	s_waitcnt lgkmcnt(5)
	v_mfma_f32_32x32x16_bf16 v[0:15], v[128:131], v[144:147], v[0:15]
	ds_read_b128 v[226:229], v204 offset:24576
	s_waitcnt lgkmcnt(4)
	v_mfma_f32_32x32x16_bf16 v[16:31], v[128:131], v[140:143], v[16:31]
	ds_read_b128 v[230:233], v195 offset:16384
	s_waitcnt lgkmcnt(4)
	v_mfma_f32_32x32x16_bf16 v[144:159], v[148:151], v[178:181], 0
	ds_read_b128 v[234:237], v195 offset:24576
	s_waitcnt lgkmcnt(4)
	v_mfma_f32_32x32x16_bf16 v[128:143], v[132:135], v[178:181], 0
	ds_read_b128 v[238:241], v199 offset:16384
	s_waitcnt lgkmcnt(4)
	v_mfma_f32_32x32x16_bf16 v[144:159], v[222:225], v[174:177], v[144:159]
	ds_read_b128 v[242:245], v199 offset:24576
	s_waitcnt lgkmcnt(4)
	v_mfma_f32_32x32x16_bf16 v[128:143], v[226:229], v[174:177], v[128:143]
	ds_read_b128 v[222:225], v200 offset:16384
	s_waitcnt lgkmcnt(4)
	v_mfma_f32_32x32x16_bf16 v[144:159], v[230:233], v[170:173], v[144:159]
	ds_read_b128 v[226:229], v200 offset:24576
	s_waitcnt lgkmcnt(4)
	v_mfma_f32_32x32x16_bf16 v[128:143], v[234:237], v[170:173], v[128:143]
	ds_read_b128 v[230:233], v201 offset:16384
	s_waitcnt lgkmcnt(4)
	v_mfma_f32_32x32x16_bf16 v[144:159], v[238:241], v[166:169], v[144:159]
	ds_read_b128 v[234:237], v201 offset:24576
	s_waitcnt lgkmcnt(4)
	v_mfma_f32_32x32x16_bf16 v[128:143], v[242:245], v[166:169], v[128:143]
	ds_read_b128 v[238:241], v202 offset:16384
	s_waitcnt lgkmcnt(4)
	v_mfma_f32_32x32x16_bf16 v[144:159], v[222:225], v[162:165], v[144:159]
	ds_read_b128 v[242:245], v202 offset:24576
	s_waitcnt lgkmcnt(4)
	v_mfma_f32_32x32x16_bf16 v[128:143], v[226:229], v[162:165], v[128:143]
	ds_read_b128 v[222:225], v203 offset:16384
	s_waitcnt lgkmcnt(4)
	v_mfma_f32_32x32x16_bf16 v[144:159], v[230:233], v[182:185], v[144:159]
	ds_read_b128 v[226:229], v203 offset:24576
	s_waitcnt lgkmcnt(4)
	v_mfma_f32_32x32x16_bf16 v[128:143], v[234:237], v[182:185], v[128:143]
	s_waitcnt lgkmcnt(3)
	v_mfma_f32_32x32x16_bf16 v[144:159], v[238:241], v[186:189], v[144:159]
	s_waitcnt lgkmcnt(2)
	v_mfma_f32_32x32x16_bf16 v[128:143], v[242:245], v[186:189], v[128:143]
	s_waitcnt lgkmcnt(1)
	v_mfma_f32_32x32x16_bf16 v[144:159], v[222:225], v[190:193], v[144:159]
	s_waitcnt lgkmcnt(0)
	v_mfma_f32_32x32x16_bf16 v[128:143], v[226:229], v[190:193], v[128:143]
	s_waitcnt vmcnt(0)
	s_barrier
	s_and_b64 vcc, exec, s[6:7]
	s_cbranch_vccnz .LBB0_547
	s_add_i32 s4, s12, 1
	s_cmp_ge_u32 s4, s10
	s_cbranch_scc1 .LBB0_546
	s_add_i32 s13, s11, 64
	s_cmp_lt_u32 s13, s29
	s_cselect_b64 s[4:5], -1, 0
	s_and_b64 s[14:15], s[4:5], exec
	s_cselect_b32 s14, s91, s43
	s_cselect_b32 s36, s90, s42
	s_and_b32 s37, s14, 0xffff
	s_and_b64 s[4:5], s[4:5], exec
	s_cselect_b32 s4, s28, s24
	s_lshl_b32 s5, s4, 1
	s_sub_i32 s14, s13, s29
	s_min_u32 s13, s13, s14
	v_mul_u32_u24_e32 v215, s5, v219
	v_or_b32_e32 v216, v215, v213
	s_mul_i32 s5, s13, s5
	s_mov_b32 s13, m0
	s_mov_b32 m0, s85
	s_nop 0
	buffer_load_dwordx4 v216, s[36:39], s5 offen lds
	s_mov_b32 m0, s13
	s_lshl_b32 s4, s4, 3
	v_bitop3_b32 v216, v215, 64, v213 bitop3:0x36
	s_add_i32 s5, s5, s4
	s_mov_b32 s13, m0
	s_mov_b32 m0, s76
	s_nop 0
	buffer_load_dwordx4 v216, s[36:39], s5 offen lds
	s_mov_b32 m0, s13
	v_bitop3_b32 v216, v215, s87, v213 bitop3:0x36
	s_add_i32 s5, s5, s4
	s_mov_b32 s13, m0
	s_mov_b32 m0, s45
	s_nop 0
	buffer_load_dwordx4 v216, s[36:39], s5 offen lds
	s_mov_b32 m0, s13
	v_bitop3_b32 v215, v215, s53, v213 bitop3:0x36
	s_add_i32 s5, s5, s4
	s_mov_b32 s4, m0
	s_mov_b32 m0, s82
	s_nop 0
	buffer_load_dwordx4 v215, s[36:39], s5 offen lds
	s_mov_b32 m0, s4
.LBB0_546:
	s_cmp_lt_u32 s11, s29
	s_cselect_b64 s[4:5], -1, 0
	s_and_b64 s[14:15], s[4:5], exec
	s_cselect_b32 s13, s41, s95
	s_cselect_b32 s36, s40, s94
	s_and_b32 s37, s13, 0xffff
	s_and_b64 s[4:5], s[4:5], exec
	s_cselect_b32 s4, s28, s24
	s_lshl_b32 s5, s4, 1
	s_sub_i32 s13, s11, s29
	s_min_u32 s13, s11, s13
	v_mul_u32_u24_e32 v215, s5, v218
	v_or_b32_e32 v215, v215, v198
	s_mul_i32 s5, s13, s5
	s_mov_b32 s13, m0
	s_mov_b32 m0, s64
	s_nop 0
	buffer_load_dwordx4 v215, s[36:39], s5 offen lds
	s_mov_b32 m0, s13
	v_or_b32_e32 v216, 0x80, v215
	s_mov_b32 s13, m0
	s_mov_b32 m0, s77
	s_nop 0
	buffer_load_dwordx4 v216, s[36:39], s5 offen lds
	s_mov_b32 m0, s13
	s_lshl_b32 s4, s4, 4
	s_add_i32 s4, s5, s4
	s_mov_b32 s13, m0
	s_mov_b32 m0, s83
	s_nop 0
	buffer_load_dwordx4 v215, s[36:39], s4 offen lds
	s_mov_b32 m0, s13
	s_nop 0
	s_mov_b32 s13, m0
	s_mov_b32 m0, s81
	s_nop 0
	buffer_load_dwordx4 v216, s[36:39], s4 offen lds
	s_mov_b32 m0, s13
	v_or_b32_e32 v216, 0x100, v215
	s_mov_b32 s13, m0
	s_mov_b32 m0, s54
	s_nop 0
	buffer_load_dwordx4 v216, s[36:39], s5 offen lds
	s_mov_b32 m0, s13
	v_or_b32_e32 v215, 0x180, v215
	s_mov_b32 s13, m0
	s_mov_b32 m0, s55
	s_nop 0
	buffer_load_dwordx4 v215, s[36:39], s5 offen lds
	s_mov_b32 m0, s13
	s_mov_b32 s5, m0
	s_mov_b32 m0, s78
	s_nop 0
	buffer_load_dwordx4 v216, s[36:39], s4 offen lds
	s_mov_b32 m0, s5
	s_nop 0
	s_mov_b32 s5, m0
	s_mov_b32 m0, s71
	s_nop 0
	buffer_load_dwordx4 v215, s[36:39], s4 offen lds
	s_mov_b32 m0, s5

.LBB0_550:
	v_cvt_pk_bf16_f32 v140, v222, v223
	v_cvt_pk_bf16_f32 v141, v224, v225
	v_cvt_pk_bf16_f32 v142, v226, v227
	v_cvt_pk_bf16_f32 v143, v228, v229
	v_cvt_pk_bf16_f32 v136, v230, v231
	v_cvt_pk_bf16_f32 v137, v232, v233
	v_cvt_pk_bf16_f32 v138, v234, v235
	v_cvt_pk_bf16_f32 v139, v236, v237
	v_cvt_pk_bf16_f32 v132, v238, v239
	v_cvt_pk_bf16_f32 v133, v240, v241
	v_cvt_pk_bf16_f32 v134, v242, v243
	v_cvt_pk_bf16_f32 v135, v244, v245
	v_cvt_pk_bf16_f32 v128, v246, v247
	v_cvt_pk_bf16_f32 v129, v248, v249
	v_cvt_pk_bf16_f32 v130, v250, v251
	v_cvt_pk_bf16_f32 v131, v215, v216
	s_barrier
	ds_read_b64_tr_b16 v[144:145], v160 offset:32768
	ds_read_b64_tr_b16 v[148:149], v160 offset:33280
	ds_read_b64_tr_b16 v[152:153], v160 offset:33792
	ds_read_b64_tr_b16 v[156:157], v160 offset:34304
	ds_read_b64_tr_b16 v[146:147], v160 offset:34816
	ds_read_b64_tr_b16 v[150:151], v160 offset:35328
	ds_read_b64_tr_b16 v[154:155], v160 offset:35840
	ds_read_b64_tr_b16 v[158:159], v160 offset:36352
	ds_read_b64_tr_b16 v[222:223], v160 offset:36864
	ds_read_b64_tr_b16 v[224:225], v160 offset:38912
	s_waitcnt lgkmcnt(5)
	v_mfma_f32_32x32x16_bf16 v[96:111], v[140:143], v[144:147], v[96:111]
	ds_read_b64_tr_b16 v[226:227], v160 offset:37376
	ds_read_b64_tr_b16 v[228:229], v160 offset:39424
	s_waitcnt lgkmcnt(6)
	v_mfma_f32_32x32x16_bf16 v[112:127], v[140:143], v[148:151], v[112:127]
	ds_read_b64_tr_b16 v[144:145], v160 offset:37888
	ds_read_b64_tr_b16 v[146:147], v160 offset:39936
	s_waitcnt lgkmcnt(7)
	v_mfma_f32_32x32x16_bf16 v[64:79], v[140:143], v[152:155], v[64:79]
	ds_read_b64_tr_b16 v[148:149], v160 offset:38400
	ds_read_b64_tr_b16 v[150:151], v160 offset:40448
	s_waitcnt lgkmcnt(8)
	v_mfma_f32_32x32x16_bf16 v[80:95], v[140:143], v[156:159], v[80:95]
	ds_read_b64_tr_b16 v[152:153], v160 offset:40960
	ds_read_b64_tr_b16 v[154:155], v160 offset:43008
	s_waitcnt lgkmcnt(8)
	v_mfma_f32_32x32x16_bf16 v[96:111], v[136:139], v[222:225], v[96:111]
	ds_read_b64_tr_b16 v[156:157], v160 offset:41472
	ds_read_b64_tr_b16 v[158:159], v160 offset:43520
	s_waitcnt lgkmcnt(8)
	v_mfma_f32_32x32x16_bf16 v[112:127], v[136:139], v[226:229], v[112:127]
	ds_read_b64_tr_b16 v[222:223], v160 offset:41984
	ds_read_b64_tr_b16 v[224:225], v160 offset:44032
	s_waitcnt lgkmcnt(8)
	v_mfma_f32_32x32x16_bf16 v[64:79], v[136:139], v[144:147], v[64:79]
	ds_read_b64_tr_b16 v[226:227], v160 offset:42496
	ds_read_b64_tr_b16 v[228:229], v160 offset:44544
	s_waitcnt lgkmcnt(8)
	v_mfma_f32_32x32x16_bf16 v[80:95], v[136:139], v[148:151], v[80:95]
	ds_read_b64_tr_b16 v[144:145], v160 offset:45056
	ds_read_b64_tr_b16 v[146:147], v160 offset:47104
	s_waitcnt lgkmcnt(8)
	v_mfma_f32_32x32x16_bf16 v[96:111], v[132:135], v[152:155], v[96:111]
	ds_read_b64_tr_b16 v[148:149], v160 offset:45568
	ds_read_b64_tr_b16 v[150:151], v160 offset:47616
	s_waitcnt lgkmcnt(8)
	v_mfma_f32_32x32x16_bf16 v[112:127], v[132:135], v[156:159], v[112:127]
	ds_read_b64_tr_b16 v[152:153], v160 offset:46080
	ds_read_b64_tr_b16 v[154:155], v160 offset:48128
	s_waitcnt lgkmcnt(8)
	v_mfma_f32_32x32x16_bf16 v[64:79], v[132:135], v[222:225], v[64:79]
	ds_read_b64_tr_b16 v[156:157], v160 offset:46592
	ds_read_b64_tr_b16 v[158:159], v160 offset:48640
	s_waitcnt lgkmcnt(8)
	v_mfma_f32_32x32x16_bf16 v[80:95], v[132:135], v[226:229], v[80:95]
	ds_read_b64_tr_b16 v[222:223], v160 offset:49152
	ds_read_b64_tr_b16 v[224:225], v160 offset:51200
	s_waitcnt lgkmcnt(8)
	v_mfma_f32_32x32x16_bf16 v[96:111], v[128:131], v[144:147], v[96:111]
	ds_read_b64_tr_b16 v[226:227], v160 offset:49664
	ds_read_b64_tr_b16 v[228:229], v160 offset:51712
	s_waitcnt lgkmcnt(8)
	v_mfma_f32_32x32x16_bf16 v[112:127], v[128:131], v[148:151], v[112:127]
	ds_read_b64_tr_b16 v[144:145], v160 offset:50176
	ds_read_b64_tr_b16 v[146:147], v160 offset:52224
	s_waitcnt lgkmcnt(8)
	v_mfma_f32_32x32x16_bf16 v[64:79], v[128:131], v[152:155], v[64:79]
	ds_read_b64_tr_b16 v[148:149], v160 offset:50688
	ds_read_b64_tr_b16 v[150:151], v160 offset:52736
	s_waitcnt lgkmcnt(8)
	v_mfma_f32_32x32x16_bf16 v[80:95], v[128:131], v[156:159], v[80:95]
	ds_read_b64_tr_b16 v[152:153], v160 offset:53248
	ds_read_b64_tr_b16 v[154:155], v160 offset:55296
	s_waitcnt lgkmcnt(8)
	v_mfma_f32_32x32x16_bf16 v[32:47], v[140:143], v[222:225], v[32:47]
	ds_read_b64_tr_b16 v[156:157], v160 offset:53760
	ds_read_b64_tr_b16 v[158:159], v160 offset:55808
	s_waitcnt lgkmcnt(8)
	v_mfma_f32_32x32x16_bf16 v[48:63], v[140:143], v[226:229], v[48:63]
	ds_read_b64_tr_b16 v[222:223], v160 offset:54272
	ds_read_b64_tr_b16 v[224:225], v160 offset:56320
	s_waitcnt lgkmcnt(8)
	v_mfma_f32_32x32x16_bf16 v[0:15], v[140:143], v[144:147], v[0:15]
	ds_read_b64_tr_b16 v[226:227], v160 offset:54784
	ds_read_b64_tr_b16 v[228:229], v160 offset:56832
	s_waitcnt lgkmcnt(8)
	v_mfma_f32_32x32x16_bf16 v[16:31], v[140:143], v[148:151], v[16:31]
	ds_read_b64_tr_b16 v[144:145], v160 offset:57344
	ds_read_b64_tr_b16 v[146:147], v160 offset:59392
	s_waitcnt lgkmcnt(8)
	v_mfma_f32_32x32x16_bf16 v[32:47], v[136:139], v[152:155], v[32:47]
	ds_read_b64_tr_b16 v[140:141], v160 offset:57856
	ds_read_b64_tr_b16 v[142:143], v160 offset:59904
	s_waitcnt lgkmcnt(8)
	v_mfma_f32_32x32x16_bf16 v[48:63], v[136:139], v[156:159], v[48:63]
	ds_read_b64_tr_b16 v[148:149], v160 offset:58368
	ds_read_b64_tr_b16 v[150:151], v160 offset:60416
	s_waitcnt lgkmcnt(8)
	v_mfma_f32_32x32x16_bf16 v[0:15], v[136:139], v[222:225], v[0:15]
	ds_read_b64_tr_b16 v[152:153], v160 offset:58880
	ds_read_b64_tr_b16 v[154:155], v160 offset:60928
	s_waitcnt lgkmcnt(8)
	v_mfma_f32_32x32x16_bf16 v[16:31], v[136:139], v[226:229], v[16:31]
	ds_read_b64_tr_b16 v[156:157], v160 offset:61440
	ds_read_b64_tr_b16 v[158:159], v160 offset:63488
	s_waitcnt lgkmcnt(8)
	v_mfma_f32_32x32x16_bf16 v[32:47], v[132:135], v[144:147], v[32:47]
	ds_read_b64_tr_b16 v[136:137], v160 offset:61952
	ds_read_b64_tr_b16 v[138:139], v160 offset:64000
	s_waitcnt lgkmcnt(8)
	v_mfma_f32_32x32x16_bf16 v[48:63], v[132:135], v[140:143], v[48:63]
	ds_read_b64_tr_b16 v[144:145], v160 offset:62464
	ds_read_b64_tr_b16 v[146:147], v160 offset:64512
	s_waitcnt lgkmcnt(8)
	v_mfma_f32_32x32x16_bf16 v[0:15], v[132:135], v[148:151], v[0:15]
	ds_read_b64_tr_b16 v[140:141], v160 offset:62976
	ds_read_b64_tr_b16 v[142:143], v160 offset:65024
	s_waitcnt lgkmcnt(8)
	v_mfma_f32_32x32x16_bf16 v[16:31], v[132:135], v[152:155], v[16:31]
	ds_read_b128 v[148:151], v205
	s_waitcnt lgkmcnt(7)
	v_mfma_f32_32x32x16_bf16 v[32:47], v[128:131], v[156:159], v[32:47]
	ds_read_b128 v[132:135], v205 offset:8192
	s_waitcnt lgkmcnt(6)
	v_mfma_f32_32x32x16_bf16 v[48:63], v[128:131], v[136:139], v[48:63]
	ds_read_b128 v[222:225], v204
	s_waitcnt lgkmcnt(5)
	v_mfma_f32_32x32x16_bf16 v[0:15], v[128:131], v[144:147], v[0:15]
	ds_read_b128 v[226:229], v204 offset:8192
	s_waitcnt lgkmcnt(4)
	v_mfma_f32_32x32x16_bf16 v[16:31], v[128:131], v[140:143], v[16:31]
	ds_read_b128 v[230:233], v195
	s_waitcnt lgkmcnt(4)
	v_mfma_f32_32x32x16_bf16 v[144:159], v[148:151], v[178:181], 0
	ds_read_b128 v[234:237], v195 offset:8192
	s_waitcnt lgkmcnt(4)
	v_mfma_f32_32x32x16_bf16 v[128:143], v[132:135], v[178:181], 0
	ds_read_b128 v[238:241], v199
	s_waitcnt lgkmcnt(4)
	v_mfma_f32_32x32x16_bf16 v[144:159], v[222:225], v[174:177], v[144:159]
	ds_read_b128 v[242:245], v199 offset:8192
	s_waitcnt lgkmcnt(4)
	v_mfma_f32_32x32x16_bf16 v[128:143], v[226:229], v[174:177], v[128:143]
	ds_read_b128 v[222:225], v200
	s_waitcnt lgkmcnt(4)
	v_mfma_f32_32x32x16_bf16 v[144:159], v[230:233], v[170:173], v[144:159]
	ds_read_b128 v[226:229], v200 offset:8192
	s_waitcnt lgkmcnt(4)
	v_mfma_f32_32x32x16_bf16 v[128:143], v[234:237], v[170:173], v[128:143]
	ds_read_b128 v[230:233], v201
	s_waitcnt lgkmcnt(4)
	v_mfma_f32_32x32x16_bf16 v[144:159], v[238:241], v[166:169], v[144:159]
	ds_read_b128 v[234:237], v201 offset:8192
	s_waitcnt lgkmcnt(4)
	v_mfma_f32_32x32x16_bf16 v[128:143], v[242:245], v[166:169], v[128:143]
	ds_read_b128 v[238:241], v202
	s_waitcnt lgkmcnt(4)
	v_mfma_f32_32x32x16_bf16 v[144:159], v[222:225], v[162:165], v[144:159]
	ds_read_b128 v[242:245], v202 offset:8192
	s_waitcnt lgkmcnt(4)
	v_mfma_f32_32x32x16_bf16 v[128:143], v[226:229], v[162:165], v[128:143]
	ds_read_b128 v[222:225], v203
	s_waitcnt lgkmcnt(4)
	v_mfma_f32_32x32x16_bf16 v[144:159], v[230:233], v[182:185], v[144:159]
	ds_read_b128 v[226:229], v203 offset:8192
	s_waitcnt lgkmcnt(4)
	v_mfma_f32_32x32x16_bf16 v[128:143], v[234:237], v[182:185], v[128:143]
	s_waitcnt lgkmcnt(3)
	v_mfma_f32_32x32x16_bf16 v[144:159], v[238:241], v[186:189], v[144:159]
	s_waitcnt lgkmcnt(2)
	v_mfma_f32_32x32x16_bf16 v[128:143], v[242:245], v[186:189], v[128:143]
	s_waitcnt lgkmcnt(1)
	v_mfma_f32_32x32x16_bf16 v[144:159], v[222:225], v[190:193], v[144:159]
	s_waitcnt lgkmcnt(0)
	v_mfma_f32_32x32x16_bf16 v[128:143], v[226:229], v[190:193], v[128:143]
	s_waitcnt vmcnt(0)
	s_barrier
	s_and_b64 vcc, exec, s[6:7]
	s_cbranch_vccnz .LBB0_555
	s_add_i32 s4, s12, 2
	s_cmp_ge_u32 s4, s10
	s_cbranch_scc1 .LBB0_553
	s_add_i32 s13, s11, 0x80
	s_cmp_lt_u32 s13, s29
	s_cselect_b64 s[4:5], -1, 0
	s_and_b64 s[14:15], s[4:5], exec
	s_cselect_b32 s14, s91, s43
	s_cselect_b32 s36, s90, s42
	s_and_b32 s37, s14, 0xffff
	s_and_b64 s[4:5], s[4:5], exec
	s_cselect_b32 s4, s28, s24
	s_lshl_b32 s5, s4, 1
	s_sub_i32 s14, s13, s29
	s_min_u32 s13, s13, s14
	v_mul_u32_u24_e32 v208, s5, v219
	v_or_b32_e32 v209, v208, v213
	s_mul_i32 s5, s13, s5
	s_mov_b32 s13, m0
	s_mov_b32 m0, s58
	s_nop 0
	buffer_load_dwordx4 v209, s[36:39], s5 offen lds
	s_mov_b32 m0, s13
	s_lshl_b32 s4, s4, 3
	v_bitop3_b32 v209, v208, 64, v213 bitop3:0x36
	s_add_i32 s5, s5, s4
	s_mov_b32 s13, m0
	s_mov_b32 m0, s84
	s_nop 0
	buffer_load_dwordx4 v209, s[36:39], s5 offen lds
	s_mov_b32 m0, s13
	v_bitop3_b32 v209, v208, s87, v213 bitop3:0x36
	s_add_i32 s5, s5, s4
	s_mov_b32 s13, m0
	s_mov_b32 m0, s79
	s_nop 0
	buffer_load_dwordx4 v209, s[36:39], s5 offen lds
	s_mov_b32 m0, s13
	v_bitop3_b32 v208, v208, s53, v213 bitop3:0x36
	s_add_i32 s5, s5, s4
	s_mov_b32 s4, m0
	s_mov_b32 m0, s80
	s_nop 0
	buffer_load_dwordx4 v208, s[36:39], s5 offen lds
	s_mov_b32 m0, s4
.LBB0_553:
	s_add_i32 s4, s12, 1
	s_cmp_ge_u32 s4, s10
	s_cbranch_scc1 .LBB0_555
	s_add_i32 s13, s11, 64
	s_cmp_lt_u32 s13, s29
	s_cselect_b64 s[4:5], -1, 0
	s_and_b64 s[14:15], s[4:5], exec
	s_cselect_b32 s14, s41, s95
	s_cselect_b32 s36, s40, s94
	s_and_b32 s37, s14, 0xffff
	s_and_b64 s[4:5], s[4:5], exec
	s_cselect_b32 s4, s28, s24
	s_lshl_b32 s5, s4, 1
	s_sub_i32 s14, s13, s29
	s_min_u32 s13, s13, s14
	v_mul_u32_u24_e32 v208, s5, v218
	v_or_b32_e32 v208, v208, v198
	s_mul_i32 s5, s13, s5
	s_mov_b32 s13, m0
	s_mov_b32 m0, s59
	s_nop 0
	buffer_load_dwordx4 v208, s[36:39], s5 offen lds
	s_mov_b32 m0, s13
	v_or_b32_e32 v209, 0x80, v208
	s_mov_b32 s13, m0
	s_mov_b32 m0, s88
	s_nop 0
	buffer_load_dwordx4 v209, s[36:39], s5 offen lds
	s_mov_b32 m0, s13
	s_lshl_b32 s4, s4, 4
	s_add_i32 s4, s5, s4
	s_mov_b32 s13, m0
	s_mov_b32 m0, s89
	s_nop 0
	buffer_load_dwordx4 v208, s[36:39], s4 offen lds
	s_mov_b32 m0, s13
	s_nop 0
	s_mov_b32 s13, m0
	s_mov_b32 m0, s44
	s_nop 0
	buffer_load_dwordx4 v209, s[36:39], s4 offen lds
	s_mov_b32 m0, s13
	v_or_b32_e32 v209, 0x100, v208
	s_mov_b32 s13, m0
	s_mov_b32 m0, s65
	s_nop 0
	buffer_load_dwordx4 v209, s[36:39], s5 offen lds
	s_mov_b32 m0, s13
	v_or_b32_e32 v208, 0x180, v208
	s_mov_b32 s13, m0
	s_mov_b32 m0, s33
	s_nop 0
	buffer_load_dwordx4 v208, s[36:39], s5 offen lds
	s_mov_b32 m0, s13
	s_mov_b32 s5, m0
	s_mov_b32 m0, s93
	s_nop 0
	buffer_load_dwordx4 v209, s[36:39], s4 offen lds
	s_mov_b32 m0, s5
	s_nop 0
	s_mov_b32 s5, m0
	s_mov_b32 m0, s16
	s_nop 0
	buffer_load_dwordx4 v208, s[36:39], s4 offen lds
	s_mov_b32 m0, s5

.LBB0_596:
	ds_read_b64_tr_b16 v[80:81], v129
	ds_read_b64_tr_b16 v[84:85], v129 offset:512
	ds_read_b64_tr_b16 v[88:89], v129 offset:1024
	ds_read_b64_tr_b16 v[92:93], v129 offset:1536
	ds_read_b64_tr_b16 v[82:83], v129 offset:2048
	ds_read_b64_tr_b16 v[86:87], v129 offset:2560
	ds_read_b64_tr_b16 v[90:91], v129 offset:3072
	ds_read_b64_tr_b16 v[94:95], v129 offset:3584
	ds_read_b64_tr_b16 v[148:149], v129 offset:4096
	ds_read_b64_tr_b16 v[150:151], v129 offset:6144
	s_waitcnt lgkmcnt(5)
	v_mfma_f32_32x32x16_bf16 v[32:47], v[76:79], v[80:83], v[32:47]
	ds_read_b64_tr_b16 v[152:153], v129 offset:4608
	ds_read_b64_tr_b16 v[154:155], v129 offset:6656
	s_waitcnt lgkmcnt(6)
	v_mfma_f32_32x32x16_bf16 v[48:63], v[76:79], v[84:87], v[48:63]
	ds_read_b64_tr_b16 v[80:81], v129 offset:5120
	ds_read_b64_tr_b16 v[82:83], v129 offset:7168
	s_waitcnt lgkmcnt(7)
	v_mfma_f32_32x32x16_bf16 v[0:15], v[76:79], v[88:91], v[0:15]
	ds_read_b64_tr_b16 v[84:85], v129 offset:5632
	ds_read_b64_tr_b16 v[86:87], v129 offset:7680
	s_waitcnt lgkmcnt(8)
	v_mfma_f32_32x32x16_bf16 v[16:31], v[76:79], v[92:95], v[16:31]
	ds_read_b64_tr_b16 v[88:89], v129 offset:8192
	ds_read_b64_tr_b16 v[90:91], v129 offset:10240
	s_waitcnt lgkmcnt(8)
	v_mfma_f32_32x32x16_bf16 v[32:47], v[72:75], v[148:151], v[32:47]
	ds_read_b64_tr_b16 v[76:77], v129 offset:8704
	ds_read_b64_tr_b16 v[78:79], v129 offset:10752
	s_waitcnt lgkmcnt(8)
	v_mfma_f32_32x32x16_bf16 v[48:63], v[72:75], v[152:155], v[48:63]
	ds_read_b64_tr_b16 v[92:93], v129 offset:9216
	ds_read_b64_tr_b16 v[94:95], v129 offset:11264
	s_waitcnt lgkmcnt(8)
	v_mfma_f32_32x32x16_bf16 v[0:15], v[72:75], v[80:83], v[0:15]
	ds_read_b64_tr_b16 v[148:149], v129 offset:9728
	ds_read_b64_tr_b16 v[150:151], v129 offset:11776
	s_waitcnt lgkmcnt(8)
	v_mfma_f32_32x32x16_bf16 v[16:31], v[72:75], v[84:87], v[16:31]
	ds_read_b64_tr_b16 v[80:81], v129 offset:12288
	ds_read_b64_tr_b16 v[82:83], v129 offset:14336
	s_waitcnt lgkmcnt(8)
	v_mfma_f32_32x32x16_bf16 v[32:47], v[68:71], v[88:91], v[32:47]
	ds_read_b64_tr_b16 v[72:73], v129 offset:12800
	ds_read_b64_tr_b16 v[74:75], v129 offset:14848
	s_waitcnt lgkmcnt(8)
	v_mfma_f32_32x32x16_bf16 v[48:63], v[68:71], v[76:79], v[48:63]
	ds_read_b64_tr_b16 v[84:85], v129 offset:13312
	ds_read_b64_tr_b16 v[86:87], v129 offset:15360
	s_waitcnt lgkmcnt(8)
	v_mfma_f32_32x32x16_bf16 v[0:15], v[68:71], v[92:95], v[0:15]
	ds_read_b64_tr_b16 v[76:77], v129 offset:13824
	ds_read_b64_tr_b16 v[78:79], v129 offset:15872
	s_waitcnt lgkmcnt(8)
	v_mfma_f32_32x32x16_bf16 v[16:31], v[68:71], v[148:151], v[16:31]
	ds_read_b128 v[88:91], v141 offset:16384
	s_waitcnt lgkmcnt(7)
	v_mfma_f32_32x32x16_bf16 v[32:47], v[64:67], v[80:83], v[32:47]
	ds_read_b128 v[68:71], v141 offset:24576
	s_waitcnt lgkmcnt(6)
	v_mfma_f32_32x32x16_bf16 v[48:63], v[64:67], v[72:75], v[48:63]
	ds_read_b128 v[148:151], v140 offset:16384
	s_waitcnt lgkmcnt(5)
	v_mfma_f32_32x32x16_bf16 v[0:15], v[64:67], v[84:87], v[0:15]
	ds_read_b128 v[152:155], v140 offset:24576
	s_waitcnt lgkmcnt(4)
	v_mfma_f32_32x32x16_bf16 v[16:31], v[64:67], v[76:79], v[16:31]
	ds_read_b128 v[156:159], v134 offset:16384
	s_waitcnt lgkmcnt(4)
	v_mfma_f32_32x32x16_bf16 v[80:95], v[88:91], v[112:115], 0
	ds_read_b128 v[162:165], v134 offset:24576
	s_waitcnt lgkmcnt(4)
	v_mfma_f32_32x32x16_bf16 v[64:79], v[68:71], v[112:115], 0
	ds_read_b128 v[166:169], v135 offset:16384
	s_waitcnt lgkmcnt(4)
	v_mfma_f32_32x32x16_bf16 v[80:95], v[148:151], v[108:111], v[80:95]
	ds_read_b128 v[170:173], v135 offset:24576
	s_waitcnt lgkmcnt(4)
	v_mfma_f32_32x32x16_bf16 v[64:79], v[152:155], v[108:111], v[64:79]
	ds_read_b128 v[148:151], v136 offset:16384
	s_waitcnt lgkmcnt(4)
	v_mfma_f32_32x32x16_bf16 v[80:95], v[156:159], v[104:107], v[80:95]
	ds_read_b128 v[152:155], v136 offset:24576
	s_waitcnt lgkmcnt(4)
	v_mfma_f32_32x32x16_bf16 v[64:79], v[162:165], v[104:107], v[64:79]
	ds_read_b128 v[156:159], v137 offset:16384
	s_waitcnt lgkmcnt(4)
	v_mfma_f32_32x32x16_bf16 v[80:95], v[166:169], v[100:103], v[80:95]
	ds_read_b128 v[162:165], v137 offset:24576
	s_waitcnt lgkmcnt(4)
	v_mfma_f32_32x32x16_bf16 v[64:79], v[170:173], v[100:103], v[64:79]
	ds_read_b128 v[166:169], v138 offset:16384
	s_waitcnt lgkmcnt(4)
	v_mfma_f32_32x32x16_bf16 v[80:95], v[148:151], v[96:99], v[80:95]
	ds_read_b128 v[170:173], v138 offset:24576
	s_waitcnt lgkmcnt(4)
	v_mfma_f32_32x32x16_bf16 v[64:79], v[152:155], v[96:99], v[64:79]
	ds_read_b128 v[148:151], v139 offset:16384
	s_waitcnt lgkmcnt(4)
	v_mfma_f32_32x32x16_bf16 v[80:95], v[156:159], v[116:119], v[80:95]
	ds_read_b128 v[152:155], v139 offset:24576
	s_waitcnt lgkmcnt(4)
	v_mfma_f32_32x32x16_bf16 v[64:79], v[162:165], v[116:119], v[64:79]
	s_waitcnt lgkmcnt(3)
	v_mfma_f32_32x32x16_bf16 v[80:95], v[166:169], v[120:123], v[80:95]
	s_waitcnt lgkmcnt(2)
	v_mfma_f32_32x32x16_bf16 v[64:79], v[170:173], v[120:123], v[64:79]
	s_waitcnt lgkmcnt(1)
	v_mfma_f32_32x32x16_bf16 v[80:95], v[148:151], v[124:127], v[80:95]
	s_waitcnt lgkmcnt(0)
	v_mfma_f32_32x32x16_bf16 v[64:79], v[152:155], v[124:127], v[64:79]
	s_waitcnt vmcnt(0)
	s_barrier
	s_and_b64 vcc, exec, s[6:7]
	s_cbranch_vccnz .LBB0_600
	s_add_i32 s4, s14, 1
	s_cmp_ge_u32 s4, s12
	s_cbranch_scc1 .LBB0_599
	s_add_i32 s15, s13, 64
	s_cmp_lt_u32 s15, s29
	s_cselect_b64 s[4:5], -1, 0
	s_and_b64 s[36:37], s[4:5], exec
	s_cselect_b32 s37, s91, s43
	s_cselect_b32 s36, s90, s42
	s_and_b32 s37, s37, 0xffff
	s_and_b64 s[4:5], s[4:5], exec
	s_cselect_b32 s4, s28, s24
	s_lshl_b32 s5, s4, 1
	s_sub_i32 s48, s15, s29
	s_min_u32 s15, s15, s48
	v_mul_u32_u24_e32 v147, s5, v144
	v_or_b32_e32 v148, v147, v143
	s_mul_i32 s5, s15, s5
	s_mov_b32 s15, m0
	s_mov_b32 m0, s85
	s_nop 0
	buffer_load_dwordx4 v148, s[36:39], s5 offen lds
	s_mov_b32 m0, s15
	s_lshl_b32 s4, s4, 3
	v_bitop3_b32 v148, v147, 64, v143 bitop3:0x36
	s_add_i32 s5, s5, s4
	s_mov_b32 s15, m0
	s_mov_b32 m0, s76
	s_nop 0
	buffer_load_dwordx4 v148, s[36:39], s5 offen lds
	s_mov_b32 m0, s15
	v_bitop3_b32 v148, v147, s87, v143 bitop3:0x36
	s_add_i32 s5, s5, s4
	s_mov_b32 s15, m0
	s_mov_b32 m0, s45
	s_nop 0
	buffer_load_dwordx4 v148, s[36:39], s5 offen lds
	s_mov_b32 m0, s15
	v_bitop3_b32 v147, v147, s53, v143 bitop3:0x36
	s_add_i32 s5, s5, s4
	s_mov_b32 s4, m0
	s_mov_b32 m0, s82
	s_nop 0
	buffer_load_dwordx4 v147, s[36:39], s5 offen lds
	s_mov_b32 m0, s4
.LBB0_599:
	s_cmp_lt_u32 s13, s29
	s_cselect_b64 s[4:5], -1, 0
	s_and_b64 s[36:37], s[4:5], exec
	s_cselect_b32 s15, s41, s95
	s_cselect_b32 s36, s40, s94
	s_and_b32 s37, s15, 0xffff
	s_and_b64 s[4:5], s[4:5], exec
	s_cselect_b32 s4, s28, s24
	s_lshl_b32 s5, s4, 1
	s_sub_i32 s15, s13, s29
	s_min_u32 s15, s13, s15
	v_mul_u32_u24_e32 v147, s5, v145
	v_or_b32_e32 v147, v147, v133
	s_mul_i32 s5, s15, s5
	s_mov_b32 s15, m0
	s_mov_b32 m0, s64
	s_nop 0
	buffer_load_dwordx4 v147, s[36:39], s5 offen lds
	s_mov_b32 m0, s15
	v_or_b32_e32 v148, 0x80, v147
	s_mov_b32 s15, m0
	s_mov_b32 m0, s77
	s_nop 0
	buffer_load_dwordx4 v148, s[36:39], s5 offen lds
	s_mov_b32 m0, s15
	s_lshl_b32 s4, s4, 4
	s_add_i32 s4, s5, s4
	s_mov_b32 s5, m0
	s_mov_b32 m0, s83
	s_nop 0
	buffer_load_dwordx4 v147, s[36:39], s4 offen lds
	s_mov_b32 m0, s5
	s_nop 0
	s_mov_b32 s5, m0
	s_mov_b32 m0, s81
	s_nop 0
	buffer_load_dwordx4 v148, s[36:39], s4 offen lds
	s_mov_b32 m0, s5

.LBB0_603:
	v_cvt_pk_bf16_f32 v64, v148, v149
	v_cvt_pk_bf16_f32 v65, v150, v151
	v_cvt_pk_bf16_f32 v66, v152, v153
	v_cvt_pk_bf16_f32 v67, v154, v155
	v_cvt_pk_bf16_f32 v68, v156, v157
	v_cvt_pk_bf16_f32 v69, v158, v159
	v_cvt_pk_bf16_f32 v70, v160, v162
	v_cvt_pk_bf16_f32 v71, v163, v164
	v_cvt_pk_bf16_f32 v72, v165, v166
	v_cvt_pk_bf16_f32 v73, v167, v168
	v_cvt_pk_bf16_f32 v74, v169, v170
	v_cvt_pk_bf16_f32 v75, v171, v172
	v_cvt_pk_bf16_f32 v76, v173, v174
	v_cvt_pk_bf16_f32 v77, v175, v176
	v_cvt_pk_bf16_f32 v78, v177, v178
	v_cvt_pk_bf16_f32 v79, v179, v180
	s_barrier
	ds_read_b64_tr_b16 v[80:81], v129 offset:32768
	ds_read_b64_tr_b16 v[84:85], v129 offset:33280
	ds_read_b64_tr_b16 v[88:89], v129 offset:33792
	ds_read_b64_tr_b16 v[92:93], v129 offset:34304
	ds_read_b64_tr_b16 v[82:83], v129 offset:34816
	ds_read_b64_tr_b16 v[86:87], v129 offset:35328
	ds_read_b64_tr_b16 v[90:91], v129 offset:35840
	ds_read_b64_tr_b16 v[94:95], v129 offset:36352
	ds_read_b64_tr_b16 v[148:149], v129 offset:36864
	ds_read_b64_tr_b16 v[150:151], v129 offset:38912
	s_waitcnt lgkmcnt(5)
	v_mfma_f32_32x32x16_bf16 v[32:47], v[64:67], v[80:83], v[32:47]
	ds_read_b64_tr_b16 v[152:153], v129 offset:37376
	ds_read_b64_tr_b16 v[154:155], v129 offset:39424
	s_waitcnt lgkmcnt(6)
	v_mfma_f32_32x32x16_bf16 v[48:63], v[64:67], v[84:87], v[48:63]
	ds_read_b64_tr_b16 v[80:81], v129 offset:37888
	ds_read_b64_tr_b16 v[82:83], v129 offset:39936
	s_waitcnt lgkmcnt(7)
	v_mfma_f32_32x32x16_bf16 v[0:15], v[64:67], v[88:91], v[0:15]
	ds_read_b64_tr_b16 v[84:85], v129 offset:38400
	ds_read_b64_tr_b16 v[86:87], v129 offset:40448
	s_waitcnt lgkmcnt(8)
	v_mfma_f32_32x32x16_bf16 v[16:31], v[64:67], v[92:95], v[16:31]
	ds_read_b64_tr_b16 v[88:89], v129 offset:40960
	ds_read_b64_tr_b16 v[90:91], v129 offset:43008
	s_waitcnt lgkmcnt(8)
	v_mfma_f32_32x32x16_bf16 v[32:47], v[68:71], v[148:151], v[32:47]
	ds_read_b64_tr_b16 v[64:65], v129 offset:41472
	ds_read_b64_tr_b16 v[66:67], v129 offset:43520
	s_waitcnt lgkmcnt(8)
	v_mfma_f32_32x32x16_bf16 v[48:63], v[68:71], v[152:155], v[48:63]
	ds_read_b64_tr_b16 v[92:93], v129 offset:41984
	ds_read_b64_tr_b16 v[94:95], v129 offset:44032
	s_waitcnt lgkmcnt(8)
	v_mfma_f32_32x32x16_bf16 v[0:15], v[68:71], v[80:83], v[0:15]
	ds_read_b64_tr_b16 v[148:149], v129 offset:42496
	ds_read_b64_tr_b16 v[150:151], v129 offset:44544
	s_waitcnt lgkmcnt(8)
	v_mfma_f32_32x32x16_bf16 v[16:31], v[68:71], v[84:87], v[16:31]
	ds_read_b64_tr_b16 v[80:81], v129 offset:45056
	ds_read_b64_tr_b16 v[82:83], v129 offset:47104
	s_waitcnt lgkmcnt(8)
	v_mfma_f32_32x32x16_bf16 v[32:47], v[72:75], v[88:91], v[32:47]
	ds_read_b64_tr_b16 v[68:69], v129 offset:45568
	ds_read_b64_tr_b16 v[70:71], v129 offset:47616
	s_waitcnt lgkmcnt(8)
	v_mfma_f32_32x32x16_bf16 v[48:63], v[72:75], v[64:67], v[48:63]
	ds_read_b64_tr_b16 v[84:85], v129 offset:46080
	ds_read_b64_tr_b16 v[86:87], v129 offset:48128
	s_waitcnt lgkmcnt(8)
	v_mfma_f32_32x32x16_bf16 v[0:15], v[72:75], v[92:95], v[0:15]
	ds_read_b64_tr_b16 v[64:65], v129 offset:46592
	ds_read_b64_tr_b16 v[66:67], v129 offset:48640
	s_waitcnt lgkmcnt(8)
	v_mfma_f32_32x32x16_bf16 v[16:31], v[72:75], v[148:151], v[16:31]
	ds_read_b128 v[88:91], v141
	s_waitcnt lgkmcnt(7)
	v_mfma_f32_32x32x16_bf16 v[32:47], v[76:79], v[80:83], v[32:47]
	ds_read_b128 v[72:75], v141 offset:8192
	s_waitcnt lgkmcnt(6)
	v_mfma_f32_32x32x16_bf16 v[48:63], v[76:79], v[68:71], v[48:63]
	ds_read_b128 v[148:151], v140
	s_waitcnt lgkmcnt(5)
	v_mfma_f32_32x32x16_bf16 v[0:15], v[76:79], v[84:87], v[0:15]
	ds_read_b128 v[152:155], v140 offset:8192
	s_waitcnt lgkmcnt(4)
	v_mfma_f32_32x32x16_bf16 v[16:31], v[76:79], v[64:67], v[16:31]
	ds_read_b128 v[156:159], v134
	s_waitcnt lgkmcnt(4)
	v_mfma_f32_32x32x16_bf16 v[80:95], v[88:91], v[112:115], 0
	ds_read_b128 v[162:165], v134 offset:8192
	s_waitcnt lgkmcnt(4)
	v_mfma_f32_32x32x16_bf16 v[64:79], v[72:75], v[112:115], 0
	ds_read_b128 v[166:169], v135
	s_waitcnt lgkmcnt(4)
	v_mfma_f32_32x32x16_bf16 v[80:95], v[148:151], v[108:111], v[80:95]
	ds_read_b128 v[170:173], v135 offset:8192
	s_waitcnt lgkmcnt(4)
	v_mfma_f32_32x32x16_bf16 v[64:79], v[152:155], v[108:111], v[64:79]
	ds_read_b128 v[148:151], v136
	s_waitcnt lgkmcnt(4)
	v_mfma_f32_32x32x16_bf16 v[80:95], v[156:159], v[104:107], v[80:95]
	ds_read_b128 v[152:155], v136 offset:8192
	s_waitcnt lgkmcnt(4)
	v_mfma_f32_32x32x16_bf16 v[64:79], v[162:165], v[104:107], v[64:79]
	ds_read_b128 v[156:159], v137
	s_waitcnt lgkmcnt(4)
	v_mfma_f32_32x32x16_bf16 v[80:95], v[166:169], v[100:103], v[80:95]
	ds_read_b128 v[162:165], v137 offset:8192
	s_waitcnt lgkmcnt(4)
	v_mfma_f32_32x32x16_bf16 v[64:79], v[170:173], v[100:103], v[64:79]
	ds_read_b128 v[166:169], v138
	s_waitcnt lgkmcnt(4)
	v_mfma_f32_32x32x16_bf16 v[80:95], v[148:151], v[96:99], v[80:95]
	ds_read_b128 v[170:173], v138 offset:8192
	s_waitcnt lgkmcnt(4)
	v_mfma_f32_32x32x16_bf16 v[64:79], v[152:155], v[96:99], v[64:79]
	ds_read_b128 v[148:151], v139
	s_waitcnt lgkmcnt(4)
	v_mfma_f32_32x32x16_bf16 v[80:95], v[156:159], v[116:119], v[80:95]
	ds_read_b128 v[152:155], v139 offset:8192
	s_waitcnt lgkmcnt(4)
	v_mfma_f32_32x32x16_bf16 v[64:79], v[162:165], v[116:119], v[64:79]
	s_waitcnt lgkmcnt(3)
	v_mfma_f32_32x32x16_bf16 v[80:95], v[166:169], v[120:123], v[80:95]
	s_waitcnt lgkmcnt(2)
	v_mfma_f32_32x32x16_bf16 v[64:79], v[170:173], v[120:123], v[64:79]
	s_waitcnt lgkmcnt(1)
	v_mfma_f32_32x32x16_bf16 v[80:95], v[148:151], v[124:127], v[80:95]
	s_waitcnt lgkmcnt(0)
	v_mfma_f32_32x32x16_bf16 v[64:79], v[152:155], v[124:127], v[64:79]
	s_waitcnt vmcnt(0)
	s_barrier
	s_and_b64 vcc, exec, s[6:7]
	s_cbranch_vccnz .LBB0_608
	s_add_i32 s4, s14, 2
	s_cmp_ge_u32 s4, s12
	s_cbranch_scc1 .LBB0_606
	s_add_i32 s15, s13, 0x80
	s_cmp_lt_u32 s15, s29
	s_cselect_b64 s[4:5], -1, 0
	s_and_b64 s[36:37], s[4:5], exec
	s_cselect_b32 s37, s91, s43
	s_cselect_b32 s36, s90, s42
	s_and_b32 s37, s37, 0xffff
	s_and_b64 s[4:5], s[4:5], exec
	s_cselect_b32 s4, s28, s24
	s_lshl_b32 s5, s4, 1
	s_sub_i32 s48, s15, s29
	s_min_u32 s15, s15, s48
	v_mul_u32_u24_e32 v146, s5, v144
	v_or_b32_e32 v148, v146, v143
	s_mul_i32 s5, s15, s5
	s_mov_b32 s15, m0
	s_mov_b32 m0, s58
	s_nop 0
	buffer_load_dwordx4 v148, s[36:39], s5 offen lds
	s_mov_b32 m0, s15
	s_lshl_b32 s4, s4, 3
	v_bitop3_b32 v148, v146, 64, v143 bitop3:0x36
	s_add_i32 s5, s5, s4
	s_mov_b32 s15, m0
	s_mov_b32 m0, s84
	s_nop 0
	buffer_load_dwordx4 v148, s[36:39], s5 offen lds
	s_mov_b32 m0, s15
	v_bitop3_b32 v148, v146, s87, v143 bitop3:0x36
	s_add_i32 s5, s5, s4
	s_mov_b32 s15, m0
	s_mov_b32 m0, s79
	s_nop 0
	buffer_load_dwordx4 v148, s[36:39], s5 offen lds
	s_mov_b32 m0, s15
	v_bitop3_b32 v146, v146, s53, v143 bitop3:0x36
	s_add_i32 s5, s5, s4
	s_mov_b32 s4, m0
	s_mov_b32 m0, s80
	s_nop 0
	buffer_load_dwordx4 v146, s[36:39], s5 offen lds
	s_mov_b32 m0, s4
.LBB0_606:
	s_add_i32 s4, s14, 1
	s_cmp_ge_u32 s4, s12
	s_cbranch_scc1 .LBB0_608
	s_add_i32 s15, s13, 64
	s_cmp_lt_u32 s15, s29
	s_cselect_b64 s[4:5], -1, 0
	s_and_b64 s[36:37], s[4:5], exec
	s_cselect_b32 s37, s41, s95
	s_cselect_b32 s36, s40, s94
	s_and_b32 s37, s37, 0xffff
	s_and_b64 s[4:5], s[4:5], exec
	s_cselect_b32 s4, s28, s24
	s_lshl_b32 s5, s4, 1
	s_sub_i32 s48, s15, s29
	s_min_u32 s15, s15, s48
	v_mul_u32_u24_e32 v146, s5, v145
	v_or_b32_e32 v146, v146, v133
	s_mul_i32 s5, s15, s5
	s_mov_b32 s15, m0
	s_mov_b32 m0, s59
	s_nop 0
	buffer_load_dwordx4 v146, s[36:39], s5 offen lds
	s_mov_b32 m0, s15
	v_or_b32_e32 v148, 0x80, v146
	s_mov_b32 s15, m0
	s_mov_b32 m0, s88
	s_nop 0
	buffer_load_dwordx4 v148, s[36:39], s5 offen lds
	s_mov_b32 m0, s15
	s_lshl_b32 s4, s4, 4
	s_add_i32 s4, s5, s4
	s_mov_b32 s5, m0
	s_mov_b32 m0, s89
	s_nop 0
	buffer_load_dwordx4 v146, s[36:39], s4 offen lds
	s_mov_b32 m0, s5
	s_nop 0
	s_mov_b32 s5, m0
	s_mov_b32 m0, s44
	s_nop 0
	buffer_load_dwordx4 v148, s[36:39], s4 offen lds
	s_mov_b32 m0, s5

.LBB0_785:
	s_add_i32 s0, s20, 0xffffff00
	s_cmpk_lt_i32 s20, 0x100
	s_cselect_b32 s0, s20, s0
	s_cselect_b32 s24, 64, 4
	s_and_b32 s1, s0, 7
	s_lshl_b32 s1, s1, 1
	s_bfe_u32 s6, s0, 0x10003
	s_or_b32 s1, s1, s6
	s_andn2_b32 s0, s0, 15
	s_or_b32 s0, s0, s1
	s_ashr_i32 s6, s0, 5
	s_lshl_b32 s1, s6, 12
	s_addk_i32 s1, 0x1000
	s_lshl_b32 s7, s6, 8
	s_cmpk_lt_i32 s20, 0x100
	s_cselect_b32 s23, s1, s7
	s_cmpk_gt_i32 s20, 0xff
	s_cselect_b64 s[8:9], -1, 0
	s_bfe_u32 s21, s0, 0x30002
	s_bfe_u32 s22, s0, 0x10001
	s_and_b32 s7, s0, 1
	s_mov_b64 s[0:1], -1
	s_and_b64 vcc, exec, s[2:3]
	s_cbranch_vccz .LBB0_813
	v_readlane_b32 s12, v252, 20
	v_readlane_b32 s13, v252, 21
	s_ashr_i32 s25, s23, 6
	s_lshl_b32 s16, s21, 1
	s_or_b32 s27, s16, s22
	s_lshl_b32 s26, s7, 13
	v_lshlrev_b32_e32 v197, 4, v219
	v_lshlrev_b32_e32 v198, 2, v218
	s_waitcnt vmcnt(0) lgkmcnt(0)
	s_barrier
	s_mov_b32 s29, 0
	s_sub_i32 s14, s24, 1
	s_sub_i32 s14, s14, s29
	s_cmp_eq_u32 s22, 0
	s_cselect_b32 s14, s29, s14
	s_add_i32 s14, s14, s25
	s_lshl_b32 s14, s14, 4
	s_or_b32 s14, s14, s27
	s_mul_hi_u32 s15, s14, 0x12100
	s_mul_i32 s14, s14, 0x12100
	s_add_u32 s10, s12, s14
	s_addc_u32 s11, s13, s15
	s_add_u32 s16, s10, 0x12000
	s_addc_u32 s17, s11, 0
	global_load_dwordx4 v[0:3], v197, s[10:11]
	s_add_u32 s10, s10, 0x1000
	s_addc_u32 s11, s11, 0
	global_load_dwordx4 v[4:7], v197, s[10:11]
	s_add_u32 s10, s10, 0x1000
	s_addc_u32 s11, s11, 0
	global_load_dwordx4 v[8:11], v197, s[10:11]
	s_add_u32 s10, s10, 0x1000
	s_addc_u32 s11, s11, 0
	global_load_dwordx4 v[12:15], v197, s[10:11]
	s_add_u32 s10, s10, 0x1000
	s_addc_u32 s11, s11, 0
	global_load_dwordx4 v[16:19], v197, s[10:11]
	s_add_u32 s10, s10, 0x1000
	s_addc_u32 s11, s11, 0
	global_load_dwordx4 v[20:23], v197, s[10:11]
	s_add_u32 s10, s10, 0x1000
	s_addc_u32 s11, s11, 0
	global_load_dwordx4 v[24:27], v197, s[10:11]
	s_add_u32 s10, s10, 0x1000
	s_addc_u32 s11, s11, 0
	global_load_dwordx4 v[28:31], v197, s[10:11]
	s_add_u32 s10, s10, 0x1000
	s_addc_u32 s11, s11, 0
	global_load_dwordx4 v[32:35], v197, s[10:11]
	s_add_u32 s10, s10, 0x1000
	s_addc_u32 s11, s11, 0
	global_load_dwordx4 v[36:39], v197, s[10:11]
	s_add_u32 s10, s10, 0x1000
	s_addc_u32 s11, s11, 0
	global_load_dwordx4 v[40:43], v197, s[10:11]
	s_add_u32 s10, s10, 0x1000
	s_addc_u32 s11, s11, 0
	global_load_dwordx4 v[44:47], v197, s[10:11]
	s_add_u32 s10, s10, 0x1000
	s_addc_u32 s11, s11, 0
	global_load_dwordx4 v[48:51], v197, s[10:11]
	s_add_u32 s10, s10, 0x1000
	s_addc_u32 s11, s11, 0
	global_load_dwordx4 v[52:55], v197, s[10:11]
	s_add_u32 s10, s10, 0x1000
	s_addc_u32 s11, s11, 0
	s_add_u32 s10, s10, s26
	s_addc_u32 s11, s11, 0
	global_load_dwordx4 v[56:59], v197, s[10:11]
	s_add_u32 s10, s10, 0x1000
	s_addc_u32 s11, s11, 0
	global_load_dwordx4 v[60:63], v197, s[10:11]
	global_load_dword v194, v198, s[16:17]
	s_mov_b32 s29, 1
	s_sub_i32 s14, s24, 1
	s_sub_i32 s14, s14, s29
	s_cmp_eq_u32 s22, 0
	s_cselect_b32 s14, s29, s14
	s_add_i32 s14, s14, s25
	s_lshl_b32 s14, s14, 4
	s_or_b32 s14, s14, s27
	s_mul_hi_u32 s15, s14, 0x12100
	s_mul_i32 s14, s14, 0x12100
	s_add_u32 s10, s12, s14
	s_addc_u32 s11, s13, s15
	s_add_u32 s16, s10, 0x12000
	s_addc_u32 s17, s11, 0
	global_load_dwordx4 v[64:67], v197, s[10:11]
	s_add_u32 s10, s10, 0x1000
	s_addc_u32 s11, s11, 0
	global_load_dwordx4 v[68:71], v197, s[10:11]
	s_add_u32 s10, s10, 0x1000
	s_addc_u32 s11, s11, 0
	global_load_dwordx4 v[72:75], v197, s[10:11]
	s_add_u32 s10, s10, 0x1000
	s_addc_u32 s11, s11, 0
	global_load_dwordx4 v[76:79], v197, s[10:11]
	s_add_u32 s10, s10, 0x1000
	s_addc_u32 s11, s11, 0
	global_load_dwordx4 v[80:83], v197, s[10:11]
	s_add_u32 s10, s10, 0x1000
	s_addc_u32 s11, s11, 0
	global_load_dwordx4 v[84:87], v197, s[10:11]
	s_add_u32 s10, s10, 0x1000
	s_addc_u32 s11, s11, 0
	global_load_dwordx4 v[88:91], v197, s[10:11]
	s_add_u32 s10, s10, 0x1000
	s_addc_u32 s11, s11, 0
	global_load_dwordx4 v[92:95], v197, s[10:11]
	s_add_u32 s10, s10, 0x1000
	s_addc_u32 s11, s11, 0
	global_load_dwordx4 v[96:99], v197, s[10:11]
	s_add_u32 s10, s10, 0x1000
	s_addc_u32 s11, s11, 0
	global_load_dwordx4 v[100:103], v197, s[10:11]
	s_add_u32 s10, s10, 0x1000
	s_addc_u32 s11, s11, 0
	global_load_dwordx4 v[104:107], v197, s[10:11]
	s_add_u32 s10, s10, 0x1000
	s_addc_u32 s11, s11, 0
	global_load_dwordx4 v[108:111], v197, s[10:11]
	s_add_u32 s10, s10, 0x1000
	s_addc_u32 s11, s11, 0
	global_load_dwordx4 v[112:115], v197, s[10:11]
	s_add_u32 s10, s10, 0x1000
	s_addc_u32 s11, s11, 0
	global_load_dwordx4 v[116:119], v197, s[10:11]
	s_add_u32 s10, s10, 0x1000
	s_addc_u32 s11, s11, 0
	s_add_u32 s10, s10, s26
	s_addc_u32 s11, s11, 0
	global_load_dwordx4 v[120:123], v197, s[10:11]
	s_add_u32 s10, s10, 0x1000
	s_addc_u32 s11, s11, 0
	global_load_dwordx4 v[124:127], v197, s[10:11]
	global_load_dword v195, v198, s[16:17]
	s_mov_b32 s29, 2
	s_sub_i32 s14, s24, 1
	s_sub_i32 s14, s14, s29
	s_cmp_eq_u32 s22, 0
	s_cselect_b32 s14, s29, s14
	s_add_i32 s14, s14, s25
	s_lshl_b32 s14, s14, 4
	s_or_b32 s14, s14, s27
	s_mul_hi_u32 s15, s14, 0x12100
	s_mul_i32 s14, s14, 0x12100
	s_add_u32 s10, s12, s14
	s_addc_u32 s11, s13, s15
	s_add_u32 s16, s10, 0x12000
	s_addc_u32 s17, s11, 0
	global_load_dwordx4 v[128:131], v197, s[10:11]
	s_add_u32 s10, s10, 0x1000
	s_addc_u32 s11, s11, 0
	global_load_dwordx4 v[132:135], v197, s[10:11]
	s_add_u32 s10, s10, 0x1000
	s_addc_u32 s11, s11, 0
	global_load_dwordx4 v[136:139], v197, s[10:11]
	s_add_u32 s10, s10, 0x1000
	s_addc_u32 s11, s11, 0
	global_load_dwordx4 v[140:143], v197, s[10:11]
	s_add_u32 s10, s10, 0x1000
	s_addc_u32 s11, s11, 0
	global_load_dwordx4 v[144:147], v197, s[10:11]
	s_add_u32 s10, s10, 0x1000
	s_addc_u32 s11, s11, 0
	global_load_dwordx4 v[148:151], v197, s[10:11]
	s_add_u32 s10, s10, 0x1000
	s_addc_u32 s11, s11, 0
	global_load_dwordx4 v[152:155], v197, s[10:11]
	s_add_u32 s10, s10, 0x1000
	s_addc_u32 s11, s11, 0
	global_load_dwordx4 v[156:159], v197, s[10:11]
	s_add_u32 s10, s10, 0x1000
	s_addc_u32 s11, s11, 0
	global_load_dwordx4 v[162:165], v197, s[10:11]
	s_add_u32 s10, s10, 0x1000
	s_addc_u32 s11, s11, 0
	global_load_dwordx4 v[166:169], v197, s[10:11]
	s_add_u32 s10, s10, 0x1000
	s_addc_u32 s11, s11, 0
	global_load_dwordx4 v[170:173], v197, s[10:11]
	s_add_u32 s10, s10, 0x1000
	s_addc_u32 s11, s11, 0
	global_load_dwordx4 v[174:177], v197, s[10:11]
	s_add_u32 s10, s10, 0x1000
	s_addc_u32 s11, s11, 0
	global_load_dwordx4 v[178:181], v197, s[10:11]
	s_add_u32 s10, s10, 0x1000
	s_addc_u32 s11, s11, 0
	global_load_dwordx4 v[182:185], v197, s[10:11]
	s_add_u32 s10, s10, 0x1000
	s_addc_u32 s11, s11, 0
	s_add_u32 s10, s10, s26
	s_addc_u32 s11, s11, 0
	global_load_dwordx4 v[186:189], v197, s[10:11]
	s_add_u32 s10, s10, 0x1000
	s_addc_u32 s11, s11, 0
	global_load_dwordx4 v[190:193], v197, s[10:11]
	global_load_dword v196, v198, s[16:17]
	s_waitcnt vmcnt(34)
	s_mov_b32 s30, 0
	v_add_u32_e32 v199, s30, v197
	s_add_i32 s31, s30, 0x10000
	v_add_u32_e32 v200, s31, v198
	ds_write_b128 v199, v[0:3]
	ds_write_b128 v199, v[4:7] offset:4096
	ds_write_b128 v199, v[8:11] offset:8192
	ds_write_b128 v199, v[12:15] offset:12288
	ds_write_b128 v199, v[16:19] offset:16384
	ds_write_b128 v199, v[20:23] offset:20480
	ds_write_b128 v199, v[24:27] offset:24576
	ds_write_b128 v199, v[28:31] offset:28672
	ds_write_b128 v199, v[32:35] offset:32768
	ds_write_b128 v199, v[36:39] offset:36864
	ds_write_b128 v199, v[40:43] offset:40960
	ds_write_b128 v199, v[44:47] offset:45056
	ds_write_b128 v199, v[48:51] offset:49152
	ds_write_b128 v199, v[52:55] offset:53248
	ds_write_b128 v199, v[56:59] offset:57344
	ds_write_b128 v199, v[60:63] offset:61440
	ds_write_b32 v200, v194
	s_waitcnt lgkmcnt(0)
	s_barrier
	s_mov_b32 s28, 0
.Lscan_ld_step0:
	s_add_i32 s29, s28, 3
	s_cmp_lt_u32 s29, s24
	s_cbranch_scc0 .Lscan_ld_noload0
	s_sub_i32 s14, s24, 1
	s_sub_i32 s14, s14, s29
	s_cmp_eq_u32 s22, 0
	s_cselect_b32 s14, s29, s14
	s_add_i32 s14, s14, s25
	s_lshl_b32 s14, s14, 4
	s_or_b32 s14, s14, s27
	s_mul_hi_u32 s15, s14, 0x12100
	s_mul_i32 s14, s14, 0x12100
	s_add_u32 s10, s12, s14
	s_addc_u32 s11, s13, s15
	s_add_u32 s16, s10, 0x12000
	s_addc_u32 s17, s11, 0
	global_load_dwordx4 v[0:3], v197, s[10:11]
	s_add_u32 s10, s10, 0x1000
	s_addc_u32 s11, s11, 0
	global_load_dwordx4 v[4:7], v197, s[10:11]
	s_add_u32 s10, s10, 0x1000
	s_addc_u32 s11, s11, 0
	global_load_dwordx4 v[8:11], v197, s[10:11]
	s_add_u32 s10, s10, 0x1000
	s_addc_u32 s11, s11, 0
	global_load_dwordx4 v[12:15], v197, s[10:11]
	s_add_u32 s10, s10, 0x1000
	s_addc_u32 s11, s11, 0
	global_load_dwordx4 v[16:19], v197, s[10:11]
	s_add_u32 s10, s10, 0x1000
	s_addc_u32 s11, s11, 0
	global_load_dwordx4 v[20:23], v197, s[10:11]
	s_add_u32 s10, s10, 0x1000
	s_addc_u32 s11, s11, 0
	global_load_dwordx4 v[24:27], v197, s[10:11]
	s_add_u32 s10, s10, 0x1000
	s_addc_u32 s11, s11, 0
	global_load_dwordx4 v[28:31], v197, s[10:11]
	s_add_u32 s10, s10, 0x1000
	s_addc_u32 s11, s11, 0
	global_load_dwordx4 v[32:35], v197, s[10:11]
	s_add_u32 s10, s10, 0x1000
	s_addc_u32 s11, s11, 0
	global_load_dwordx4 v[36:39], v197, s[10:11]
	s_add_u32 s10, s10, 0x1000
	s_addc_u32 s11, s11, 0
	global_load_dwordx4 v[40:43], v197, s[10:11]
	s_add_u32 s10, s10, 0x1000
	s_addc_u32 s11, s11, 0
	global_load_dwordx4 v[44:47], v197, s[10:11]
	s_add_u32 s10, s10, 0x1000
	s_addc_u32 s11, s11, 0
	global_load_dwordx4 v[48:51], v197, s[10:11]
	s_add_u32 s10, s10, 0x1000
	s_addc_u32 s11, s11, 0
	global_load_dwordx4 v[52:55], v197, s[10:11]
	s_add_u32 s10, s10, 0x1000
	s_addc_u32 s11, s11, 0
	s_add_u32 s10, s10, s26
	s_addc_u32 s11, s11, 0
	global_load_dwordx4 v[56:59], v197, s[10:11]
	s_add_u32 s10, s10, 0x1000
	s_addc_u32 s11, s11, 0
	global_load_dwordx4 v[60:63], v197, s[10:11]
	global_load_dword v194, v198, s[16:17]
	s_waitcnt vmcnt(34)
	s_branch .Lscan_ld_store0
.Lscan_ld_noload0:
	s_add_i32 s29, s28, 2
	s_cmp_lt_u32 s29, s24
	s_cbranch_scc0 .Lscan_ld_drain0
	s_waitcnt vmcnt(17)
	s_branch .Lscan_ld_store0

.Lscan_ld_store0:
	s_add_i32 s29, s28, 1
	s_cmp_lt_u32 s29, s24
	s_cbranch_scc0 .Lscan_ld_bar0
	s_bitcmp1_b32 s29, 0
	s_cselect_b32 s30, 0x10100, 0
	v_add_u32_e32 v199, s30, v197
	s_add_i32 s31, s30, 0x10000
	v_add_u32_e32 v200, s31, v198
	ds_write_b128 v199, v[64:67]
	ds_write_b128 v199, v[68:71] offset:4096
	ds_write_b128 v199, v[72:75] offset:8192
	ds_write_b128 v199, v[76:79] offset:12288
	ds_write_b128 v199, v[80:83] offset:16384
	ds_write_b128 v199, v[84:87] offset:20480
	ds_write_b128 v199, v[88:91] offset:24576
	ds_write_b128 v199, v[92:95] offset:28672
	ds_write_b128 v199, v[96:99] offset:32768
	ds_write_b128 v199, v[100:103] offset:36864
	ds_write_b128 v199, v[104:107] offset:40960
	ds_write_b128 v199, v[108:111] offset:45056
	ds_write_b128 v199, v[112:115] offset:49152
	ds_write_b128 v199, v[116:119] offset:53248
	ds_write_b128 v199, v[120:123] offset:57344
	ds_write_b128 v199, v[124:127] offset:61440
	ds_write_b32 v200, v195
.Lscan_ld_bar0:
	s_waitcnt lgkmcnt(0)
	s_barrier
	s_add_i32 s28, s28, 1
	s_cmp_lt_u32 s28, s24
	s_cbranch_scc0 .Lscan_ld_done
.Lscan_ld_step1:
	s_add_i32 s29, s28, 3
	s_cmp_lt_u32 s29, s24
	s_cbranch_scc0 .Lscan_ld_noload1
	s_sub_i32 s14, s24, 1
	s_sub_i32 s14, s14, s29
	s_cmp_eq_u32 s22, 0
	s_cselect_b32 s14, s29, s14
	s_add_i32 s14, s14, s25
	s_lshl_b32 s14, s14, 4
	s_or_b32 s14, s14, s27
	s_mul_hi_u32 s15, s14, 0x12100
	s_mul_i32 s14, s14, 0x12100
	s_add_u32 s10, s12, s14
	s_addc_u32 s11, s13, s15
	s_add_u32 s16, s10, 0x12000
	s_addc_u32 s17, s11, 0
	global_load_dwordx4 v[64:67], v197, s[10:11]
	s_add_u32 s10, s10, 0x1000
	s_addc_u32 s11, s11, 0
	global_load_dwordx4 v[68:71], v197, s[10:11]
	s_add_u32 s10, s10, 0x1000
	s_addc_u32 s11, s11, 0
	global_load_dwordx4 v[72:75], v197, s[10:11]
	s_add_u32 s10, s10, 0x1000
	s_addc_u32 s11, s11, 0
	global_load_dwordx4 v[76:79], v197, s[10:11]
	s_add_u32 s10, s10, 0x1000
	s_addc_u32 s11, s11, 0
	global_load_dwordx4 v[80:83], v197, s[10:11]
	s_add_u32 s10, s10, 0x1000
	s_addc_u32 s11, s11, 0
	global_load_dwordx4 v[84:87], v197, s[10:11]
	s_add_u32 s10, s10, 0x1000
	s_addc_u32 s11, s11, 0
	global_load_dwordx4 v[88:91], v197, s[10:11]
	s_add_u32 s10, s10, 0x1000
	s_addc_u32 s11, s11, 0
	global_load_dwordx4 v[92:95], v197, s[10:11]
	s_add_u32 s10, s10, 0x1000
	s_addc_u32 s11, s11, 0
	global_load_dwordx4 v[96:99], v197, s[10:11]
	s_add_u32 s10, s10, 0x1000
	s_addc_u32 s11, s11, 0
	global_load_dwordx4 v[100:103], v197, s[10:11]
	s_add_u32 s10, s10, 0x1000
	s_addc_u32 s11, s11, 0
	global_load_dwordx4 v[104:107], v197, s[10:11]
	s_add_u32 s10, s10, 0x1000
	s_addc_u32 s11, s11, 0
	global_load_dwordx4 v[108:111], v197, s[10:11]
	s_add_u32 s10, s10, 0x1000
	s_addc_u32 s11, s11, 0
	global_load_dwordx4 v[112:115], v197, s[10:11]
	s_add_u32 s10, s10, 0x1000
	s_addc_u32 s11, s11, 0
	global_load_dwordx4 v[116:119], v197, s[10:11]
	s_add_u32 s10, s10, 0x1000
	s_addc_u32 s11, s11, 0
	s_add_u32 s10, s10, s26
	s_addc_u32 s11, s11, 0
	global_load_dwordx4 v[120:123], v197, s[10:11]
	s_add_u32 s10, s10, 0x1000
	s_addc_u32 s11, s11, 0
	global_load_dwordx4 v[124:127], v197, s[10:11]
	global_load_dword v195, v198, s[16:17]
	s_waitcnt vmcnt(34)
	s_branch .Lscan_ld_store1

.Lscan_ld_store1:
	s_add_i32 s29, s28, 1
	s_cmp_lt_u32 s29, s24
	s_cbranch_scc0 .Lscan_ld_bar1
	s_bitcmp1_b32 s29, 0
	s_cselect_b32 s30, 0x10100, 0
	v_add_u32_e32 v199, s30, v197
	s_add_i32 s31, s30, 0x10000
	v_add_u32_e32 v200, s31, v198
	ds_write_b128 v199, v[128:131]
	ds_write_b128 v199, v[132:135] offset:4096
	ds_write_b128 v199, v[136:139] offset:8192
	ds_write_b128 v199, v[140:143] offset:12288
	ds_write_b128 v199, v[144:147] offset:16384
	ds_write_b128 v199, v[148:151] offset:20480
	ds_write_b128 v199, v[152:155] offset:24576
	ds_write_b128 v199, v[156:159] offset:28672
	ds_write_b128 v199, v[162:165] offset:32768
	ds_write_b128 v199, v[166:169] offset:36864
	ds_write_b128 v199, v[170:173] offset:40960
	ds_write_b128 v199, v[174:177] offset:45056
	ds_write_b128 v199, v[178:181] offset:49152
	ds_write_b128 v199, v[182:185] offset:53248
	ds_write_b128 v199, v[186:189] offset:57344
	ds_write_b128 v199, v[190:193] offset:61440
	ds_write_b32 v200, v196

.Lscan_ld_step2:
	s_add_i32 s29, s28, 3
	s_cmp_lt_u32 s29, s24
	s_cbranch_scc0 .Lscan_ld_noload2
	s_sub_i32 s14, s24, 1
	s_sub_i32 s14, s14, s29
	s_cmp_eq_u32 s22, 0
	s_cselect_b32 s14, s29, s14
	s_add_i32 s14, s14, s25
	s_lshl_b32 s14, s14, 4
	s_or_b32 s14, s14, s27
	s_mul_hi_u32 s15, s14, 0x12100
	s_mul_i32 s14, s14, 0x12100
	s_add_u32 s10, s12, s14
	s_addc_u32 s11, s13, s15
	s_add_u32 s16, s10, 0x12000
	s_addc_u32 s17, s11, 0
	global_load_dwordx4 v[128:131], v197, s[10:11]
	s_add_u32 s10, s10, 0x1000
	s_addc_u32 s11, s11, 0
	global_load_dwordx4 v[132:135], v197, s[10:11]
	s_add_u32 s10, s10, 0x1000
	s_addc_u32 s11, s11, 0
	global_load_dwordx4 v[136:139], v197, s[10:11]
	s_add_u32 s10, s10, 0x1000
	s_addc_u32 s11, s11, 0
	global_load_dwordx4 v[140:143], v197, s[10:11]
	s_add_u32 s10, s10, 0x1000
	s_addc_u32 s11, s11, 0
	global_load_dwordx4 v[144:147], v197, s[10:11]
	s_add_u32 s10, s10, 0x1000
	s_addc_u32 s11, s11, 0
	global_load_dwordx4 v[148:151], v197, s[10:11]
	s_add_u32 s10, s10, 0x1000
	s_addc_u32 s11, s11, 0
	global_load_dwordx4 v[152:155], v197, s[10:11]
	s_add_u32 s10, s10, 0x1000
	s_addc_u32 s11, s11, 0
	global_load_dwordx4 v[156:159], v197, s[10:11]
	s_add_u32 s10, s10, 0x1000
	s_addc_u32 s11, s11, 0
	global_load_dwordx4 v[162:165], v197, s[10:11]
	s_add_u32 s10, s10, 0x1000
	s_addc_u32 s11, s11, 0
	global_load_dwordx4 v[166:169], v197, s[10:11]
	s_add_u32 s10, s10, 0x1000
	s_addc_u32 s11, s11, 0
	global_load_dwordx4 v[170:173], v197, s[10:11]
	s_add_u32 s10, s10, 0x1000
	s_addc_u32 s11, s11, 0
	global_load_dwordx4 v[174:177], v197, s[10:11]
	s_add_u32 s10, s10, 0x1000
	s_addc_u32 s11, s11, 0
	global_load_dwordx4 v[178:181], v197, s[10:11]
	s_add_u32 s10, s10, 0x1000
	s_addc_u32 s11, s11, 0
	global_load_dwordx4 v[182:185], v197, s[10:11]
	s_add_u32 s10, s10, 0x1000
	s_addc_u32 s11, s11, 0
	s_add_u32 s10, s10, s26
	s_addc_u32 s11, s11, 0
	global_load_dwordx4 v[186:189], v197, s[10:11]
	s_add_u32 s10, s10, 0x1000
	s_addc_u32 s11, s11, 0
	global_load_dwordx4 v[190:193], v197, s[10:11]
	global_load_dword v196, v198, s[16:17]
	s_waitcnt vmcnt(34)
	s_branch .Lscan_ld_store2

.Lscan_ld_store2:
	s_add_i32 s29, s28, 1
	s_cmp_lt_u32 s29, s24
	s_cbranch_scc0 .Lscan_ld_bar2
	s_bitcmp1_b32 s29, 0
	s_cselect_b32 s30, 0x10100, 0
	v_add_u32_e32 v199, s30, v197
	s_add_i32 s31, s30, 0x10000
	v_add_u32_e32 v200, s31, v198
	ds_write_b128 v199, v[0:3]
	ds_write_b128 v199, v[4:7] offset:4096
	ds_write_b128 v199, v[8:11] offset:8192
	ds_write_b128 v199, v[12:15] offset:12288
	ds_write_b128 v199, v[16:19] offset:16384
	ds_write_b128 v199, v[20:23] offset:20480
	ds_write_b128 v199, v[24:27] offset:24576
	ds_write_b128 v199, v[28:31] offset:28672
	ds_write_b128 v199, v[32:35] offset:32768
	ds_write_b128 v199, v[36:39] offset:36864
	ds_write_b128 v199, v[40:43] offset:40960
	ds_write_b128 v199, v[44:47] offset:45056
	ds_write_b128 v199, v[48:51] offset:49152
	ds_write_b128 v199, v[52:55] offset:53248
	ds_write_b128 v199, v[56:59] offset:57344
	ds_write_b128 v199, v[60:63] offset:61440
	ds_write_b32 v200, v194
.Lscan_ld_bar2:
	s_waitcnt lgkmcnt(0)
	s_barrier
	s_add_i32 s28, s28, 1
	s_cmp_lt_u32 s28, s24
	s_cbranch_scc0 .Lscan_ld_done
	s_branch .Lscan_ld_step0

.LBB0_819:
	s_bitcmp1_b32 s7, 0
	s_cselect_b32 s12, 0x10100, 0
	s_cmp_eq_u32 s22, 0
	s_cselect_b64 vcc, -1, 0
	s_cselect_b32 s13, s7, s14
	s_movk_i32 s16, 0x8000
	s_cselect_b32 s16, 0x8000, s16
	s_cselect_b32 s17, 0, -1
	s_add_i32 s25, s12, s19
	s_add_i32 s15, s12, 0x10000
	v_lshl_add_u32 v150, v218, 4, s12
	v_lshl_add_u32 v151, v218, 3, s25
	v_lshrrev_b32_e32 v158, 4, v218
	v_lshl_add_u32 v152, v158, 4, s15
	s_add_i32 s15, s15, 0xfc
	v_mov_b32_e32 v153, s15
	ds_read_b32 v145, v153
	ds_read_b128 v[96:99], v152 offset:0
	ds_read_b128 v[100:103], v152 offset:64
	ds_read_b128 v[104:107], v152 offset:128
	ds_read_b128 v[108:111], v152 offset:192
	ds_read_b64 v[162:163], v151 offset:57344
	ds_read_b64 v[164:165], v151 offset:57856
	ds_read_b64 v[166:167], v151 offset:58368
	ds_read_b64 v[168:169], v151 offset:58880
	ds_read_b128 v[146:149], v150 offset:0
	ds_read_b128 v[170:173], v150 offset:4096
	ds_read_b128 v[174:177], v150 offset:8192
	ds_read_b128 v[178:181], v150 offset:12288
	ds_read_b128 v[182:185], v150 offset:1024
	ds_read_b128 v[186:189], v150 offset:5120
	ds_read_b128 v[190:193], v150 offset:9216
	ds_read_b128 v[194:197], v150 offset:13312
	ds_read_b128 v[198:201], v150 offset:2048
	ds_read_b128 v[202:205], v150 offset:6144
	s_lshl_b32 s13, s13, 6
	s_add_i32 s13, s13, s23
	s_mul_i32 s15, s22, 0x9000
	s_add_i32 s13, s13, s15
	s_lshl_b32 s13, s13, 11
	s_add_u32 s26, s10, s13
	s_addc_u32 s27, s11, 0
	s_add_u32 s28, s26, s16
	s_addc_u32 s29, s27, s17
	s_add_u32 s30, s28, s16
	s_addc_u32 s31, s29, s17
	s_add_u32 s12, s30, s16
	s_addc_u32 s13, s31, s17
	s_ashr_i32 s15, s16, 4
	v_lshlrev_b32_e32 v158, 2, v158
	v_sub_u32_e32 v159, 63, v158
	v_cndmask_b32_e32 v158, v159, v158, vcc
	v_and_b32_e32 v159, 15, v218
	v_lshlrev_b32_e32 v158, 11, v158
	v_lshl_add_u32 v154, v159, 1, v158
	v_add_u32_e32 v155, s15, v154
	v_add_u32_e32 v156, s15, v155
	v_add_u32_e32 v157, s15, v156
	s_waitcnt lgkmcnt(15)
	v_mul_f32_e32 v112, 0x3fb8aa3b, v96
	v_mul_f32_e32 v113, 0x3fb8aa3b, v97
	v_mul_f32_e32 v114, 0x3fb8aa3b, v98
	v_mul_f32_e32 v115, 0x3fb8aa3b, v99
	v_sub_f32_e32 v128, v145, v96
	v_sub_f32_e32 v129, v145, v97
	v_sub_f32_e32 v130, v145, v98
	v_sub_f32_e32 v131, v145, v99
	v_exp_f32_e32 v112, v112
	v_exp_f32_e32 v113, v113
	v_exp_f32_e32 v114, v114
	v_exp_f32_e32 v115, v115
	v_mul_f32_e32 v128, 0x3fb8aa3b, v128
	v_mul_f32_e32 v129, 0x3fb8aa3b, v129
	v_mul_f32_e32 v130, 0x3fb8aa3b, v130
	v_mul_f32_e32 v131, 0x3fb8aa3b, v131
	v_exp_f32_e32 v128, v128
	v_exp_f32_e32 v129, v129
	v_exp_f32_e32 v130, v130
	v_exp_f32_e32 v131, v131
	v_pk_mul_f32 v[112:113], v[112:113], s[24:25] op_sel_hi:[1,0]
	v_pk_mul_f32 v[114:115], v[114:115], s[24:25] op_sel_hi:[1,0]
	s_waitcnt lgkmcnt(15)
	v_mul_f32_e32 v116, 0x3fb8aa3b, v100
	v_mul_f32_e32 v117, 0x3fb8aa3b, v101
	v_mul_f32_e32 v118, 0x3fb8aa3b, v102
	v_mul_f32_e32 v119, 0x3fb8aa3b, v103
	v_sub_f32_e32 v132, v145, v100
	v_sub_f32_e32 v133, v145, v101
	v_sub_f32_e32 v134, v145, v102
	v_sub_f32_e32 v135, v145, v103
	v_exp_f32_e32 v116, v116
	v_exp_f32_e32 v117, v117
	v_exp_f32_e32 v118, v118
	v_exp_f32_e32 v119, v119
	v_mul_f32_e32 v132, 0x3fb8aa3b, v132
	v_mul_f32_e32 v133, 0x3fb8aa3b, v133
	v_mul_f32_e32 v134, 0x3fb8aa3b, v134
	v_mul_f32_e32 v135, 0x3fb8aa3b, v135
	v_exp_f32_e32 v132, v132
	v_exp_f32_e32 v133, v133
	v_exp_f32_e32 v134, v134
	v_exp_f32_e32 v135, v135
	v_pk_mul_f32 v[116:117], v[116:117], s[24:25] op_sel_hi:[1,0]
	v_pk_mul_f32 v[118:119], v[118:119], s[24:25] op_sel_hi:[1,0]
	s_waitcnt lgkmcnt(15)
	v_mul_f32_e32 v120, 0x3fb8aa3b, v104
	v_mul_f32_e32 v121, 0x3fb8aa3b, v105
	v_mul_f32_e32 v122, 0x3fb8aa3b, v106
	v_mul_f32_e32 v123, 0x3fb8aa3b, v107
	v_sub_f32_e32 v136, v145, v104
	v_sub_f32_e32 v137, v145, v105
	v_sub_f32_e32 v138, v145, v106
	v_sub_f32_e32 v139, v145, v107
	v_exp_f32_e32 v120, v120
	v_exp_f32_e32 v121, v121
	v_exp_f32_e32 v122, v122
	v_exp_f32_e32 v123, v123
	v_mul_f32_e32 v136, 0x3fb8aa3b, v136
	v_mul_f32_e32 v137, 0x3fb8aa3b, v137
	v_mul_f32_e32 v138, 0x3fb8aa3b, v138
	v_mul_f32_e32 v139, 0x3fb8aa3b, v139
	v_exp_f32_e32 v136, v136
	v_exp_f32_e32 v137, v137
	v_exp_f32_e32 v138, v138
	v_exp_f32_e32 v139, v139
	v_pk_mul_f32 v[120:121], v[120:121], s[24:25] op_sel_hi:[1,0]
	v_pk_mul_f32 v[122:123], v[122:123], s[24:25] op_sel_hi:[1,0]
	s_waitcnt lgkmcnt(14)
	v_mul_f32_e32 v124, 0x3fb8aa3b, v108
	v_mul_f32_e32 v125, 0x3fb8aa3b, v109
	v_mul_f32_e32 v126, 0x3fb8aa3b, v110
	v_mul_f32_e32 v127, 0x3fb8aa3b, v111
	v_sub_f32_e32 v140, v145, v108
	v_sub_f32_e32 v141, v145, v109
	v_sub_f32_e32 v142, v145, v110
	v_sub_f32_e32 v143, v145, v111
	v_exp_f32_e32 v124, v124
	v_exp_f32_e32 v125, v125
	v_exp_f32_e32 v126, v126
	v_exp_f32_e32 v127, v127
	v_mul_f32_e32 v140, 0x3fb8aa3b, v140
	v_mul_f32_e32 v141, 0x3fb8aa3b, v141
	v_mul_f32_e32 v142, 0x3fb8aa3b, v142
	v_mul_f32_e32 v143, 0x3fb8aa3b, v143
	v_exp_f32_e32 v140, v140
	v_exp_f32_e32 v141, v141
	v_exp_f32_e32 v142, v142
	v_exp_f32_e32 v143, v143
	v_pk_mul_f32 v[124:125], v[124:125], s[24:25] op_sel_hi:[1,0]
	v_pk_mul_f32 v[126:127], v[126:127], s[24:25] op_sel_hi:[1,0]
	v_mul_f32_e32 v144, 0x3fb8aa3b, v145
	v_exp_f32_e32 v144, v144
	s_waitcnt lgkmcnt(13)
	v_lshlrev_b32_e32 v48, 16, v162
	v_and_b32_e32 v49, 0xffff0000, v162
	v_lshlrev_b32_e32 v50, 16, v163
	v_and_b32_e32 v51, 0xffff0000, v163
	s_waitcnt lgkmcnt(12)
	v_lshlrev_b32_e32 v52, 16, v164
	v_and_b32_e32 v53, 0xffff0000, v164
	v_lshlrev_b32_e32 v54, 16, v165
	v_and_b32_e32 v55, 0xffff0000, v165
	s_waitcnt lgkmcnt(11)
	v_lshlrev_b32_e32 v56, 16, v166
	v_and_b32_e32 v57, 0xffff0000, v166
	v_lshlrev_b32_e32 v58, 16, v167
	v_and_b32_e32 v59, 0xffff0000, v167
	s_waitcnt lgkmcnt(10)
	v_lshlrev_b32_e32 v60, 16, v168
	v_and_b32_e32 v61, 0xffff0000, v168
	v_lshlrev_b32_e32 v62, 16, v169
	v_and_b32_e32 v63, 0xffff0000, v169
	s_waitcnt lgkmcnt(9)
	v_mfma_f32_16x16x32_bf16 v[48:51], v[146:149], v[44:47], v[48:51]
	ds_read_b128 v[146:149], v150 offset:10240
	s_waitcnt lgkmcnt(9)
	v_mfma_f32_16x16x32_bf16 v[52:55], v[170:173], v[44:47], v[52:55]
	ds_read_b128 v[170:173], v150 offset:14336
	s_waitcnt lgkmcnt(9)
	v_mfma_f32_16x16x32_bf16 v[56:59], v[174:177], v[44:47], v[56:59]
	ds_read_b128 v[174:177], v150 offset:3072
	s_waitcnt lgkmcnt(9)
	v_mfma_f32_16x16x32_bf16 v[60:63], v[178:181], v[44:47], v[60:63]
	ds_read_b128 v[178:181], v150 offset:7168
	s_waitcnt lgkmcnt(9)
	v_mfma_f32_16x16x32_bf16 v[48:51], v[182:185], v[40:43], v[48:51]
	ds_read_b128 v[182:185], v150 offset:11264
	s_waitcnt lgkmcnt(9)
	v_mfma_f32_16x16x32_bf16 v[52:55], v[186:189], v[40:43], v[52:55]
	ds_read_b128 v[186:189], v150 offset:15360
	s_waitcnt lgkmcnt(9)
	v_mfma_f32_16x16x32_bf16 v[56:59], v[190:193], v[40:43], v[56:59]
	ds_read_b128 v[190:193], v150 offset:16384
	s_waitcnt lgkmcnt(9)
	v_mfma_f32_16x16x32_bf16 v[60:63], v[194:197], v[40:43], v[60:63]
	ds_read_b128 v[194:197], v150 offset:20480
	s_waitcnt lgkmcnt(9)
	v_mfma_f32_16x16x32_bf16 v[48:51], v[198:201], v[32:35], v[48:51]
	ds_read_b128 v[198:201], v150 offset:24576
	s_waitcnt lgkmcnt(9)
	v_mfma_f32_16x16x32_bf16 v[52:55], v[202:205], v[32:35], v[52:55]
	ds_read_b128 v[202:205], v150 offset:28672
	s_waitcnt lgkmcnt(9)
	v_mfma_f32_16x16x32_bf16 v[56:59], v[146:149], v[32:35], v[56:59]
	ds_read_b128 v[146:149], v150 offset:17408
	s_waitcnt lgkmcnt(9)
	v_mfma_f32_16x16x32_bf16 v[60:63], v[170:173], v[32:35], v[60:63]
	ds_read_b128 v[170:173], v150 offset:21504
	s_waitcnt lgkmcnt(9)
	v_mfma_f32_16x16x32_bf16 v[48:51], v[174:177], v[36:39], v[48:51]
	ds_read_b128 v[174:177], v150 offset:25600
	s_waitcnt lgkmcnt(9)
	v_mfma_f32_16x16x32_bf16 v[52:55], v[178:181], v[36:39], v[52:55]
	ds_read_b128 v[178:181], v150 offset:29696
	s_waitcnt lgkmcnt(9)
	v_mfma_f32_16x16x32_bf16 v[56:59], v[182:185], v[36:39], v[56:59]
	ds_read_b128 v[182:185], v150 offset:18432
	s_waitcnt lgkmcnt(9)
	v_mfma_f32_16x16x32_bf16 v[60:63], v[186:189], v[36:39], v[60:63]
	ds_read_b128 v[186:189], v150 offset:22528
	s_waitcnt lgkmcnt(9)
	v_mfma_f32_16x16x32_bf16 v[80:83], v[190:193], v[44:47], 0
	ds_read_b128 v[190:193], v150 offset:26624
	v_pk_mul_f32 v[24:25], v[24:25], v[144:145] op_sel_hi:[1,0]
	v_pk_mul_f32 v[26:27], v[26:27], v[144:145] op_sel_hi:[1,0]
	s_waitcnt lgkmcnt(9)
	v_mfma_f32_16x16x32_bf16 v[84:87], v[194:197], v[44:47], 0
	ds_read_b128 v[194:197], v150 offset:30720
	v_pk_mul_f32 v[0:1], v[0:1], v[144:145] op_sel_hi:[1,0]
	v_pk_mul_f32 v[2:3], v[2:3], v[144:145] op_sel_hi:[1,0]
	s_waitcnt lgkmcnt(9)
	v_mfma_f32_16x16x32_bf16 v[88:91], v[198:201], v[44:47], 0
	ds_read_b128 v[198:201], v150 offset:19456
	v_pk_mul_f32 v[8:9], v[8:9], v[144:145] op_sel_hi:[1,0]
	v_pk_mul_f32 v[10:11], v[10:11], v[144:145] op_sel_hi:[1,0]
	s_waitcnt lgkmcnt(9)
	v_mfma_f32_16x16x32_bf16 v[92:95], v[202:205], v[44:47], 0
	ds_read_b128 v[202:205], v150 offset:23552
	v_pk_mul_f32 v[4:5], v[4:5], v[144:145] op_sel_hi:[1,0]
	v_pk_mul_f32 v[6:7], v[6:7], v[144:145] op_sel_hi:[1,0]
	s_waitcnt lgkmcnt(9)
	v_mfma_f32_16x16x32_bf16 v[80:83], v[146:149], v[40:43], v[80:83]
	ds_read_b128 v[146:149], v150 offset:27648
	v_pk_mul_f32 v[12:13], v[12:13], v[144:145] op_sel_hi:[1,0]
	v_pk_mul_f32 v[14:15], v[14:15], v[144:145] op_sel_hi:[1,0]
	s_waitcnt lgkmcnt(9)
	v_mfma_f32_16x16x32_bf16 v[84:87], v[170:173], v[40:43], v[84:87]
	ds_read_b128 v[170:173], v150 offset:31744
	v_pk_mul_f32 v[16:17], v[16:17], v[144:145] op_sel_hi:[1,0]
	v_pk_mul_f32 v[18:19], v[18:19], v[144:145] op_sel_hi:[1,0]
	s_waitcnt lgkmcnt(9)
	v_mfma_f32_16x16x32_bf16 v[88:91], v[174:177], v[40:43], v[88:91]
	ds_read_b128 v[174:177], v150 offset:32768
	v_pk_mul_f32 v[28:29], v[28:29], v[144:145] op_sel_hi:[1,0]
	v_pk_mul_f32 v[30:31], v[30:31], v[144:145] op_sel_hi:[1,0]
	s_waitcnt lgkmcnt(9)
	v_mfma_f32_16x16x32_bf16 v[92:95], v[178:181], v[40:43], v[92:95]
	ds_read_b128 v[178:181], v150 offset:33792
	v_pk_mul_f32 v[20:21], v[20:21], v[144:145] op_sel_hi:[1,0]
	v_pk_mul_f32 v[22:23], v[22:23], v[144:145] op_sel_hi:[1,0]
	s_waitcnt lgkmcnt(9)
	v_mfma_f32_16x16x32_bf16 v[80:83], v[182:185], v[32:35], v[80:83]
	ds_read_b128 v[182:185], v150 offset:34816
	v_cvt_pk_bf16_f32 v64, v48, v49
	v_cvt_pk_bf16_f32 v65, v50, v51
	v_cvt_pk_bf16_f32 v66, v52, v53
	s_waitcnt lgkmcnt(9)
	v_mfma_f32_16x16x32_bf16 v[84:87], v[186:189], v[32:35], v[84:87]
	ds_read_b128 v[186:189], v150 offset:35840
	v_cvt_pk_bf16_f32 v67, v54, v55
	v_cvt_pk_bf16_f32 v68, v56, v57
	v_cvt_pk_bf16_f32 v69, v58, v59
	s_waitcnt lgkmcnt(9)
	v_mfma_f32_16x16x32_bf16 v[88:91], v[190:193], v[32:35], v[88:91]
	ds_read_b128 v[190:193], v150 offset:36864
	v_cvt_pk_bf16_f32 v70, v60, v61
	v_cvt_pk_bf16_f32 v71, v62, v63
	v_pk_mul_f32 v[128:129], v[48:49], v[128:129]
	s_waitcnt lgkmcnt(9)
	v_mfma_f32_16x16x32_bf16 v[92:95], v[194:197], v[32:35], v[92:95]
	ds_read_b128 v[194:197], v150 offset:37888
	v_pk_mul_f32 v[130:131], v[50:51], v[130:131]
	v_cvt_pk_bf16_f32 v72, v128, v129
	v_cvt_pk_bf16_f32 v73, v130, v131
	s_waitcnt lgkmcnt(9)
	v_mfma_f32_16x16x32_bf16 v[80:83], v[198:201], v[36:39], v[80:83]
	ds_read_b128 v[198:201], v150 offset:38912
	v_pk_mul_f32 v[132:133], v[52:53], v[132:133]
	v_pk_mul_f32 v[134:135], v[54:55], v[134:135]
	v_cvt_pk_bf16_f32 v74, v132, v133
	s_waitcnt lgkmcnt(9)
	v_mfma_f32_16x16x32_bf16 v[84:87], v[202:205], v[36:39], v[84:87]
	ds_read_b128 v[202:205], v150 offset:39936
	v_cvt_pk_bf16_f32 v75, v134, v135
	v_pk_mul_f32 v[136:137], v[56:57], v[136:137]
	v_pk_mul_f32 v[138:139], v[58:59], v[138:139]
	s_waitcnt lgkmcnt(9)
	v_mfma_f32_16x16x32_bf16 v[88:91], v[146:149], v[36:39], v[88:91]
	ds_read_b128 v[146:149], v150 offset:40960
	v_cvt_pk_bf16_f32 v76, v136, v137
	v_cvt_pk_bf16_f32 v77, v138, v139
	v_pk_mul_f32 v[140:141], v[60:61], v[140:141]
	s_waitcnt lgkmcnt(9)
	v_mfma_f32_16x16x32_bf16 v[92:95], v[170:173], v[36:39], v[92:95]
	ds_read_b128 v[170:173], v150 offset:41984
	v_pk_mul_f32 v[142:143], v[62:63], v[142:143]
	v_cvt_pk_bf16_f32 v78, v140, v141
	v_cvt_pk_bf16_f32 v79, v142, v143
	s_waitcnt lgkmcnt(9)
	v_mfma_f32_16x16x32_bf16 v[24:27], v[174:177], v[72:75], v[24:27]
	ds_read_b128 v[174:177], v150 offset:43008
	s_waitcnt lgkmcnt(9)
	v_mfma_f32_16x16x32_bf16 v[24:27], v[178:181], v[76:79], v[24:27]
	ds_read_b128 v[178:181], v150 offset:44032
	s_waitcnt lgkmcnt(9)
	v_mfma_f32_16x16x32_bf16 v[0:3], v[182:185], v[72:75], v[0:3]
	ds_read_b128 v[182:185], v150 offset:45056
	s_waitcnt lgkmcnt(9)
	v_mfma_f32_16x16x32_bf16 v[0:3], v[186:189], v[76:79], v[0:3]
	ds_read_b128 v[186:189], v150 offset:46080
	s_waitcnt lgkmcnt(9)
	v_mfma_f32_16x16x32_bf16 v[8:11], v[190:193], v[72:75], v[8:11]
	ds_read_b128 v[190:193], v150 offset:47104
	s_waitcnt lgkmcnt(9)
	v_mfma_f32_16x16x32_bf16 v[8:11], v[194:197], v[76:79], v[8:11]
	ds_read_b128 v[194:197], v150 offset:48128
	s_waitcnt lgkmcnt(9)
	v_mfma_f32_16x16x32_bf16 v[4:7], v[198:201], v[72:75], v[4:7]
	ds_read_b128 v[198:201], v150 offset:49152
	s_waitcnt lgkmcnt(9)
	v_mfma_f32_16x16x32_bf16 v[4:7], v[202:205], v[76:79], v[4:7]
	ds_read_b128 v[202:205], v150 offset:50176
	s_waitcnt lgkmcnt(9)
	v_mfma_f32_16x16x32_bf16 v[12:15], v[146:149], v[72:75], v[12:15]
	ds_read_b128 v[146:149], v150 offset:51200
	v_mul_f32_e32 v80, v112, v80
	v_mul_f32_e32 v81, v113, v81
	s_waitcnt lgkmcnt(9)
	v_mfma_f32_16x16x32_bf16 v[12:15], v[170:173], v[76:79], v[12:15]
	ds_read_b128 v[170:173], v150 offset:52224
	v_mul_f32_e32 v82, v114, v82
	v_mul_f32_e32 v83, v115, v83
	s_waitcnt lgkmcnt(9)
	v_mfma_f32_16x16x32_bf16 v[16:19], v[174:177], v[72:75], v[16:19]
	ds_read_b128 v[174:177], v150 offset:53248
	v_mul_f32_e32 v84, v116, v84
	v_mul_f32_e32 v85, v117, v85
	s_waitcnt lgkmcnt(9)
	v_mfma_f32_16x16x32_bf16 v[16:19], v[178:181], v[76:79], v[16:19]
	ds_read_b128 v[178:181], v150 offset:54272
	v_mul_f32_e32 v86, v118, v86
	v_mul_f32_e32 v87, v119, v87
	s_waitcnt lgkmcnt(9)
	v_mfma_f32_16x16x32_bf16 v[28:31], v[182:185], v[72:75], v[28:31]
	ds_read_b128 v[182:185], v150 offset:55296
	v_mul_f32_e32 v88, v120, v88
	v_mul_f32_e32 v89, v121, v89
	s_waitcnt lgkmcnt(9)
	v_mfma_f32_16x16x32_bf16 v[28:31], v[186:189], v[76:79], v[28:31]
	ds_read_b128 v[186:189], v150 offset:56320
	v_mul_f32_e32 v90, v122, v90
	v_mul_f32_e32 v91, v123, v91
	s_waitcnt lgkmcnt(9)
	v_mfma_f32_16x16x32_bf16 v[20:23], v[190:193], v[72:75], v[20:23]
	v_mul_f32_e32 v92, v124, v92
	v_mul_f32_e32 v93, v125, v93
	s_waitcnt lgkmcnt(8)
	v_mfma_f32_16x16x32_bf16 v[20:23], v[194:197], v[76:79], v[20:23]
	v_mul_f32_e32 v94, v126, v94
	v_mul_f32_e32 v95, v127, v95
	s_waitcnt lgkmcnt(7)
	v_mfma_f32_16x16x32_bf16 v[80:83], v[198:201], v[64:67], v[80:83]
	s_waitcnt lgkmcnt(6)
	v_mfma_f32_16x16x32_bf16 v[80:83], v[202:205], v[68:71], v[80:83]
	s_waitcnt lgkmcnt(5)
	v_mfma_f32_16x16x32_bf16 v[84:87], v[146:149], v[64:67], v[84:87]
	s_waitcnt lgkmcnt(4)
	v_mfma_f32_16x16x32_bf16 v[84:87], v[170:173], v[68:71], v[84:87]
	s_waitcnt lgkmcnt(3)
	v_mfma_f32_16x16x32_bf16 v[88:91], v[174:177], v[64:67], v[88:91]
	s_waitcnt lgkmcnt(2)
	v_mfma_f32_16x16x32_bf16 v[88:91], v[178:181], v[68:71], v[88:91]
	s_waitcnt lgkmcnt(1)
	v_mfma_f32_16x16x32_bf16 v[92:95], v[182:185], v[64:67], v[92:95]
	s_waitcnt lgkmcnt(0)
	v_mfma_f32_16x16x32_bf16 v[92:95], v[186:189], v[68:71], v[92:95]
	v_cvt_pk_bf16_f32 v44, v24, v25
	v_cvt_pk_bf16_f32 v45, v26, v27
	v_cvt_pk_bf16_f32 v46, v0, v1
	v_cvt_pk_bf16_f32 v47, v2, v3
	v_cvt_pk_bf16_f32 v40, v8, v9
	v_cvt_pk_bf16_f32 v41, v10, v11
	v_cvt_pk_bf16_f32 v42, v4, v5
	v_cvt_pk_bf16_f32 v43, v6, v7
	v_cvt_pk_bf16_f32 v32, v12, v13
	v_cvt_pk_bf16_f32 v33, v14, v15
	v_cvt_pk_bf16_f32 v34, v16, v17
	v_cvt_pk_bf16_f32 v35, v18, v19
	v_cvt_pk_bf16_f32 v36, v28, v29
	v_cvt_pk_bf16_f32 v37, v30, v31
	v_cvt_pk_bf16_f32 v38, v20, v21
	v_cvt_pk_bf16_f32 v39, v22, v23
	s_add_i32 s7, s7, 1
	s_add_i32 s14, s14, -1
	v_cvt_pk_bf16_f32 v96, v80, v81
	v_cvt_pk_bf16_f32 v97, v82, v83
	v_cvt_pk_bf16_f32 v100, v84, v85
	v_cvt_pk_bf16_f32 v101, v86, v87
	v_cvt_pk_bf16_f32 v104, v88, v89
	v_cvt_pk_bf16_f32 v105, v90, v91
	v_cvt_pk_bf16_f32 v108, v92, v93
	v_cvt_pk_bf16_f32 v109, v94, v95
	global_store_short v154, v96, s[26:27]
	global_store_short_d16_hi v155, v96, s[26:27]
	global_store_short v156, v97, s[26:27]
	global_store_short_d16_hi v157, v97, s[26:27]
	global_store_short v154, v100, s[28:29]
	global_store_short_d16_hi v155, v100, s[28:29]
	global_store_short v156, v101, s[28:29]
	global_store_short_d16_hi v157, v101, s[28:29]
	global_store_short v154, v104, s[30:31]
	global_store_short_d16_hi v155, v104, s[30:31]
	global_store_short v156, v105, s[30:31]
	global_store_short_d16_hi v157, v105, s[30:31]
	global_store_short v154, v108, s[12:13]
	global_store_short_d16_hi v155, v108, s[12:13]
	global_store_short v156, v109, s[12:13]
	global_store_short_d16_hi v157, v109, s[12:13]
	s_cmp_eq_u32 s14, -1
	s_barrier
	s_cbranch_scc0 .LBB0_819
	s_and_b64 vcc, exec, s[8:9]
	s_cbranch_vccz .LBB0_784
	s_ashr_i32 s7, s6, 31
	s_lshl_b64 s[6:7], s[6:7], 2
	s_add_u32 s6, s6, s4
	s_addc_u32 s7, s7, s5
	s_or_b32 s6, s6, s22
	s_lshl_b64 s[6:7], s[6:7], 19
	v_readlane_b32 s8, v253, 30
	s_add_u32 s6, s8, s6
	v_readlane_b32 s8, v253, 31
	s_addc_u32 s7, s8, s7
	s_lshl_b32 s8, s21, 16
	v_mov_b32_e32 v32, v218
	s_add_u32 s6, s6, s8
	s_addc_u32 s7, s7, 0
	v_ashrrev_i32_e32 v40, 2, v32
	s_lshl_b64 s[0:1], s[0:1], 2
	v_and_b32_e32 v33, 15, v32
	v_and_b32_e32 v32, -4, v40
	s_add_u32 s0, s6, s0
	s_addc_u32 s1, s7, s1
	v_lshlrev_b32_e32 v160, 2, v33
	v_ashrrev_i32_e32 v33, 31, v32
	v_or_b32_e32 v38, 1, v32
	v_lshl_add_u64 v[34:35], s[0:1], 0, v[160:161]
	v_lshlrev_b64 v[36:37], 9, v[32:33]
	v_ashrrev_i32_e32 v39, 31, v38
	v_lshl_add_u64 v[36:37], v[34:35], 0, v[36:37]
	v_lshlrev_b64 v[38:39], 9, v[38:39]
	global_store_dword v[36:37], v24, off
	v_lshl_add_u64 v[38:39], v[34:35], 0, v[38:39]
	v_or_b32_e32 v24, 2, v32
	global_store_dword v[38:39], v25, off
	v_ashrrev_i32_e32 v25, 31, v24
	v_lshlrev_b64 v[24:25], 9, v[24:25]
	v_lshl_add_u64 v[24:25], v[34:35], 0, v[24:25]
	global_store_dword v[24:25], v26, off
	v_or_b32_e32 v24, 3, v40
	v_ashrrev_i32_e32 v25, 31, v24
	v_lshlrev_b64 v[24:25], 9, v[24:25]
	v_lshl_add_u64 v[24:25], v[34:35], 0, v[24:25]
	s_movk_i32 s0, 0x2000
	global_store_dword v[24:25], v27, off
	v_add_co_u32_e32 v24, vcc, s0, v36
	s_nop 1
	v_addc_co_u32_e32 v25, vcc, 0, v37, vcc
	global_store_dword v[24:25], v0, off
	global_store_dword v[24:25], v1, off offset:512
	global_store_dword v[24:25], v2, off offset:1024
	global_store_dword v[24:25], v3, off offset:1536
	v_add_co_u32_e32 v0, vcc, s94, v36
	s_nop 1
	v_addc_co_u32_e32 v1, vcc, 0, v37, vcc
	global_store_dword v[0:1], v8, off
	global_store_dword v[0:1], v9, off offset:512
	global_store_dword v[0:1], v10, off offset:1024
	global_store_dword v[0:1], v11, off offset:1536
	v_add_co_u32_e32 v0, vcc, s46, v36
	s_nop 1
	v_addc_co_u32_e32 v1, vcc, 0, v37, vcc
	global_store_dword v[0:1], v4, off
	global_store_dword v[0:1], v5, off offset:512
	global_store_dword v[0:1], v6, off offset:1024
	global_store_dword v[0:1], v7, off offset:1536
	v_add_co_u32_e32 v0, vcc, s91, v36
	s_nop 1
	v_addc_co_u32_e32 v1, vcc, 0, v37, vcc
	global_store_dword v[0:1], v12, off
	global_store_dword v[0:1], v13, off offset:512
	global_store_dword v[0:1], v14, off offset:1024
	global_store_dword v[0:1], v15, off offset:1536
	v_add_co_u32_e32 v0, vcc, 0xa000, v36
	s_nop 1
	v_addc_co_u32_e32 v1, vcc, 0, v37, vcc
	global_store_dword v[0:1], v16, off
	global_store_dword v[0:1], v17, off offset:512
	global_store_dword v[0:1], v18, off offset:1024
	global_store_dword v[0:1], v19, off offset:1536
	v_add_co_u32_e32 v0, vcc, 0xc000, v36
	s_nop 1
	v_addc_co_u32_e32 v1, vcc, 0, v37, vcc
	global_store_dword v[0:1], v28, off
	global_store_dword v[0:1], v29, off offset:512
	global_store_dword v[0:1], v30, off offset:1024
	global_store_dword v[0:1], v31, off offset:1536
	v_add_co_u32_e32 v0, vcc, 0xe000, v36
	s_nop 1
	v_addc_co_u32_e32 v1, vcc, 0, v37, vcc
	global_store_dword v[0:1], v20, off
	global_store_dword v[0:1], v21, off offset:512
	global_store_dword v[0:1], v22, off offset:1024
	global_store_dword v[0:1], v23, off offset:1536
	s_branch .LBB0_784

.LBB0_869:
	v_readlane_b32 s0, v253, 32
	v_readlane_b32 s1, v253, 33
	s_andn2_b64 vcc, exec, s[0:1]
	s_cbranch_vccnz .LBB0_874
	v_readlane_b32 s0, v254, 10
	v_mbcnt_lo_u32_b32 v9, -1, 0
	v_mbcnt_hi_u32_b32 v9, -1, v9
	s_nop 1
	v_mov_b32_e32 v0, s0
	s_waitcnt vmcnt(0)
	ds_read_b64 v[0:1], v0
	v_readlane_b32 s0, v253, 53
	s_waitcnt lgkmcnt(0)
	v_readfirstlane_b32 s2, v0
	v_add_u32_e32 v2, s0, v9
	v_ashrrev_i32_e32 v2, 6, v2
	v_readlane_b32 s0, v252, 15
	v_readfirstlane_b32 s3, v1
	s_nop 0
	v_add_u32_e32 v8, s0, v2
	v_cmp_gt_i32_e32 vcc, s47, v8
	s_and_saveexec_b64 s[0:1], vcc
	v_readlane_b32 s8, v253, 55
	v_readlane_b32 s9, v253, 56
	v_readlane_b32 s10, v253, 57
	v_readlane_b32 s11, v253, 58
	s_mov_b32 s8, 0x800000
	s_mov_b32 s9, 0x8fff
	s_cbranch_execz .LBB0_873
	s_ashr_i32 s73, s72, 31
	s_lshl_b64 s[4:5], s[72:73], 9
	s_add_u32 s2, s2, s4
	v_lshlrev_b32_e32 v0, 5, v9
	s_addc_u32 s3, s3, s5
	v_and_b32_e32 v160, 0x1e0, v0
	v_lshl_add_u64 v[4:5], s[2:3], 0, v[160:161]
	flat_load_dwordx4 v[0:3], v[4:5]
	s_nop 0
	flat_load_dwordx4 v[4:7], v[4:5] offset:16
	v_readlane_b32 s2, v252, 16
	v_readlane_b32 s3, v252, 17
	s_load_dword s2, s[2:3], 0x0
	v_lshlrev_b32_e32 v10, 3, v9
	v_and_b32_e32 v12, 0x1f8, v10
	v_lshlrev_b32_e32 v9, 2, v9
	v_bfrev_b32_e32 v11, 0.5
	s_waitcnt lgkmcnt(0)
	s_lshl_b32 s4, s2, 3
	v_readlane_b32 s2, v253, 43
	v_or_b32_e32 v14, 0x200, v12
	v_lshlrev_b32_e32 v160, 1, v12
	v_readlane_b32 s3, v253, 44
	v_readlane_b32 s73, v254, 13
	s_movk_i32 s63, 0x3bb
	v_readlane_b32 s62, v254, 12
	v_bitop3_b32 v16, v9, 4, v11 bitop3:0x6c
	v_bitop3_b32 v17, v9, 8, v11 bitop3:0x6c
	v_bitop3_b32 v18, v9, 16, v11 bitop3:0x6c
	v_bitop3_b32 v19, v9, 32, v11 bitop3:0x6c
	v_lshl_add_u64 v[10:11], s[2:3], 0, v[160:161]
	s_mov_b64 s[2:3], 0
	v_lshlrev_b32_e32 v160, 1, v12
	v_lshlrev_b32_e32 v12, 1, v14
	v_ashrrev_i32_e32 v9, 31, v8
	v_lshlrev_b64 v[14:15], 11, v[8:9]
	v_lshl_add_u64 v[14:15], s[68:69], 0, v[14:15]
	s_mov_b64 s[6:7], 0x4800000
	v_lshlrev_b64 v[40:41], 13, v[8:9]
	v_lshl_add_u64 v[24:25], v[14:15], 0, v[160:161]
	v_lshl_add_u64 v[14:15], v[14:15], 0, s[6:7]
	v_lshl_add_u64 v[32:33], s[10:11], 0, v[40:41]
	s_mov_b64 s[6:7], 0x23701800
	v_lshl_add_u64 v[42:43], v[32:33], 0, s[6:7]
	v_lshl_add_u64 v[32:33], v[42:43], 0, v[160:161]
	global_load_dwordx4 v[20:23], v[24:25], off
	s_nop 0
	global_load_dwordx4 v[24:27], v[24:25], off offset:1024
	v_lshl_add_u64 v[28:29], v[14:15], 0, v[160:161]
	global_load_dwordx4 v[32:35], v[32:33], off
	v_mov_b32_e32 v13, v161
	global_load_dwordx4 v[28:31], v[28:29], off
	v_lshl_add_u64 v[14:15], v[14:15], 0, v[12:13]
	global_load_dwordx4 v[36:39], v[14:15], off
	v_lshl_add_u64 v[14:15], v[10:11], 0, v[40:41]
	v_lshl_add_u64 v[40:41], v[42:43], 0, v[12:13]
	global_load_dwordx4 v[40:43], v[40:41], off
	s_brev_b32 s6, 60
	v_add_u32_e32 v8, s4, v8
.LBB0_872:
	s_waitcnt vmcnt(0)
	v_mov_b32_e32 v108, v8
	v_mov_b32_e32 v114, v14
	v_mov_b32_e32 v115, v15
	v_mov_b32_e32 v120, v20
	v_mov_b32_e32 v121, v21
	v_mov_b32_e32 v122, v22
	v_mov_b32_e32 v123, v23
	v_mov_b32_e32 v124, v24
	v_mov_b32_e32 v125, v25
	v_mov_b32_e32 v126, v26
	v_mov_b32_e32 v127, v27
	v_mov_b32_e32 v128, v28
	v_mov_b32_e32 v129, v29
	v_mov_b32_e32 v130, v30
	v_mov_b32_e32 v131, v31
	v_mov_b32_e32 v132, v32
	v_mov_b32_e32 v133, v33
	v_mov_b32_e32 v134, v34
	v_mov_b32_e32 v135, v35
	v_mov_b32_e32 v136, v36
	v_mov_b32_e32 v137, v37
	v_mov_b32_e32 v138, v38
	v_mov_b32_e32 v139, v39
	v_mov_b32_e32 v140, v40
	v_mov_b32_e32 v141, v41
	v_mov_b32_e32 v142, v42
	v_mov_b32_e32 v143, v43
	v_min_i32_e32 v110, s9, v8
	v_ashrrev_i32_e32 v111, 31, v110
	v_lshlrev_b64 v[14:15], 11, v[110:111]
	v_lshl_add_u64 v[14:15], s[68:69], 0, v[14:15]
	s_mov_b64 s[6:7], 0x4800000
	v_lshlrev_b64 v[40:41], 13, v[110:111]
	v_lshl_add_u64 v[24:25], v[14:15], 0, v[160:161]
	v_lshl_add_u64 v[14:15], v[14:15], 0, s[6:7]
	v_lshl_add_u64 v[32:33], s[10:11], 0, v[40:41]
	s_mov_b64 s[6:7], 0x23701800
	v_lshl_add_u64 v[42:43], v[32:33], 0, s[6:7]
	v_lshl_add_u64 v[32:33], v[42:43], 0, v[160:161]
	global_load_dwordx4 v[20:23], v[24:25], off
	s_nop 0
	global_load_dwordx4 v[24:27], v[24:25], off offset:1024
	v_lshl_add_u64 v[28:29], v[14:15], 0, v[160:161]
	global_load_dwordx4 v[32:35], v[32:33], off
	v_mov_b32_e32 v13, v161
	global_load_dwordx4 v[28:31], v[28:29], off
	v_lshl_add_u64 v[14:15], v[14:15], 0, v[12:13]
	global_load_dwordx4 v[36:39], v[14:15], off
	v_lshl_add_u64 v[14:15], v[10:11], 0, v[40:41]
	v_lshl_add_u64 v[40:41], v[42:43], 0, v[12:13]
	global_load_dwordx4 v[40:43], v[40:41], off
	s_brev_b32 s6, 60
	v_add_u32_e32 v8, s4, v8
	v_lshlrev_b32_e32 v46, 16, v122
	v_and_b32_e32 v47, 0xffff0000, v122
	v_lshlrev_b32_e32 v122, 16, v123
	v_lshlrev_b32_e32 v58, 16, v134
	v_and_b32_e32 v59, 0xffff0000, v134
	v_lshlrev_b32_e32 v134, 16, v135
	v_and_b32_e32 v135, 0xffff0000, v135
	v_mul_f32_e32 v64, 0xbfb8aa3b, v134
	v_mul_f32_e32 v65, 0xbfb8aa3b, v135
	v_exp_f32_e32 v64, v64
	v_exp_f32_e32 v65, v65
	v_and_b32_e32 v123, 0xffff0000, v123
	v_lshlrev_b32_e32 v54, 16, v130
	v_and_b32_e32 v55, 0xffff0000, v130
	v_lshlrev_b32_e32 v130, 16, v131
	v_and_b32_e32 v131, 0xffff0000, v131
	v_lshlrev_b32_e32 v56, 16, v132
	v_and_b32_e32 v57, 0xffff0000, v132
	v_lshlrev_b32_e32 v132, 16, v133
	v_and_b32_e32 v133, 0xffff0000, v133
	v_pk_add_f32 v[130:131], v[122:123], v[130:131]
	v_pk_add_f32 v[122:123], v[46:47], v[54:55]
	v_mul_f32_e32 v51, 0xbfb8aa3b, v132
	v_mul_f32_e32 v54, 0xbfb8aa3b, v133
	v_mul_f32_e32 v55, 0xbfb8aa3b, v56
	v_mul_f32_e32 v63, 0xbfb8aa3b, v57
	v_add_f32_e32 v68, 1.0, v64
	v_add_f32_e32 v69, 1.0, v65
	v_exp_f32_e32 v51, v51
	v_exp_f32_e32 v54, v54
	v_exp_f32_e32 v55, v55
	v_exp_f32_e32 v63, v63
	v_rcp_f32_e32 v68, v68
	v_rcp_f32_e32 v69, v69
	v_lshlrev_b32_e32 v44, 16, v120
	v_and_b32_e32 v45, 0xffff0000, v120
	v_lshlrev_b32_e32 v120, 16, v121
	v_and_b32_e32 v121, 0xffff0000, v121
	v_lshlrev_b32_e32 v48, 16, v124
	v_and_b32_e32 v49, 0xffff0000, v124
	v_lshlrev_b32_e32 v52, 16, v128
	v_and_b32_e32 v53, 0xffff0000, v128
	v_lshlrev_b32_e32 v128, 16, v129
	v_and_b32_e32 v129, 0xffff0000, v129
	v_lshlrev_b32_e32 v60, 16, v136
	v_and_b32_e32 v61, 0xffff0000, v136
	v_lshlrev_b32_e32 v124, 16, v125
	v_and_b32_e32 v125, 0xffff0000, v125
	v_lshlrev_b32_e32 v136, 16, v137
	v_and_b32_e32 v137, 0xffff0000, v137
	v_pk_add_f32 v[128:129], v[120:121], v[128:129]
	v_pk_add_f32 v[120:121], v[44:45], v[52:53]
	v_pk_add_f32 v[48:49], v[48:49], v[60:61]
	v_add_f32_e32 v51, 1.0, v51
	v_add_f32_e32 v66, 1.0, v54
	v_add_f32_e32 v67, 1.0, v55
	v_add_f32_e32 v63, 1.0, v63
	v_pk_mul_f32 v[134:135], v[68:69], v[134:135]
	v_pk_add_f32 v[124:125], v[124:125], v[136:137]
	v_mov_b32_e32 v68, v49
	v_mov_b32_e32 v69, v121
	v_lshlrev_b32_e32 v50, 16, v126
	v_lshlrev_b32_e32 v62, 16, v138
	v_pk_mul_f32 v[52:53], v[128:129], v[128:129]
	v_rcp_f32_e32 v64, v51
	v_rcp_f32_e32 v65, v66
	v_rcp_f32_e32 v66, v67
	v_rcp_f32_e32 v67, v63
	v_and_b32_e32 v51, 0xffff0000, v126
	v_and_b32_e32 v63, 0xffff0000, v138
	v_pk_mul_f32 v[136:137], v[124:125], v[124:125]
	v_mov_b32_e32 v60, v48
	v_mov_b32_e32 v61, v120
	v_pk_mul_f32 v[68:69], v[68:69], v[68:69]
	v_pk_add_f32 v[50:51], v[50:51], v[62:63]
	v_pk_fma_f32 v[60:61], v[60:61], v[60:61], v[68:69]
	v_mov_b32_e32 v68, v136
	v_mov_b32_e32 v69, v52
	v_pk_mul_f32 v[46:47], v[122:123], v[122:123]
	v_lshlrev_b32_e32 v126, 16, v127
	v_lshlrev_b32_e32 v138, 16, v139
	v_and_b32_e32 v127, 0xffff0000, v127
	v_and_b32_e32 v139, 0xffff0000, v139
	v_pk_mul_f32 v[62:63], v[50:51], v[50:51]
	v_pk_add_f32 v[60:61], v[60:61], v[68:69]
	v_mov_b32_e32 v52, v137
	v_pk_add_f32 v[126:127], v[126:127], v[138:139]
	v_pk_add_f32 v[136:137], v[52:53], v[60:61]
	v_mov_b32_e32 v52, v62
	v_mov_b32_e32 v53, v46
	v_pk_mul_f32 v[44:45], v[130:131], v[130:131]
	v_pk_mul_f32 v[138:139], v[126:127], v[126:127]
	v_pk_add_f32 v[136:137], v[52:53], v[136:137]
	v_mov_b32_e32 v46, v63
	v_pk_add_f32 v[136:137], v[46:47], v[136:137]
	v_mov_b32_e32 v46, v138
	v_mov_b32_e32 v47, v44
	v_mul_f32_e32 v9, 0xbfb8aa3b, v58
	v_pk_add_f32 v[136:137], v[46:47], v[136:137]
	v_mov_b32_e32 v44, v139
	v_mul_f32_e32 v13, 0xbfb8aa3b, v59
	v_exp_f32_e32 v9, v9
	v_pk_add_f32 v[136:137], v[44:45], v[136:137]
	v_exp_f32_e32 v13, v13
	ds_bpermute_b32 v139, v16, v137
	ds_bpermute_b32 v138, v16, v136
	v_add_f32_e32 v9, 1.0, v9
	v_pk_mul_f32 v[132:133], v[64:65], v[132:133]
	v_lshlrev_b32_e32 v64, 16, v142
	v_add_f32_e32 v13, 1.0, v13
	v_rcp_f32_e32 v54, v9
	v_and_b32_e32 v65, 0xffff0000, v142
	v_mul_f32_e32 v9, 0xbfb8aa3b, v64
	v_rcp_f32_e32 v55, v13
	v_exp_f32_e32 v9, v9
	v_mul_f32_e32 v13, 0xbfb8aa3b, v65
	s_waitcnt lgkmcnt(0)
	v_pk_add_f32 v[136:137], v[136:137], v[138:139]
	v_exp_f32_e32 v13, v13
	ds_bpermute_b32 v139, v17, v137
	ds_bpermute_b32 v138, v17, v136
	v_add_f32_e32 v9, 1.0, v9
	v_pk_mul_f32 v[54:55], v[54:55], v[58:59]
	v_pk_mul_f32 v[56:57], v[66:67], v[56:57]
	v_lshlrev_b32_e32 v58, 16, v140
	v_and_b32_e32 v59, 0xffff0000, v140
	v_lshlrev_b32_e32 v140, 16, v141
	v_rcp_f32_e32 v66, v9
	v_add_f32_e32 v9, 1.0, v13
	v_and_b32_e32 v141, 0xffff0000, v141
	v_rcp_f32_e32 v67, v9
	v_mul_f32_e32 v9, 0xbfb8aa3b, v140
	s_waitcnt lgkmcnt(0)
	v_pk_add_f32 v[136:137], v[136:137], v[138:139]
	v_exp_f32_e32 v9, v9
	v_mul_f32_e32 v13, 0xbfb8aa3b, v141
	ds_bpermute_b32 v139, v18, v137
	ds_bpermute_b32 v138, v18, v136
	v_exp_f32_e32 v13, v13
	v_add_f32_e32 v9, 1.0, v9
	v_rcp_f32_e32 v44, v9
	v_lshlrev_b32_e32 v142, 16, v143
	v_add_f32_e32 v9, 1.0, v13
	s_waitcnt lgkmcnt(0)
	v_pk_add_f32 v[136:137], v[136:137], v[138:139]
	v_rcp_f32_e32 v45, v9
	v_mul_f32_e32 v9, 0xbfb8aa3b, v58
	ds_bpermute_b32 v139, v19, v137
	ds_bpermute_b32 v138, v19, v136
	v_exp_f32_e32 v9, v9
	v_mul_f32_e32 v13, 0xbfb8aa3b, v59
	v_exp_f32_e32 v13, v13
	v_pk_mul_f32 v[140:141], v[44:45], v[140:141]
	v_add_f32_e32 v9, 1.0, v9
	s_waitcnt lgkmcnt(0)
	v_pk_add_f32 v[136:137], v[136:137], v[138:139]
	v_rcp_f32_e32 v46, v9
	v_add_f32_e32 v9, 1.0, v13
	v_pk_fma_f32 v[136:137], v[136:137], s[6:7], v[206:207] op_sel_hi:[1,0,0]
	v_rcp_f32_e32 v47, v9
	v_mul_f32_e32 v9, 0x4b800000, v137
	v_cmp_gt_f32_e32 vcc, s8, v137
	v_and_b32_e32 v143, 0xffff0000, v143
	v_pk_mul_f32 v[44:45], v[46:47], v[58:59]
	v_cndmask_b32_e32 v9, v137, v9, vcc
	v_rsq_f32_e32 v9, v9
	v_pk_mul_f32 v[138:139], v[66:67], v[64:65]
	v_mul_f32_e32 v13, 0x45800000, v9
	v_cndmask_b32_e32 v46, v9, v13, vcc
	v_mul_f32_e32 v9, 0x4b800000, v136
	v_cmp_gt_f32_e32 vcc, s8, v136
	v_pk_mul_f32 v[120:121], v[120:121], v[46:47] op_sel_hi:[1,0]
	v_pk_mul_f32 v[128:129], v[128:129], v[46:47] op_sel_hi:[1,0]
	v_cndmask_b32_e32 v9, v136, v9, vcc
	v_pk_mul_f32 v[120:121], v[0:1], v[120:121]
	v_pk_mul_f32 v[128:129], v[2:3], v[128:129]
	v_rsq_f32_e32 v9, v9
	v_pk_mul_f32 v[120:121], v[56:57], v[120:121]
	v_pk_mul_f32 v[128:129], v[132:133], v[128:129]
	v_cvt_pk_bf16_f32 v120, v120, v121
	v_cvt_pk_bf16_f32 v121, v128, v129
	v_pk_mul_f32 v[122:123], v[122:123], v[46:47] op_sel_hi:[1,0]
	v_pk_mul_f32 v[128:129], v[130:131], v[46:47] op_sel_hi:[1,0]
	v_pk_mul_f32 v[122:123], v[4:5], v[122:123]
	v_pk_mul_f32 v[128:129], v[6:7], v[128:129]
	v_pk_mul_f32 v[122:123], v[54:55], v[122:123]
	v_pk_mul_f32 v[128:129], v[134:135], v[128:129]
	v_mul_f32_e32 v13, 0x45800000, v9
	v_cvt_pk_bf16_f32 v122, v122, v123
	v_cvt_pk_bf16_f32 v123, v128, v129
	v_cndmask_b32_e32 v128, v9, v13, vcc
	v_mul_f32_e32 v9, 0xbfb8aa3b, v142
	v_exp_f32_e32 v9, v9
	v_mul_f32_e32 v13, 0xbfb8aa3b, v143
	v_exp_f32_e32 v13, v13
	global_store_dwordx4 v[114:115], v[120:123], off
	v_add_f32_e32 v9, 1.0, v9
	v_pk_mul_f32 v[126:127], v[126:127], v[128:129] op_sel_hi:[1,0]
	v_pk_mul_f32 v[122:123], v[124:125], v[128:129] op_sel_hi:[1,0]
	v_rcp_f32_e32 v124, v9
	v_add_f32_e32 v9, 1.0, v13
	v_pk_mul_f32 v[120:121], v[48:49], v[128:129] op_sel_hi:[1,0]
	v_rcp_f32_e32 v125, v9
	v_pk_mul_f32 v[120:121], v[0:1], v[120:121]
	v_pk_mul_f32 v[122:123], v[2:3], v[122:123]
	v_pk_mul_f32 v[120:121], v[44:45], v[120:121]
	v_pk_mul_f32 v[122:123], v[140:141], v[122:123]
	v_cvt_pk_bf16_f32 v120, v120, v121
	v_cvt_pk_bf16_f32 v121, v122, v123
	v_pk_mul_f32 v[122:123], v[50:51], v[128:129] op_sel_hi:[1,0]
	v_pk_mul_f32 v[126:127], v[6:7], v[126:127]
	v_pk_mul_f32 v[122:123], v[4:5], v[122:123]
	v_pk_mul_f32 v[124:125], v[124:125], v[142:143]
	v_pk_mul_f32 v[122:123], v[138:139], v[122:123]
	v_pk_mul_f32 v[124:125], v[124:125], v[126:127]
	v_cmp_lt_i32_e32 vcc, s9, v108
	v_cvt_pk_bf16_f32 v122, v122, v123
	v_cvt_pk_bf16_f32 v123, v124, v125
	s_or_b64 s[2:3], vcc, s[2:3]
	global_store_dwordx4 v[114:115], v[120:123], off offset:1024
	s_andn2_b64 exec, exec, s[2:3]
	s_cbranch_execnz .LBB0_872

.LBB0_998:
	v_readlane_b32 s0, v252, 10
	s_nop 3
	s_add_i32 s1, s72, 1
	s_cmp_ge_i32 s1, s0
	s_cbranch_scc1 .Llastseam_go
	v_readlane_b32 s0, v252, 8
	v_readlane_b32 s1, v252, 9
	s_and_b64 vcc, exec, s[0:1]
	s_cbranch_vccz .LBB0_999
.Llastseam_go:
	s_getpc_b64 s[98:99]
